# adds in-proj scan-epilogue trimming (logf expansion collapsed to v_log+mul, exp argument folding), unit order v2, conv epilogue row prefetch into v192-v251 (VGPR budget 256)
# speedup vs baseline: 1.0286x; 1.0202x over previous
;     __device__ bool next(int i, Unit& u) const { const long L = (long)i * G + c; if (L >= nwg) return false; return map((int)L, u); }
;     __device__ bool next(int i, Unit& u) const {
;         const long L = (long)i * G + c;
;         if (L < nwg) return map((int)L, u);
;         const int k = (int)(L - nwg); if (k >= 64) return false;
;         u.pm = 128 + (k >> 3); u.pn = k & 7; return true;
;     }
.LBB0_158:
	s_cmp_lt_i32 s72, 3
	s_cselect_b64 s[6:7], -1, 0
	s_and_b64 s[18:19], s[6:7], s[8:9]
	s_andn2_b64 vcc, exec, s[18:19]
	s_cbranch_vccnz .LBB0_202
	s_load_dword s85, s[0:1], 0x98
	s_waitcnt lgkmcnt(0)
	s_ashr_i32 s3, s2, 31
	s_cmpk_gt_i32 s2, 0x7ff
	v_readfirstlane_b32 s16, v0
	s_cbranch_scc0 .LBB0_162
	s_add_i32 s11, s2, 0xfffff800
	s_mov_b64 s[8:9], 0
	s_cmp_gt_u32 s11, 63
	s_mov_b64 s[6:7], 0
	s_cbranch_scc1 .LBB0_163
	s_lshr_b32 s6, s11, 3
	s_and_b32 s10, s2, 7
	s_add_i32 s12, s6, 0x80
	s_mov_b64 s[6:7], -1
	s_branch .LBB0_163

;     __device__ bool next(int i, Unit& u) const { const long L = (long)i * G + c; if (L >= nwg) return false; return map((int)L, u); }
; #define PG8_STAGE(bufoff, gbase, voff) do { _Pragma("unroll") for (int _i = 0; _i < 2; ++_i) \
;         __builtin_amdgcn_global_load_lds((const unsigned*)((const char*)(gbase) + (voff)[_i]), (LAS unsigned*)(lds + (bufoff) + ldsw + _i * 8192), 16, 0, 0); } while (0)
; #define PG8_WAIT_V(n) asm volatile("s_waitcnt vmcnt(" #n ")" ::: "memory")
; #define PG8_BAR __builtin_amdgcn_s_barrier()
; template <class Epi, class Sched>
; __device__ __forceinline__ void gemm_phase(LAS unsigned char* lds, const Gemm g, const Sched& S, const Epi& E) {
;     ...
;     for (int i = 0; i < 2; ++i) { int R, C; stage_rc(tid * 16 + i * 8192, R, C); const int Rb = Epi::PERM ? ((R & ~31) + perm32(R & 31)) : R;
;         voffA[i] = (unsigned)(R * K + C) * 2u; voffB[i] = (unsigned)(Rb * K + C) * 2u; }
;     const size_t kstep = (size_t)(BK * 2);
;     const size_t hstep = (size_t)HALF * K * 2;
;     const size_t tstep = 2 * hstep;
;     const unsigned ldsw = (unsigned)wid * 1024u;
;     const int aoff = lds_byte(wr * 64 + fr, fq * 8), boff = lds_byte(wc * 32 + fr, fq * 8);
;     ...
;     Unit cur, nxt; int ui = 0;
;     if (!S.next(0, cur)) return;
;     f32x4 acc[2][2][4][2];
; #pragma unroll
;     for (int a = 0; a < 2; ++a)
; #pragma unroll
;         for (int b = 0; b < 2; ++b)
; #pragma unroll
;             for (int m = 0; m < 4; ++m)
; #pragma unroll
;                 for (int n = 0; n < 2; ++n) acc[a][b][m][n] = (f32x4){0.f, 0.f, 0.f, 0.f};
;     bf16x8 At[4][2], B0[2][2], B1[2][2];
;     const char* cA = (const char*)g.A + (size_t)cur.pm * tstep; const char* cB = (const char*)g.Bt + (size_t)cur.pn * tstep;
;     PG8_STAGE(PG8_SB(0, 0), cB, voffB); PG8_STAGE(PG8_SA(0, 0), cA, voffA); PG8_STAGE(PG8_SB(0, 1), cB + hstep, voffB); PG8_STAGE(PG8_SA(0, 1), cA + hstep, voffA);
;     if (wr == 1) PG8_BAR;
;     PG8_WAIT_V(4); PG8_BAR;
;     PG8_STAGE(PG8_SB(1, 0), cB + kstep, voffB); PG8_STAGE(PG8_SA(1, 0), cA + kstep, voffA); PG8_STAGE(PG8_SB(1, 1), cB + hstep + kstep, voffB);
;     PG8_WAIT_V(6); PG8_BAR;
.LBB0_165:
	s_andn2_b64 vcc, exec, s[6:7]
	s_cbranch_vccnz .LBB0_202
	s_cmp_lg_u32 s85, 0x100
	s_cbranch_scc1 .Lp2_first_done
	s_and_b32 s11, s2, 7
	s_cmp_gt_u32 s11, 1
	s_cbranch_scc1 .Lp2_first_done
	s_add_u32 s10, s10, 8
.Lp2_first_done:
	v_lshrrev_b32_e32 v3, 1, v0
	v_lshrrev_b32_e32 v4, 5, v0
	v_lshlrev_b32_e32 v1, 4, v0
	v_and_b32_e32 v2, 32, v0
	v_and_b32_e32 v3, 24, v3
	v_and_b32_e32 v4, 4, v4
	v_bfe_u32 v5, v0, 2, 2
	v_bfe_u32 v12, v0, 2, 4
	v_bitop3_b32 v10, v1, v2, 48 bitop3:0x6c
	v_and_b32_e32 v11, 64, v0
	v_or3_b32 v3, v4, v5, v3
	v_lshrrev_b32_e32 v4, 3, v0
	v_or_b32_e32 v13, 0x2000, v1
	s_add_u32 s78, s70, 0xd00000
	v_or_b32_e32 v2, v10, v11
	v_and_or_b32 v5, v4, 48, v12
	v_and_or_b32 v4, v4, 32, v3
	v_lshrrev_b32_e32 v1, 7, v13
	s_movk_i32 s6, 0x70
	s_addc_u32 s79, s71, 0
	v_lshl_or_b32 v160, v4, 11, v2
	v_and_or_b32 v4, v1, s6, v12
	s_movk_i32 s6, 0x60
	s_lshr_b32 s7, s16, 6
	s_ashr_i32 s13, s12, 31
	s_ashr_i32 s11, s10, 31
	v_and_or_b32 v1, v1, s6, v3
	s_lshr_b32 s6, s16, 8
	s_lshl_b32 s80, s7, 10
	s_lshl_b64 s[8:9], s[12:13], 19
	s_lshl_b64 s[14:15], s[10:11], 19
	s_add_u32 s14, s70, s14
	s_addc_u32 s15, s71, s15
	s_add_i32 s81, s80, 0
	s_add_i32 m0, s81, 0x10000
	v_lshl_or_b32 v164, v1, 11, v2
	global_load_lds_dwordx4 v160, s[14:15]
	s_add_i32 m0, s81, 0x12000
	s_add_u32 s8, s78, s8
	v_lshl_or_b32 v158, v5, 11, v2
	global_load_lds_dwordx4 v164, s[14:15]
	s_addc_u32 s9, s79, s9
	s_mov_b32 m0, s81
	s_add_i32 s82, s81, 0x2000
	v_lshl_or_b32 v162, v4, 11, v2
	global_load_lds_dwordx4 v158, s[8:9]
	s_mov_b32 m0, s82
	s_add_u32 s20, s14, 0x40000
	global_load_lds_dwordx4 v162, s[8:9]
	s_addc_u32 s21, s15, 0
	s_add_i32 m0, s81, 0x14000
	s_load_dword s85, s[0:1], 0x98
	global_load_lds_dwordx4 v160, s[20:21]
	s_add_i32 m0, s81, 0x16000
	v_mov_b32_e32 v161, 0
	global_load_lds_dwordx4 v164, s[20:21]
	s_add_u32 s20, s8, 0x40000
	s_addc_u32 s21, s9, 0
	s_add_i32 s83, s81, 0x4000
	s_mov_b32 m0, s83
	s_add_i32 s84, s81, 0x6000
	global_load_lds_dwordx4 v158, s[20:21]
	s_mov_b32 m0, s84
	v_writelane_b32 v230, s86, 0
	global_load_lds_dwordx4 v162, s[20:21]
	v_mov_b32_e32 v165, v161
	v_mov_b32_e32 v159, v161
	v_mov_b32_e32 v163, v161
	s_cmp_eq_u32 s6, 1
	v_writelane_b32 v230, s87, 1
	s_mov_b32 s86, 0
	v_lshl_add_u64 v[8:9], s[14:15], 0, v[160:161]
	v_lshl_add_u64 v[6:7], s[14:15], 0, v[164:165]
	v_lshl_add_u64 v[2:3], s[8:9], 0, v[158:159]
	s_cselect_b64 s[20:21], -1, 0
	s_cmp_lg_u32 s6, 1
	v_lshl_add_u64 v[4:5], s[8:9], 0, v[162:163]
	s_cbranch_scc1 .LBB0_168
	s_barrier

;     __device__ bool next(int i, Unit& u) const { const long L = (long)i * G + c; if (L >= nwg) return false; return map((int)L, u); }
;     __device__ bool next(int i, Unit& u) const {
;         const long L = (long)i * G + c;
;         if (L < nwg) return map((int)L, u);
;         const int k = (int)(L - nwg); if (k >= 64) return false;
;         u.pm = 128 + (k >> 3); u.pn = k & 7; return true;
.Lp2_map_lat:
	s_lshr_b32 s50, s86, 2
	s_lshl_b32 s51, s11, 1
	s_add_u32 s50, s50, s51
	s_and_b32 s51, s86, 3
	s_cmp_gt_u32 s11, 1
	s_cbranch_scc1 .Lp2_map_b
	s_and_b32 s51, s86, 1
	s_add_u32 s51, s51, 2
	s_cmp_gt_u32 s86, 3
	s_cbranch_scc1 .Lp2_map_a2
	s_lshr_b32 s50, s86, 1
	s_lshl_b32 s64, s11, 1
	s_add_u32 s50, s50, s64
	s_branch .Lp2_map_fin
.Lp2_map_a2:
	s_cmp_gt_u32 s86, 5
	s_cbranch_scc1 .Lp2_map_a3
	s_lshl_b32 s50, s11, 1
	s_add_u32 s50, s50, 5
	s_branch .Lp2_map_fin
.Lp2_map_a3:
	s_lshl_b32 s50, s11, 2
	s_lshl_b32 s64, s86, 1
	s_add_u32 s50, s50, s64
	s_sub_u32 s50, s50, 3
	s_mov_b32 s51, 3
	s_branch .Lp2_map_fin
.Lp2_map_b:
	s_cmp_gt_u32 s11, 3
	s_cbranch_scc1 .Lp2_map_c
	s_cmp_lt_u32 s86, 6
	s_cbranch_scc1 .Lp2_map_fin
	s_lshl_b32 s50, s11, 1
	s_sub_u32 s50, s50, 4
	s_sub_u32 s51, s86, 6
	s_branch .Lp2_map_fin
.Lp2_map_c:
	s_cmp_lt_u32 s86, 7
	s_cbranch_scc1 .Lp2_map_fin
	s_sub_u32 s64, s11, 4
	s_and_b32 s51, s64, 1
	s_and_b32 s50, s64, 2
	s_add_u32 s50, s50, 1

;     __device__ __forceinline__ void operator()(const f32x4 (&acc)[2][2][4][2], const pg8::Unit& u, int wr, int wc, int fr, int fq) const {
;     ...
;             const int ch0 = 64 * pn + 16 * wc + 4 * fq;
;             float lbF[4], lbB[4];
; #pragma unroll
;             for (int j = 0; j < 4; ++j) { lbF[j] = 1.f / (1.f + __expf(lb_logits[1024 + ch0 + j] - lb_logits[ch0 + j])); lbB[j] = 1.f / (1.f + __expf(lb_logits[1536 + ch0 + j] - lb_logits[512 + ch0 + j])); }
; #pragma unroll
;             for (int ai = 0; ai < 2; ++ai) {
;                 const int rowc = u.pm * 256 + 128 * ai + 64 * wr;
;                 const int cid = rowc >> 6;
;                 unsigned oQF[4][2], oQB[4][2], oKF[4][2], oKB[4][2]; f32x4 rtv[4];
; #pragma unroll
;                 for (int jp = 0; jp < 2; ++jp) {
;                     float vQF[4][2], vQB[4][2], vKF[4][2], vKB[4][2];
; #pragma unroll
;                     for (int jj = 0; jj < 2; ++jj) {
;                         const int j = 2 * jp + jj;
;                         float lfF[4], kkF[4], lfB[4], kkB[4], pF[4], pB[4], tF[4], tB[4];
; #pragma unroll
;                         for (int m = 0; m < 4; ++m) {
;                             { const float z = acc[ai][0][m][1][j]; const float e = __expf(fminf(-z, 30.f)); const float s = __builtin_amdgcn_rcpf(1.f + e); lfF[m] = __logf(lbF[j] + (1.f - lbF[j]) * s); kkF[m] = (1.f - lbF[j]) * e * s; }
;                             { const float z = acc[ai][1][m][0][j]; const float e = __expf(fminf(-z, 30.f)); const float s = __builtin_amdgcn_rcpf(1.f + e); lfB[m] = __logf(lbB[j] + (1.f - lbB[j]) * s); kkB[m] = (1.f - lbB[j]) * e * s; }
.LBB0_193:
	v_lshl_or_b32 v176, s10, 6, v185
	v_ashrrev_i32_e32 v177, 31, v176
	v_lshlrev_b64 v[146:147], 2, v[176:177]
	v_lshl_add_u64 v[134:135], s[52:53], 0, v[146:147]
	v_add_co_u32_e32 v138, vcc, 0x1000, v134
	s_nop 0
	s_nop 0
	v_addc_co_u32_e32 v139, vcc, 0, v135, vcc
	global_load_dwordx4 v[130:133], v[134:135], off
	s_nop 0
	global_load_dwordx4 v[134:137], v[134:135], off offset:2048
	s_nop 0
	global_load_dwordx4 v[142:145], v[138:139], off
	s_nop 0
	global_load_dwordx4 v[138:141], v[138:139], off offset:2048
	v_max_f32_e32 v126, 0xc1f00000, v126
	v_mul_f32_e32 v126, 0xbfb8aa3b, v126
	v_exp_f32_e32 v126, v126
	v_max_f32_e32 v122, 0xc1f00000, v122
	v_mul_f32_e32 v122, 0xbfb8aa3b, v122
	v_exp_f32_e32 v122, v122
	v_max_f32_e32 v118, 0xc1f00000, v118
	v_mul_f32_e32 v118, 0xbfb8aa3b, v118
	v_max_f32_e32 v114, 0xc1f00000, v114
	v_mul_f32_e32 v114, 0xbfb8aa3b, v114
	v_max_f32_e32 v110, 0xc1f00000, v110
	v_mul_f32_e32 v110, 0xbfb8aa3b, v110
	v_exp_f32_e32 v110, v110
	v_max_f32_e32 v106, 0xc1f00000, v106
	v_mul_f32_e32 v106, 0xbfb8aa3b, v106
	v_exp_f32_e32 v106, v106
	v_max_f32_e32 v102, 0xc1f00000, v102
	v_mul_f32_e32 v102, 0xbfb8aa3b, v102
	v_max_f32_e32 v98, 0xc1f00000, v98
	v_mul_f32_e32 v98, 0xbfb8aa3b, v98
	v_exp_f32_e32 v98, v98
	v_max_f32_e32 v123, 0xc1f00000, v123
	v_mul_f32_e32 v123, 0xbfb8aa3b, v123
	v_exp_f32_e32 v123, v123
	v_max_f32_e32 v119, 0xc1f00000, v119
	v_mul_f32_e32 v119, 0xbfb8aa3b, v119
	v_max_f32_e32 v115, 0xc1f00000, v115
	v_mul_f32_e32 v115, 0xbfb8aa3b, v115
	v_exp_f32_e32 v115, v115
	v_max_f32_e32 v111, 0xc1f00000, v111
	v_mul_f32_e32 v111, 0xbfb8aa3b, v111
	v_add_f32_e32 v201, 1.0, v115
	v_rcp_f32_e32 v202, v201
	v_exp_f32_e32 v111, v111
	v_max_f32_e32 v107, 0xc1f00000, v107
	v_mul_f32_e32 v107, 0xbfb8aa3b, v107
	v_exp_f32_e32 v107, v107
	v_max_f32_e32 v103, 0xc1f00000, v103
	v_mul_f32_e32 v103, 0xbfb8aa3b, v103
	v_add_f32_e32 v206, 1.0, v107
	v_rcp_f32_e32 v207, v206
	v_exp_f32_e32 v103, v103
	v_max_f32_e32 v99, 0xc1f00000, v99
	v_mul_f32_e32 v99, 0xbfb8aa3b, v99
	v_exp_f32_e32 v99, v99
	v_max_f32_e32 v116, 0xc1f00000, v116
	v_mul_f32_e32 v116, 0xbfb8aa3b, v116
	v_add_f32_e32 v211, 1.0, v99
	v_rcp_f32_e32 v211, v211
	v_exp_f32_e32 v116, v116
	v_max_f32_e32 v108, 0xc1f00000, v108
	v_mul_f32_e32 v108, 0xbfb8aa3b, v108
	v_exp_f32_e32 v108, v108
	v_max_f32_e32 v100, 0xc1f00000, v100
	v_mul_f32_e32 v100, 0xbfb8aa3b, v100
	v_exp_f32_e32 v100, v100
	v_max_f32_e32 v117, 0xc1f00000, v117
	v_mul_f32_e32 v117, 0xbfb8aa3b, v117
	v_exp_f32_e32 v117, v117
	s_waitcnt vmcnt(0)
	v_sub_f32_e32 v130, v142, v130
	v_sub_f32_e32 v134, v138, v134
	v_mul_f32_e32 v130, 0x3fb8aa3b, v130
	v_sub_f32_e32 v131, v143, v131
	v_mul_f32_e32 v134, 0x3fb8aa3b, v134
	v_exp_f32_e32 v130, v130
	v_sub_f32_e32 v135, v139, v135
	v_mul_f32_e32 v131, 0x3fb8aa3b, v131
	v_exp_f32_e32 v134, v134
	v_sub_f32_e32 v132, v144, v132
	v_mul_f32_e32 v135, 0x3fb8aa3b, v135
	v_exp_f32_e32 v131, v131
	v_mul_f32_e32 v132, 0x3fb8aa3b, v132
	v_exp_f32_e32 v135, v135
	v_exp_f32_e32 v132, v132
	v_add_f32_e32 v130, 1.0, v130
	v_add_f32_e32 v134, 1.0, v134
	v_div_scale_f32 v138, s[10:11], v130, v130, 1.0
	v_sub_f32_e32 v136, v140, v136
	v_add_f32_e32 v131, 1.0, v131
	v_div_scale_f32 v140, s[10:11], v134, v134, 1.0
	v_rcp_f32_e32 v153, v138
	v_add_f32_e32 v135, 1.0, v135
	v_div_scale_f32 v143, s[12:13], v131, v131, 1.0
	v_rcp_f32_e32 v154, v140
	v_add_f32_e32 v132, 1.0, v132
	v_div_scale_f32 v148, s[14:15], v135, v135, 1.0
	v_rcp_f32_e32 v155, v143
	v_div_scale_f32 v150, s[16:17], v132, v132, 1.0
	v_rcp_f32_e32 v156, v148
	v_rcp_f32_e32 v157, v150
	v_fma_f32 v174, -v138, v153, 1.0
	v_div_scale_f32 v139, vcc, 1.0, v130, 1.0
	v_fma_f32 v175, -v140, v154, 1.0
	v_fmac_f32_e32 v153, v174, v153
	v_div_scale_f32 v142, s[10:11], 1.0, v134, 1.0
	v_fma_f32 v177, -v143, v155, 1.0
	v_fmac_f32_e32 v154, v175, v154
	v_mul_f32_e32 v174, v139, v153
	v_mul_f32_e32 v136, 0x3fb8aa3b, v136
	v_div_scale_f32 v144, s[12:13], 1.0, v131, 1.0
	v_fma_f32 v191, -v148, v156, 1.0
	v_fmac_f32_e32 v155, v177, v155
	v_mul_f32_e32 v175, v142, v154
	v_fma_f32 v193, -v138, v174, v139
	v_exp_f32_e32 v136, v136
	v_div_scale_f32 v149, s[14:15], 1.0, v135, 1.0
	v_fma_f32 v192, -v150, v157, 1.0
	v_fmac_f32_e32 v156, v191, v156
	v_mul_f32_e32 v177, v144, v155
	v_fma_f32 v194, -v140, v175, v142
	v_fmac_f32_e32 v174, v193, v153
	v_div_scale_f32 v151, s[16:17], 1.0, v132, 1.0
	v_fmac_f32_e32 v157, v192, v157
	v_mul_f32_e32 v191, v149, v156
	v_fma_f32 v195, -v143, v177, v144
	v_fmac_f32_e32 v175, v194, v154
	v_fma_f32 v138, -v138, v174, v139
	v_mul_f32_e32 v192, v151, v157
	v_fma_f32 v196, -v148, v191, v149
	v_fmac_f32_e32 v177, v195, v155
	v_fma_f32 v139, -v140, v175, v142
	v_div_fmas_f32 v138, v138, v153, v174
	s_mov_b64 vcc, s[10:11]
	v_fma_f32 v197, -v150, v192, v151
	v_fmac_f32_e32 v191, v196, v156
	v_fma_f32 v140, -v143, v177, v144
	v_div_fixup_f32 v196, v138, v130, 1.0
	v_div_fmas_f32 v130, v139, v154, v175
	s_mov_b64 vcc, s[12:13]
	v_add_f32_e32 v136, 1.0, v136
	v_fmac_f32_e32 v192, v197, v157
	v_fma_f32 v142, -v148, v191, v149
	v_div_fixup_f32 v195, v130, v134, 1.0
	v_div_fmas_f32 v130, v140, v155, v177
	s_mov_b64 vcc, s[14:15]
	v_div_scale_f32 v152, s[98:99], v136, v136, 1.0
	v_fma_f32 v143, -v150, v192, v151
	v_div_fixup_f32 v194, v130, v131, 1.0
	v_div_fmas_f32 v130, v142, v156, v191
	s_mov_b64 vcc, s[16:17]
	v_rcp_f32_e32 v173, v152
	v_div_fixup_f32 v193, v130, v135, 1.0
	v_div_fmas_f32 v130, v143, v157, v192
	v_div_fixup_f32 v177, v130, v132, 1.0
	v_sub_f32_e32 v132, v145, v133
	v_mul_f32_e32 v132, 0x3fb8aa3b, v132
	v_exp_f32_e32 v132, v132
	v_fma_f32 v130, -v152, v173, 1.0
	v_fmac_f32_e32 v173, v130, v173
; __device__ __forceinline__ float scan16(float x) { x += dpp_shr<1>(x); x += dpp_shr<2>(x); x += dpp_shr<4>(x); x += dpp_shr<8>(x); return x; }
;     __device__ __forceinline__ void operator()(const f32x4 (&acc)[2][2][4][2], const pg8::Unit& u, int wr, int wc, int fr, int fq) const {
;     ...
;                             { const float z = acc[ai][0][m][1][j]; const float e = __expf(fminf(-z, 30.f)); const float s = __builtin_amdgcn_rcpf(1.f + e); lfF[m] = __logf(lbF[j] + (1.f - lbF[j]) * s); kkF[m] = (1.f - lbF[j]) * e * s; }
;                             { const float z = acc[ai][1][m][0][j]; const float e = __expf(fminf(-z, 30.f)); const float s = __builtin_amdgcn_rcpf(1.f + e); lfB[m] = __logf(lbB[j] + (1.f - lbB[j]) * s); kkB[m] = (1.f - lbB[j]) * e * s; }
;                             pF[m] = scan16(lfF[m]); pB[m] = scan16(lfB[m]);
;                             tF[m] = __int_as_float(__builtin_amdgcn_update_dpp(0, __float_as_int(pF[m]), 0x15F, 0xf, 0xf, true));
;                             tB[m] = __int_as_float(__builtin_amdgcn_update_dpp(0, __float_as_int(pB[m]), 0x15F, 0xf, 0xf, true));
	v_div_scale_f32 v130, vcc, 1.0, v136, 1.0
	v_mul_f32_e32 v131, v130, v173
	v_fma_f32 v133, -v152, v131, v130
	v_add_f32_e32 v132, 1.0, v132
	v_fmac_f32_e32 v131, v133, v173
	v_div_scale_f32 v133, s[10:11], v132, v132, 1.0
	v_rcp_f32_e32 v134, v133
	v_fma_f32 v130, -v152, v131, v130
	v_div_fmas_f32 v130, v130, v173, v131
	v_sub_f32_e32 v135, v141, v137
	v_div_fixup_f32 v192, v130, v136, 1.0
	v_fma_f32 v130, -v133, v134, 1.0
	v_mul_f32_e32 v135, 0x3fb8aa3b, v135
	v_fmac_f32_e32 v134, v130, v134
	v_div_scale_f32 v130, vcc, 1.0, v132, 1.0
	v_exp_f32_e32 v135, v135
	v_mul_f32_e32 v131, v130, v134
	v_fma_f32 v136, -v133, v131, v130
	v_fmac_f32_e32 v131, v136, v134
	v_fma_f32 v130, -v133, v131, v130
	v_add_f32_e32 v133, 1.0, v135
	v_div_scale_f32 v135, s[10:11], v133, v133, 1.0
	v_rcp_f32_e32 v136, v135
	v_div_fmas_f32 v130, v130, v134, v131
	v_div_fixup_f32 v173, v130, v132, 1.0
	v_sub_f32_e32 v197, 1.0, v196
	v_fma_f32 v130, -v135, v136, 1.0
	v_fmac_f32_e32 v136, v130, v136
	v_div_scale_f32 v130, vcc, 1.0, v133, 1.0
	v_mul_f32_e32 v131, v130, v136
	v_fma_f32 v132, -v135, v131, v130
	v_fmac_f32_e32 v131, v132, v136
	v_add_f32_e32 v132, 1.0, v126
	v_rcp_f32_e32 v132, v132
	v_fma_f32 v130, -v135, v131, v130
	v_div_fmas_f32 v130, v130, v136, v131
	v_div_fixup_f32 v191, v130, v133, 1.0
	v_fma_f32 v131, v132, v197, v196
	v_add_f32_e32 v133, 1.0, v122
	v_rcp_f32_e32 v133, v133
	v_log_f32_e32 v131, v131
	v_sub_f32_e32 v198, 1.0, v195
	v_fma_f32 v134, v133, v198, v195
	v_mul_f32_e32 v126, v126, v197
	v_mul_f32_e32 v138, v132, v126
	v_mul_f32_e32 v122, v122, v198
	v_mul_f32_e32 v130, 0x3f317218, v131
	v_mul_f32_e32 v136, v133, v122
	v_log_f32_e32 v134, v134
	v_add_f32_dpp v122, v130, v130 row_shr:1 row_mask:0xf bank_mask:0xf bound_ctrl:1
	v_add_f32_e32 v142, 1.0, v106
	v_rcp_f32_e32 v142, v142
	v_mul_f32_e32 v106, v106, v198
	v_mul_f32_e32 v126, 0x3f317218, v134
	v_mov_b32_e32 v137, v126
	v_exp_f32_e32 v126, v118
	v_add_f32_dpp v118, v122, v122 row_shr:2 row_mask:0xf bank_mask:0xf bound_ctrl:1
	v_exp_f32_e32 v134, v114
	v_fma_f32 v144, v142, v198, v195
	v_add_f32_dpp v118, v118, v118 row_shr:4 row_mask:0xf bank_mask:0xf bound_ctrl:1
	v_mul_f32_e32 v142, v142, v106
	v_add_f32_e32 v148, 1.0, v98
	v_add_f32_dpp v131, v118, v118 row_shr:8 row_mask:0xf bank_mask:0xf bound_ctrl:1
	v_add_f32_e32 v118, 1.0, v126
	v_rcp_f32_e32 v130, v118
	v_rcp_f32_e32 v149, v148
	v_lshl_add_u64 v[174:175], s[38:39], 0, v[146:147]
	v_mul_f32_e32 v98, v98, v198
	v_fma_f32 v122, v130, v197, v196
	v_fma_f32 v148, v149, v198, v195
	v_sub_f32_e32 v199, 1.0, v194
	v_log_f32_e32 v132, v122
	v_add_f32_dpp v118, v137, v137 row_shr:1 row_mask:0xf bank_mask:0xf bound_ctrl:1
	v_mov_b32_dpp v122, v131 row_newbcast:15 row_mask:0xf bank_mask:0xf bound_ctrl:1
	v_sub_f32_e32 v200, 1.0, v193
	v_add_f32_e32 v133, 1.0, v134
	v_rcp_f32_e32 v133, v133
	s_nop 0
	v_fma_f32 v139, v133, v198, v195
	v_add_f32_dpp v118, v118, v118 row_shr:2 row_mask:0xf bank_mask:0xf bound_ctrl:1
	v_mul_f32_e32 v114, 0x3f317218, v132
	v_mov_b32_e32 v132, v114
	v_mul_f32_e32 v114, v126, v197
	v_log_f32_e32 v139, v139
	v_mul_f32_e32 v114, v130, v114
	v_add_f32_dpp v118, v118, v118 row_shr:4 row_mask:0xf bank_mask:0xf bound_ctrl:1
	s_nop 1
	v_add_f32_dpp v135, v118, v118 row_shr:8 row_mask:0xf bank_mask:0xf bound_ctrl:1
	v_add_f32_e32 v154, 0, v135
	v_mul_f32_e32 v126, 0x3f317218, v139
	v_mov_b32_e32 v140, v126
	v_mul_f32_e32 v126, v134, v198
	v_mul_f32_e32 v139, v133, v126
	v_mov_b32_dpp v118, v135 row_newbcast:15 row_mask:0xf bank_mask:0xf bound_ctrl:1
	v_add_f32_dpp v126, v132, v132 row_shr:1 row_mask:0xf bank_mask:0xf bound_ctrl:1
	v_add_f32_e32 v135, 1.0, v123
	v_rcp_f32_e32 v135, v135
	v_add_f32_dpp v126, v126, v126 row_shr:2 row_mask:0xf bank_mask:0xf bound_ctrl:1
	v_fma_f32 v201, v202, v200, v193
	v_fma_f32 v206, v207, v200, v193
	v_add_f32_dpp v126, v126, v126 row_shr:4 row_mask:0xf bank_mask:0xf bound_ctrl:1
	v_fma_f32 v153, v135, v200, v193
	v_fma_f32 v212, v211, v200, v193
	v_add_f32_dpp v143, v126, v126 row_shr:8 row_mask:0xf bank_mask:0xf bound_ctrl:1
	v_add_f32_e32 v126, 1.0, v110
	v_rcp_f32_e32 v132, v126
	v_mul_f32_e32 v110, v110, v197
	v_add_f32_dpp v126, v140, v140 row_shr:1 row_mask:0xf bank_mask:0xf bound_ctrl:1
	v_max_f32_e32 v109, 0xc1f00000, v109
	v_fma_f32 v130, v132, v197, v196
	v_add_f32_dpp v126, v126, v126 row_shr:2 row_mask:0xf bank_mask:0xf bound_ctrl:1
	v_mul_f32_e32 v109, 0xbfb8aa3b, v109
	v_log_f32_e32 v133, v130
	v_add_f32_dpp v126, v126, v126 row_shr:4 row_mask:0xf bank_mask:0xf bound_ctrl:1
	v_mov_b32_dpp v130, v143 row_newbcast:15 row_mask:0xf bank_mask:0xf bound_ctrl:1
	v_exp_f32_e32 v109, v109
	v_add_f32_dpp v141, v126, v126 row_shr:8 row_mask:0xf bank_mask:0xf bound_ctrl:1
	v_mul_f32_e32 v133, 0x3f317218, v133
	s_nop 0
	v_mov_b32_dpp v126, v141 row_newbcast:15 row_mask:0xf bank_mask:0xf bound_ctrl:1
	v_log_f32_e32 v144, v144
	v_mul_f32_e32 v145, v132, v110
	v_add_f32_dpp v106, v133, v133 row_shr:1 row_mask:0xf bank_mask:0xf bound_ctrl:1
	v_max_f32_e32 v105, 0xc1f00000, v105
	v_mul_f32_e32 v105, 0xbfb8aa3b, v105
	v_mul_f32_e32 v110, 0x3f317218, v144
	v_mov_b32_e32 v144, v110
	v_exp_f32_e32 v110, v102
	v_add_f32_dpp v102, v106, v106 row_shr:2 row_mask:0xf bank_mask:0xf bound_ctrl:1
	v_exp_f32_e32 v105, v105
	v_add_f32_e32 v106, 1.0, v110
	v_rcp_f32_e32 v133, v106
	v_mul_f32_e32 v110, v110, v197
	v_add_f32_dpp v106, v144, v144 row_shr:1 row_mask:0xf bank_mask:0xf bound_ctrl:1
	v_add_f32_dpp v102, v102, v102 row_shr:4 row_mask:0xf bank_mask:0xf bound_ctrl:1
	v_fma_f32 v132, v133, v197, v196
	v_add_f32_dpp v106, v106, v106 row_shr:2 row_mask:0xf bank_mask:0xf bound_ctrl:1
; __device__ __forceinline__ float scan16(float x) { x += dpp_shr<1>(x); x += dpp_shr<2>(x); x += dpp_shr<4>(x); x += dpp_shr<8>(x); return x; }
;     __device__ __forceinline__ void operator()(const f32x4 (&acc)[2][2][4][2], const pg8::Unit& u, int wr, int wc, int fr, int fq) const {
;     ...
;                             { const float z = acc[ai][0][m][1][j]; const float e = __expf(fminf(-z, 30.f)); const float s = __builtin_amdgcn_rcpf(1.f + e); lfF[m] = __logf(lbF[j] + (1.f - lbF[j]) * s); kkF[m] = (1.f - lbF[j]) * e * s; }
;                             { const float z = acc[ai][1][m][0][j]; const float e = __expf(fminf(-z, 30.f)); const float s = __builtin_amdgcn_rcpf(1.f + e); lfB[m] = __logf(lbB[j] + (1.f - lbB[j]) * s); kkB[m] = (1.f - lbB[j]) * e * s; }
;                             pF[m] = scan16(lfF[m]); pB[m] = scan16(lfB[m]);
;                             tF[m] = __int_as_float(__builtin_amdgcn_update_dpp(0, __float_as_int(pF[m]), 0x15F, 0xf, 0xf, true));
;                             tB[m] = __int_as_float(__builtin_amdgcn_update_dpp(0, __float_as_int(pB[m]), 0x15F, 0xf, 0xf, true));
	v_add_f32_dpp v102, v102, v102 row_shr:8 row_mask:0xf bank_mask:0xf bound_ctrl:1
	v_log_f32_e32 v134, v132
	v_add_f32_dpp v106, v106, v106 row_shr:4 row_mask:0xf bank_mask:0xf bound_ctrl:1
	v_max_f32_e32 v101, 0xc1f00000, v101
	v_mul_f32_e32 v101, 0xbfb8aa3b, v101
	v_add_f32_dpp v146, v106, v106 row_shr:8 row_mask:0xf bank_mask:0xf bound_ctrl:1
	v_mov_b32_dpp v106, v102 row_newbcast:15 row_mask:0xf bank_mask:0xf bound_ctrl:1
	v_mul_f32_e32 v134, 0x3f317218, v134
	v_mul_f32_e32 v147, v149, v98
	v_log_f32_e32 v148, v148
	v_mul_f32_e32 v150, v133, v110
	v_add_f32_dpp v98, v134, v134 row_shr:1 row_mask:0xf bank_mask:0xf bound_ctrl:1
	s_nop 1
	v_add_f32_dpp v98, v98, v98 row_shr:2 row_mask:0xf bank_mask:0xf bound_ctrl:1
	v_mov_b32_dpp v132, v146 row_newbcast:15 row_mask:0xf bank_mask:0xf bound_ctrl:1
	v_mul_f32_e32 v110, 0x3f317218, v148
	v_mov_b32_e32 v148, v110
	v_max_f32_e32 v110, 0xc1f00000, v127
	v_mul_f32_e32 v110, 0xbfb8aa3b, v110
	v_add_f32_dpp v98, v98, v98 row_shr:4 row_mask:0xf bank_mask:0xf bound_ctrl:1
	v_exp_f32_e32 v127, v110
	v_exp_f32_e32 v101, v101
	v_add_f32_dpp v151, v98, v98 row_shr:8 row_mask:0xf bank_mask:0xf bound_ctrl:1
	v_add_f32_dpp v98, v148, v148 row_shr:1 row_mask:0xf bank_mask:0xf bound_ctrl:1
	s_nop 0
	v_mov_b32_dpp v110, v151 row_newbcast:15 row_mask:0xf bank_mask:0xf bound_ctrl:1
	v_add_f32_dpp v98, v98, v98 row_shr:2 row_mask:0xf bank_mask:0xf bound_ctrl:1
	s_nop 1
	v_add_f32_dpp v98, v98, v98 row_shr:4 row_mask:0xf bank_mask:0xf bound_ctrl:1
	s_nop 1
	v_add_f32_dpp v149, v98, v98 row_shr:8 row_mask:0xf bank_mask:0xf bound_ctrl:1
	v_add_f32_e32 v98, 1.0, v127
	v_rcp_f32_e32 v98, v98
	v_mul_f32_e32 v127, v127, v199
	v_mov_b32_dpp v134, v149 row_newbcast:15 row_mask:0xf bank_mask:0xf bound_ctrl:1
	v_fma_f32 v133, v98, v199, v194
	s_nop 1
	v_log_f32_e32 v152, v133
	v_add_f32_e32 v133, 0, v131
	s_nop 1
	v_mul_f32_e32 v131, 0x3f317218, v152
	v_mul_f32_e32 v152, v98, v127
	v_log_f32_e32 v153, v153
	s_nop 1
	v_mul_f32_e32 v98, 0x3f317218, v153
	v_mov_b32_e32 v155, v98
	v_mul_f32_e32 v98, v123, v200
	v_exp_f32_e32 v127, v119
	v_mul_f32_e32 v153, v135, v98
	v_add_f32_dpp v98, v131, v131 row_shr:1 row_mask:0xf bank_mask:0xf bound_ctrl:1
	v_add_f32_dpp v119, v155, v155 row_shr:1 row_mask:0xf bank_mask:0xf bound_ctrl:1
	s_nop 0
	v_add_f32_dpp v98, v98, v98 row_shr:2 row_mask:0xf bank_mask:0xf bound_ctrl:1
	v_add_f32_dpp v119, v119, v119 row_shr:2 row_mask:0xf bank_mask:0xf bound_ctrl:1
	s_nop 0
	v_add_f32_dpp v98, v98, v98 row_shr:4 row_mask:0xf bank_mask:0xf bound_ctrl:1
	v_add_f32_dpp v119, v119, v119 row_shr:4 row_mask:0xf bank_mask:0xf bound_ctrl:1
	s_nop 0
	v_add_f32_dpp v156, v98, v98 row_shr:8 row_mask:0xf bank_mask:0xf bound_ctrl:1
	v_add_f32_e32 v98, 1.0, v127
	v_rcp_f32_e32 v98, v98
	v_mul_f32_e32 v127, v127, v199
	v_add_f32_dpp v157, v119, v119 row_shr:8 row_mask:0xf bank_mask:0xf bound_ctrl:1
	v_fma_f32 v123, v98, v199, v194
	s_nop 0
	v_mov_b32_dpp v119, v157 row_newbcast:15 row_mask:0xf bank_mask:0xf bound_ctrl:1
	s_nop 0
	v_log_f32_e32 v131, v123
	s_nop 0
	v_mov_b32_dpp v123, v156 row_newbcast:15 row_mask:0xf bank_mask:0xf bound_ctrl:1
	s_nop 1
	v_mul_f32_e32 v131, 0x3f317218, v131
	s_nop 0
	v_log_f32_e32 v203, v201
	v_mul_f32_e32 v201, v98, v127
	s_nop 1
	v_mul_f32_e32 v98, 0x3f317218, v203
	v_mov_b32_e32 v203, v98
	v_mul_f32_e32 v98, v115, v200
	v_mul_f32_e32 v202, v202, v98
	v_add_f32_dpp v115, v203, v203 row_shr:1 row_mask:0xf bank_mask:0xf bound_ctrl:1
	v_add_f32_dpp v98, v131, v131 row_shr:1 row_mask:0xf bank_mask:0xf bound_ctrl:1
	s_nop 0
	v_add_f32_dpp v115, v115, v115 row_shr:2 row_mask:0xf bank_mask:0xf bound_ctrl:1
	v_add_f32_dpp v98, v98, v98 row_shr:2 row_mask:0xf bank_mask:0xf bound_ctrl:1
	s_nop 0
	v_add_f32_dpp v115, v115, v115 row_shr:4 row_mask:0xf bank_mask:0xf bound_ctrl:1
	v_add_f32_dpp v98, v98, v98 row_shr:4 row_mask:0xf bank_mask:0xf bound_ctrl:1
	s_nop 0
	v_add_f32_dpp v205, v115, v115 row_shr:8 row_mask:0xf bank_mask:0xf bound_ctrl:1
	v_add_f32_dpp v204, v98, v98 row_shr:8 row_mask:0xf bank_mask:0xf bound_ctrl:1
	v_add_f32_e32 v98, 1.0, v111
	v_rcp_f32_e32 v98, v98
	v_mul_f32_e32 v111, v111, v199
	v_fma_f32 v127, v98, v199, v194
	s_nop 1
	v_log_f32_e32 v135, v127
	v_mov_b32_dpp v131, v204 row_newbcast:15 row_mask:0xf bank_mask:0xf bound_ctrl:1
	v_mov_b32_dpp v127, v205 row_newbcast:15 row_mask:0xf bank_mask:0xf bound_ctrl:1
	s_nop 1
	v_mul_f32_e32 v115, 0x3f317218, v135
	s_nop 0
	v_log_f32_e32 v208, v206
	v_mul_f32_e32 v206, v98, v111
	s_nop 1
	v_mul_f32_e32 v98, 0x3f317218, v208
	v_mov_b32_e32 v208, v98
	v_mul_f32_e32 v98, v107, v200
	v_mul_f32_e32 v207, v207, v98
	v_add_f32_dpp v107, v208, v208 row_shr:1 row_mask:0xf bank_mask:0xf bound_ctrl:1
	v_add_f32_dpp v98, v115, v115 row_shr:1 row_mask:0xf bank_mask:0xf bound_ctrl:1
	s_nop 0
	v_add_f32_dpp v107, v107, v107 row_shr:2 row_mask:0xf bank_mask:0xf bound_ctrl:1
	v_add_f32_dpp v98, v98, v98 row_shr:2 row_mask:0xf bank_mask:0xf bound_ctrl:1
	s_nop 0
	v_add_f32_dpp v107, v107, v107 row_shr:4 row_mask:0xf bank_mask:0xf bound_ctrl:1
	v_add_f32_dpp v98, v98, v98 row_shr:4 row_mask:0xf bank_mask:0xf bound_ctrl:1
	s_nop 0
	v_add_f32_dpp v210, v107, v107 row_shr:8 row_mask:0xf bank_mask:0xf bound_ctrl:1
	v_add_f32_dpp v209, v98, v98 row_shr:8 row_mask:0xf bank_mask:0xf bound_ctrl:1
	v_add_f32_e32 v98, 1.0, v103
	v_rcp_f32_e32 v98, v98
	v_mul_f32_e32 v103, v103, v199
	v_mov_b32_dpp v135, v210 row_newbcast:15 row_mask:0xf bank_mask:0xf bound_ctrl:1
	v_mov_b32_dpp v107, v209 row_newbcast:15 row_mask:0xf bank_mask:0xf bound_ctrl:1
	v_fma_f32 v111, v98, v199, v194
	s_nop 1
	v_log_f32_e32 v111, v111
	s_nop 0
	s_nop 1
	v_mul_f32_e32 v111, 0x3f317218, v111
; __device__ __forceinline__ float scan16(float x) { x += dpp_shr<1>(x); x += dpp_shr<2>(x); x += dpp_shr<4>(x); x += dpp_shr<8>(x); return x; }
; __device__ __forceinline__ float clamp80(float x) { return fminf(fmaxf(x, -80.f), 80.f); }
;     __device__ __forceinline__ void operator()(const f32x4 (&acc)[2][2][4][2], const pg8::Unit& u, int wr, int wc, int fr, int fq) const {
;     ...
;                             { const float z = acc[ai][0][m][1][j]; const float e = __expf(fminf(-z, 30.f)); const float s = __builtin_amdgcn_rcpf(1.f + e); lfF[m] = __logf(lbF[j] + (1.f - lbF[j]) * s); kkF[m] = (1.f - lbF[j]) * e * s; }
;                             { const float z = acc[ai][1][m][0][j]; const float e = __expf(fminf(-z, 30.f)); const float s = __builtin_amdgcn_rcpf(1.f + e); lfB[m] = __logf(lbB[j] + (1.f - lbB[j]) * s); kkB[m] = (1.f - lbB[j]) * e * s; }
;                             pF[m] = scan16(lfF[m]); pB[m] = scan16(lfB[m]);
;                             tF[m] = __int_as_float(__builtin_amdgcn_update_dpp(0, __float_as_int(pF[m]), 0x15F, 0xf, 0xf, true));
;                             tB[m] = __int_as_float(__builtin_amdgcn_update_dpp(0, __float_as_int(pB[m]), 0x15F, 0xf, 0xf, true));
;                         }
;                         const float rF = tF[0] + tF[1], blF = rF + tF[2] + tF[3];
;                         const float rB = tB[2] + tB[3], blB = rB + tB[0] + tB[1];
;                         float cF = 0.f, cB = 0.f;
; #pragma unroll
;                         for (int m = 0; m < 4; ++m) {
;                             const float bF = pF[m] + cF; cF += tF[m];
;                             const float bB = blB - (pB[m] + cB) + lfB[m]; cB += tB[m];
;                             const float xF = clamp80(bF - rF), xB = clamp80(bB - rB);
;                             const float q = acc[ai][0][m][0][j];
;                             vQF[m][jj] = q * __expf(xF); vKF[m][jj] = kkF[m] * __expf(-xF);
;                             vQB[m][jj] = q * __expf(xB); vKB[m][jj] = kkB[m] * __expf(-xB);
;                         }
	s_nop 0
	v_log_f32_e32 v212, v212
	v_mul_f32_e32 v213, v98, v103
	s_nop 1
	v_mul_f32_e32 v98, 0x3f317218, v212
	v_mov_b32_e32 v212, v98
	v_mul_f32_e32 v98, v99, v200
	v_mul_f32_e32 v211, v211, v98
	s_nop 0
	v_add_f32_dpp v98, v111, v111 row_shr:1 row_mask:0xf bank_mask:0xf bound_ctrl:1
	s_nop 1
	v_add_f32_dpp v98, v98, v98 row_shr:2 row_mask:0xf bank_mask:0xf bound_ctrl:1
	s_nop 1
	v_add_f32_dpp v98, v98, v98 row_shr:4 row_mask:0xf bank_mask:0xf bound_ctrl:1
	s_nop 1
	v_add_f32_dpp v214, v98, v98 row_shr:8 row_mask:0xf bank_mask:0xf bound_ctrl:1
	v_add_f32_dpp v98, v212, v212 row_shr:1 row_mask:0xf bank_mask:0xf bound_ctrl:1
	s_nop 1
	v_add_f32_dpp v98, v98, v98 row_shr:2 row_mask:0xf bank_mask:0xf bound_ctrl:1
	s_nop 1
	v_add_f32_dpp v98, v98, v98 row_shr:4 row_mask:0xf bank_mask:0xf bound_ctrl:1
	s_nop 1
	v_add_f32_dpp v215, v98, v98 row_shr:8 row_mask:0xf bank_mask:0xf bound_ctrl:1
	v_pk_add_f32 v[98:99], v[122:123], v[130:131]
	v_add_f32_e32 v122, 0, v122
	v_sub_f32_e32 v103, v133, v98
	v_med3_f32 v103, v103, s96, v190
	v_mul_f32_e32 v111, 0x3fb8aa3b, v103
	v_exp_f32_e32 v115, v111
	v_mul_f32_e32 v103, 0xbfb8aa3b, v103
	v_exp_f32_e32 v103, v103
	v_mov_b32_dpp v133, v215 row_newbcast:15 row_mask:0xf bank_mask:0xf bound_ctrl:1
	v_mul_f32_e32 v216, v94, v115
	v_add_f32_e32 v115, v122, v143
	v_sub_f32_e32 v115, v115, v98
	v_med3_f32 v115, v115, s96, v190
	v_mul_f32_e32 v143, 0x3fb8aa3b, v115
	v_mul_f32_e32 v115, 0xbfb8aa3b, v115
	v_mul_f32_e32 v138, v138, v103
	v_add_f32_e32 v103, v122, v130
	v_exp_f32_e32 v115, v115
	v_add_f32_e32 v102, v103, v102
	v_add_f32_e32 v103, v103, v106
	v_add_f32_e32 v103, v103, v151
	v_sub_f32_e32 v102, v102, v98
	v_sub_f32_e32 v103, v103, v98
	v_med3_f32 v102, v102, s96, v190
	v_med3_f32 v103, v103, s96, v190
	v_mul_f32_e32 v130, v114, v115
	v_mul_f32_e32 v114, 0x3fb8aa3b, v102
	v_mul_f32_e32 v102, 0xbfb8aa3b, v102
	v_mul_f32_e32 v115, 0x3fb8aa3b, v103
	v_mul_f32_e32 v103, 0xbfb8aa3b, v103
	v_exp_f32_e32 v143, v143
	v_exp_f32_e32 v114, v114
	v_exp_f32_e32 v102, v102
	v_exp_f32_e32 v103, v103
	v_exp_f32_e32 v115, v115
	v_mul_f32_e32 v122, v90, v143
	v_mul_f32_e32 v143, v86, v114
	v_mul_f32_e32 v145, v145, v102
	v_mul_f32_e32 v217, v150, v103
	v_pk_add_f32 v[102:103], v[134:135], v[132:133]
	v_add_f32_e32 v114, 0, v118
	v_mul_f32_e32 v151, v82, v115
	v_add_f32_e32 v133, v114, v141
	v_add_f32_e32 v134, v114, v126
	v_pk_add_f32 v[114:115], v[102:103], v[118:119]
	v_add_f32_e32 v141, v134, v146
	v_pk_add_f32 v[114:115], v[114:115], v[126:127]
	v_add_f32_e32 v132, v134, v132
	v_sub_f32_e32 v118, v114, v154
	v_sub_f32_e32 v133, v114, v133
	v_add_f32_e32 v118, v137, v118
	v_add_f32_e32 v133, v140, v133
	v_sub_f32_e32 v118, v118, v102
	v_sub_f32_e32 v133, v133, v102
	v_med3_f32 v118, v118, s96, v190
	v_med3_f32 v133, v133, s96, v190
	v_mul_f32_e32 v126, 0x3fb8aa3b, v118
	v_mul_f32_e32 v137, 0x3fb8aa3b, v133
	v_mul_f32_e32 v133, 0xbfb8aa3b, v133
	v_exp_f32_e32 v126, v126
	v_exp_f32_e32 v133, v133
	v_mul_f32_e32 v118, 0xbfb8aa3b, v118
	v_add_f32_e32 v132, v132, v149
	v_mul_f32_e32 v94, v94, v126
	v_mul_f32_e32 v126, v139, v133
	v_sub_f32_e32 v133, v114, v141
	v_add_f32_e32 v133, v144, v133
	v_exp_f32_e32 v118, v118
	v_sub_f32_e32 v133, v133, v102
	v_sub_f32_e32 v132, v114, v132
	v_med3_f32 v133, v133, s96, v190
	v_add_f32_e32 v132, v148, v132
	v_mul_f32_e32 v134, 0x3fb8aa3b, v133
	v_sub_f32_e32 v132, v132, v102
	v_exp_f32_e32 v134, v134
	v_med3_f32 v132, v132, s96, v190
	v_mul_f32_e32 v118, v136, v118
	v_mul_f32_e32 v136, 0x3fb8aa3b, v132
	v_mul_f32_e32 v132, 0xbfb8aa3b, v132
	v_exp_f32_e32 v137, v137
	v_exp_f32_e32 v132, v132
	v_mul_f32_e32 v86, v86, v134
	v_add_f32_e32 v134, 0, v157
	v_exp_f32_e32 v136, v136
	v_sub_f32_e32 v134, v115, v134
	v_mul_f32_e32 v90, v90, v137
	v_mul_f32_e32 v137, v147, v132
	v_add_f32_e32 v132, 0, v156
	v_add_f32_e32 v134, v155, v134
	v_sub_f32_e32 v132, v132, v99
	v_sub_f32_e32 v134, v134, v103
	v_med3_f32 v132, v132, s96, v190
	v_med3_f32 v134, v134, s96, v190
	v_mul_f32_e32 v82, v82, v136
	v_mul_f32_e32 v136, 0x3fb8aa3b, v132
	v_mul_f32_e32 v139, 0x3fb8aa3b, v134
	v_exp_f32_e32 v136, v136
	v_exp_f32_e32 v139, v139
	v_add_f32_e32 v123, 0, v123
	v_add_f32_e32 v119, 0, v119
	v_mul_f32_e32 v136, v95, v136
	v_mul_f32_e32 v95, v95, v139
	v_add_f32_e32 v139, v123, v204
	v_add_f32_e32 v123, v123, v131
	v_add_f32_e32 v131, v119, v205
	v_sub_f32_e32 v131, v115, v131
	v_add_f32_e32 v131, v203, v131
	v_add_f32_e32 v119, v119, v127
	v_sub_f32_e32 v127, v139, v99
	v_sub_f32_e32 v131, v131, v103
	v_med3_f32 v127, v127, s96, v190
	v_med3_f32 v131, v131, s96, v190
	v_mul_f32_e32 v139, 0x3fb8aa3b, v127
	v_mul_f32_e32 v140, 0x3fb8aa3b, v131
	v_exp_f32_e32 v139, v139
	v_exp_f32_e32 v140, v140
	v_mul_f32_e32 v133, 0xbfb8aa3b, v133
	v_add_f32_e32 v141, v119, v210
	v_exp_f32_e32 v133, v133
	v_sub_f32_e32 v141, v115, v141
	v_mul_f32_e32 v139, v91, v139
	v_mul_f32_e32 v91, v91, v140
	v_add_f32_e32 v140, v123, v209
	v_add_f32_e32 v141, v208, v141
	v_add_f32_e32 v119, v119, v135
	v_sub_f32_e32 v135, v140, v99
	v_sub_f32_e32 v140, v141, v103
	v_med3_f32 v135, v135, s96, v190
	v_med3_f32 v140, v140, s96, v190
	v_mul_f32_e32 v133, v142, v133
	v_mul_f32_e32 v141, 0x3fb8aa3b, v135
	v_mul_f32_e32 v142, 0x3fb8aa3b, v140
	v_add_f32_e32 v123, v123, v107
	v_exp_f32_e32 v141, v141
	v_exp_f32_e32 v142, v142
	v_add_f32_e32 v123, v123, v214
	v_sub_f32_e32 v123, v123, v99
	v_med3_f32 v123, v123, s96, v190
	v_mul_f32_e32 v132, 0xbfb8aa3b, v132
	v_mul_f32_e32 v134, 0xbfb8aa3b, v134
	v_mul_f32_e32 v141, v87, v141
	v_mul_f32_e32 v87, v87, v142
	v_mul_f32_e32 v142, 0x3fb8aa3b, v123
	v_exp_f32_e32 v132, v132
	v_exp_f32_e32 v134, v134
; __device__ __forceinline__ unsigned cvt_pk_bf16(float lo, float hi) { unsigned r; asm volatile("v_cvt_pk_bf16_f32 %0, %1, %2" : "=v"(r) : "v"(lo), "v"(hi)); return r; }
;     __device__ __forceinline__ void operator()(const f32x4 (&acc)[2][2][4][2], const pg8::Unit& u, int wr, int wc, int fr, int fq) const {
;     ...
;                             { const float z = acc[ai][0][m][1][j]; const float e = __expf(fminf(-z, 30.f)); const float s = __builtin_amdgcn_rcpf(1.f + e); lfF[m] = __logf(lbF[j] + (1.f - lbF[j]) * s); kkF[m] = (1.f - lbF[j]) * e * s; }
;                             { const float z = acc[ai][1][m][0][j]; const float e = __expf(fminf(-z, 30.f)); const float s = __builtin_amdgcn_rcpf(1.f + e); lfB[m] = __logf(lbB[j] + (1.f - lbB[j]) * s); kkB[m] = (1.f - lbB[j]) * e * s; }
;                             pF[m] = scan16(lfF[m]); pB[m] = scan16(lfB[m]);
;                             tF[m] = __int_as_float(__builtin_amdgcn_update_dpp(0, __float_as_int(pF[m]), 0x15F, 0xf, 0xf, true));
;                             tB[m] = __int_as_float(__builtin_amdgcn_update_dpp(0, __float_as_int(pB[m]), 0x15F, 0xf, 0xf, true));
;                         }
;                         const float rF = tF[0] + tF[1], blF = rF + tF[2] + tF[3];
;                         const float rB = tB[2] + tB[3], blB = rB + tB[0] + tB[1];
;                         float cF = 0.f, cB = 0.f;
; #pragma unroll
;                         for (int m = 0; m < 4; ++m) {
;                             const float bF = pF[m] + cF; cF += tF[m];
;                             const float bB = blB - (pB[m] + cB) + lfB[m]; cB += tB[m];
;                             const float xF = clamp80(bF - rF), xB = clamp80(bB - rB);
;                             const float q = acc[ai][0][m][0][j];
;                             vQF[m][jj] = q * __expf(xF); vKF[m][jj] = kkF[m] * __expf(-xF);
;                             vQB[m][jj] = q * __expf(xB); vKB[m][jj] = kkB[m] * __expf(-xB);
;                         }
;                         rtv[0][j] = rF; rtv[1][j] = rB; rtv[2][j] = blF - rF; rtv[3][j] = blB - rB;
;                     }
; #pragma unroll
;                     for (int m = 0; m < 4; ++m) { oQF[m][jp] = cvt_pk_bf16(vQF[m][0], vQF[m][1]); oQB[m][jp] = cvt_pk_bf16(vQB[m][0], vQB[m][1]); oKF[m][jp] = cvt_pk_bf16(vKF[m][0], vKF[m][1]); oKB[m][jp] = cvt_pk_bf16(vKB[m][0], vKB[m][1]); }
	v_exp_f32_e32 v142, v142
	v_add_f32_e32 v119, v119, v215
	v_sub_f32_e32 v119, v115, v119
	v_add_f32_e32 v119, v212, v119
	v_mul_f32_e32 v132, v152, v132
	v_mul_f32_e32 v134, v153, v134
	v_sub_f32_e32 v119, v119, v103
	v_mul_f32_e32 v147, v83, v142
	v_cvt_pk_bf16_f32 v154, v216, v136
	v_cvt_pk_bf16_f32 v150, v94, v95
	v_cvt_pk_bf16_f32 v146, v138, v132
	v_cvt_pk_bf16_f32 v142, v118, v134
	v_cvt_pk_bf16_f32 v156, v122, v139
	v_cvt_pk_bf16_f32 v152, v90, v91
	v_med3_f32 v119, v119, s96, v190
	v_max_f32_e32 v90, 0xc1f00000, v128
	v_mul_f32_e32 v127, 0xbfb8aa3b, v127
	v_mul_f32_e32 v131, 0xbfb8aa3b, v131
	v_mul_f32_e32 v144, 0x3fb8aa3b, v119
	v_mul_f32_e32 v90, 0xbfb8aa3b, v90
	v_exp_f32_e32 v127, v127
	v_exp_f32_e32 v131, v131
	v_exp_f32_e32 v144, v144
	v_exp_f32_e32 v90, v90
	v_mul_f32_e32 v140, 0xbfb8aa3b, v140
	v_mul_f32_e32 v127, v201, v127
	v_mul_f32_e32 v131, v202, v131
	v_mul_f32_e32 v135, 0xbfb8aa3b, v135
	v_exp_f32_e32 v140, v140
	v_mul_f32_e32 v83, v83, v144
	v_cvt_pk_bf16_f32 v148, v130, v127
	v_cvt_pk_bf16_f32 v144, v126, v131
	v_cvt_pk_bf16_f32 v130, v143, v141
	v_cvt_pk_bf16_f32 v138, v86, v87
	v_add_f32_e32 v86, 1.0, v90
	v_exp_f32_e32 v135, v135
	v_rcp_f32_e32 v86, v86
	v_mul_f32_e32 v140, v207, v140
	v_sub_f32_e32 v122, 1.0, v177
	v_mul_f32_e32 v135, v206, v135
	v_cvt_pk_bf16_f32 v134, v145, v135
	v_cvt_pk_bf16_f32 v126, v133, v140
	v_cvt_pk_bf16_f32 v132, v151, v147
	v_cvt_pk_bf16_f32 v140, v82, v83
	v_fma_f32 v82, v86, v122, v177
	v_max_f32_e32 v87, 0xc1f00000, v124
	v_mul_f32_e32 v87, 0xbfb8aa3b, v87
	v_exp_f32_e32 v87, v87
	v_mul_f32_e32 v123, 0xbfb8aa3b, v123
	v_log_f32_e32 v82, v82
	v_exp_f32_e32 v123, v123
	v_add_f32_e32 v91, 1.0, v87
	v_rcp_f32_e32 v91, v91
	v_mul_f32_e32 v123, v213, v123
	v_cvt_pk_bf16_f32 v136, v217, v123
	v_sub_f32_e32 v123, 1.0, v192
	v_fma_f32 v94, v91, v123, v192
	v_mul_f32_e32 v119, 0xbfb8aa3b, v119
	v_mul_f32_e32 v82, 0x3f317218, v82
	v_mul_f32_e32 v83, v90, v122
	v_log_f32_e32 v94, v94
	v_mul_f32_e32 v133, v86, v83
	v_add_f32_dpp v82, v82, v82 row_shr:1 row_mask:0xf bank_mask:0xf bound_ctrl:1
	s_nop 1
	v_add_f32_dpp v82, v82, v82 row_shr:2 row_mask:0xf bank_mask:0xf bound_ctrl:1
	v_exp_f32_e32 v119, v119
	v_mul_f32_e32 v83, 0x3f317218, v94
	v_mov_b32_e32 v131, v83
	v_mul_f32_e32 v83, v87, v123
	v_mul_f32_e32 v127, v91, v83
	v_max_f32_e32 v83, 0xc1f00000, v120
	v_mul_f32_e32 v83, 0xbfb8aa3b, v83
	v_exp_f32_e32 v90, v83
	v_add_f32_dpp v82, v82, v82 row_shr:4 row_mask:0xf bank_mask:0xf bound_ctrl:1
	v_add_f32_e32 v118, 1.0, v116
	v_rcp_f32_e32 v118, v118
	v_add_f32_dpp v83, v82, v82 row_shr:8 row_mask:0xf bank_mask:0xf bound_ctrl:1
	v_add_f32_e32 v82, 1.0, v90
	v_rcp_f32_e32 v91, v82
	v_mul_f32_e32 v119, v211, v119
	v_cvt_pk_bf16_f32 v128, v137, v119
	v_fma_f32 v119, v118, v123, v192
	v_fma_f32 v86, v91, v122, v177
	v_mul_f32_e32 v90, v90, v122
	v_add_f32_dpp v82, v131, v131 row_shr:1 row_mask:0xf bank_mask:0xf bound_ctrl:1
	v_log_f32_e32 v94, v86
	s_nop 0
	v_add_f32_dpp v82, v82, v82 row_shr:2 row_mask:0xf bank_mask:0xf bound_ctrl:1
	v_mov_b32_dpp v86, v83 row_newbcast:15 row_mask:0xf bank_mask:0xf bound_ctrl:1
	v_add_f32_e32 v207, 0, v83
	v_add_f32_dpp v82, v82, v82 row_shr:4 row_mask:0xf bank_mask:0xf bound_ctrl:1
	v_sub_f32_e32 v201, 1.0, v191
	v_mul_f32_e32 v94, 0x3f317218, v94
	v_add_f32_dpp v87, v82, v82 row_shr:8 row_mask:0xf bank_mask:0xf bound_ctrl:1
	v_log_f32_e32 v119, v119
	v_mul_f32_e32 v120, v91, v90
	v_mov_b32_dpp v82, v87 row_newbcast:15 row_mask:0xf bank_mask:0xf bound_ctrl:1
	v_add_f32_e32 v203, 0, v87
	v_mul_f32_e32 v90, 0x3f317218, v119
	v_mov_b32_e32 v137, v90
	v_max_f32_e32 v91, 0xc1f00000, v112
	v_mul_f32_e32 v91, 0xbfb8aa3b, v91
	v_mul_f32_e32 v90, v116, v123
	v_exp_f32_e32 v91, v91
	v_mul_f32_e32 v135, v118, v90
	v_add_f32_dpp v90, v94, v94 row_shr:1 row_mask:0xf bank_mask:0xf bound_ctrl:1
	v_add_f32_e32 v118, 1.0, v108
	v_rcp_f32_e32 v118, v118
	v_add_f32_dpp v90, v90, v90 row_shr:2 row_mask:0xf bank_mask:0xf bound_ctrl:1
	v_max_f32_e32 v87, 0xc1f00000, v125
	v_mul_f32_e32 v87, 0xbfb8aa3b, v87
	v_add_f32_dpp v90, v90, v90 row_shr:4 row_mask:0xf bank_mask:0xf bound_ctrl:1
	v_fma_f32 v119, v118, v123, v192
	v_exp_f32_e32 v87, v87
	v_add_f32_dpp v143, v90, v90 row_shr:8 row_mask:0xf bank_mask:0xf bound_ctrl:1
	v_add_f32_e32 v90, 1.0, v91
	v_rcp_f32_e32 v95, v90
	v_mul_f32_e32 v91, v91, v122
	v_mov_b32_dpp v111, v214 row_newbcast:15 row_mask:0xf bank_mask:0xf bound_ctrl:1
	v_add_f32_dpp v90, v137, v137 row_shr:1 row_mask:0xf bank_mask:0xf bound_ctrl:1
	v_fma_f32 v94, v95, v122, v177
	v_mul_f32_e32 v147, v95, v91
	v_add_f32_dpp v90, v90, v90 row_shr:2 row_mask:0xf bank_mask:0xf bound_ctrl:1
	v_log_f32_e32 v112, v94
	s_nop 0
	v_add_f32_dpp v90, v90, v90 row_shr:4 row_mask:0xf bank_mask:0xf bound_ctrl:1
	v_mov_b32_dpp v94, v143 row_newbcast:15 row_mask:0xf bank_mask:0xf bound_ctrl:1
	s_nop 0
	v_add_f32_dpp v139, v90, v90 row_shr:8 row_mask:0xf bank_mask:0xf bound_ctrl:1
	s_nop 0
	v_mul_f32_e32 v112, 0x3f317218, v112
	v_mov_b32_dpp v90, v139 row_newbcast:15 row_mask:0xf bank_mask:0xf bound_ctrl:1
	v_log_f32_e32 v119, v119
	s_nop 1
	v_mul_f32_e32 v91, 0x3f317218, v119
	v_mov_b32_e32 v145, v91
	v_max_f32_e32 v95, 0xc1f00000, v104
	v_mul_f32_e32 v95, 0xbfb8aa3b, v95
	v_mul_f32_e32 v91, v108, v123
	v_exp_f32_e32 v95, v95
	v_mul_f32_e32 v141, v118, v91
	v_add_f32_dpp v91, v112, v112 row_shr:1 row_mask:0xf bank_mask:0xf bound_ctrl:1
	v_add_f32_e32 v119, 1.0, v100
	v_rcp_f32_e32 v119, v119
	v_add_f32_dpp v91, v91, v91 row_shr:2 row_mask:0xf bank_mask:0xf bound_ctrl:1
	v_add_f32_dpp v108, v145, v145 row_shr:1 row_mask:0xf bank_mask:0xf bound_ctrl:1
	v_fma_f32 v124, v119, v123, v192
; __device__ __forceinline__ float scan16(float x) { x += dpp_shr<1>(x); x += dpp_shr<2>(x); x += dpp_shr<4>(x); x += dpp_shr<8>(x); return x; }
;     __device__ __forceinline__ void operator()(const f32x4 (&acc)[2][2][4][2], const pg8::Unit& u, int wr, int wc, int fr, int fq) const {
;     ...
;                             { const float z = acc[ai][0][m][1][j]; const float e = __expf(fminf(-z, 30.f)); const float s = __builtin_amdgcn_rcpf(1.f + e); lfF[m] = __logf(lbF[j] + (1.f - lbF[j]) * s); kkF[m] = (1.f - lbF[j]) * e * s; }
;                             { const float z = acc[ai][1][m][0][j]; const float e = __expf(fminf(-z, 30.f)); const float s = __builtin_amdgcn_rcpf(1.f + e); lfB[m] = __logf(lbB[j] + (1.f - lbB[j]) * s); kkB[m] = (1.f - lbB[j]) * e * s; }
;                             pF[m] = scan16(lfF[m]); pB[m] = scan16(lfB[m]);
;                             tF[m] = __int_as_float(__builtin_amdgcn_update_dpp(0, __float_as_int(pF[m]), 0x15F, 0xf, 0xf, true));
;                             tB[m] = __int_as_float(__builtin_amdgcn_update_dpp(0, __float_as_int(pB[m]), 0x15F, 0xf, 0xf, true));
	v_add_f32_dpp v91, v91, v91 row_shr:4 row_mask:0xf bank_mask:0xf bound_ctrl:1
	v_add_f32_dpp v108, v108, v108 row_shr:2 row_mask:0xf bank_mask:0xf bound_ctrl:1
	s_nop 0
	v_add_f32_dpp v104, v91, v91 row_shr:8 row_mask:0xf bank_mask:0xf bound_ctrl:1
	v_add_f32_e32 v91, 1.0, v95
	v_rcp_f32_e32 v91, v91
	v_mul_f32_e32 v95, v95, v122
	v_add_f32_dpp v108, v108, v108 row_shr:4 row_mask:0xf bank_mask:0xf bound_ctrl:1
	v_fma_f32 v112, v91, v122, v177
	v_mul_f32_e32 v155, v91, v95
	v_add_f32_dpp v149, v108, v108 row_shr:8 row_mask:0xf bank_mask:0xf bound_ctrl:1
	v_log_f32_e32 v112, v112
	v_mov_b32_dpp v108, v104 row_newbcast:15 row_mask:0xf bank_mask:0xf bound_ctrl:1
	v_mov_b32_dpp v116, v149 row_newbcast:15 row_mask:0xf bank_mask:0xf bound_ctrl:1
	s_nop 1
	v_mul_f32_e32 v112, 0x3f317218, v112
	s_nop 0
	v_log_f32_e32 v124, v124
	s_nop 1
	v_mul_f32_e32 v91, 0x3f317218, v124
	v_mov_b32_e32 v153, v91
	v_mul_f32_e32 v91, v100, v123
	v_mul_f32_e32 v151, v119, v91
	s_nop 0
	v_add_f32_dpp v91, v112, v112 row_shr:1 row_mask:0xf bank_mask:0xf bound_ctrl:1
	v_max_f32_e32 v95, 0xc1f00000, v129
	v_mul_f32_e32 v95, 0xbfb8aa3b, v95
	v_add_f32_dpp v91, v91, v91 row_shr:2 row_mask:0xf bank_mask:0xf bound_ctrl:1
	v_exp_f32_e32 v95, v95
	v_sub_f32_e32 v124, 1.0, v173
	v_add_f32_dpp v91, v91, v91 row_shr:4 row_mask:0xf bank_mask:0xf bound_ctrl:1
	s_nop 1
	v_add_f32_dpp v157, v91, v91 row_shr:8 row_mask:0xf bank_mask:0xf bound_ctrl:1
	v_add_f32_dpp v91, v153, v153 row_shr:1 row_mask:0xf bank_mask:0xf bound_ctrl:1
	s_nop 0
	v_mov_b32_dpp v112, v157 row_newbcast:15 row_mask:0xf bank_mask:0xf bound_ctrl:1
	v_add_f32_dpp v91, v91, v91 row_shr:2 row_mask:0xf bank_mask:0xf bound_ctrl:1
	s_nop 1
	v_add_f32_dpp v91, v91, v91 row_shr:4 row_mask:0xf bank_mask:0xf bound_ctrl:1
	s_nop 1
	v_add_f32_dpp v129, v91, v91 row_shr:8 row_mask:0xf bank_mask:0xf bound_ctrl:1
	v_add_f32_e32 v91, 1.0, v95
	v_rcp_f32_e32 v91, v91
	v_mul_f32_e32 v95, v95, v124
	v_mov_b32_dpp v118, v129 row_newbcast:15 row_mask:0xf bank_mask:0xf bound_ctrl:1
	v_fma_f32 v100, v91, v124, v173
	s_nop 1
	v_log_f32_e32 v100, v100
	v_add_f32_e32 v119, 1.0, v87
	v_rcp_f32_e32 v119, v119
	v_mul_f32_e32 v87, v87, v201
	v_fma_f32 v125, v119, v201, v191
	s_nop 0
	v_mul_f32_e32 v83, 0x3f317218, v100
	s_nop 0
	v_log_f32_e32 v202, v125
	v_mul_f32_e32 v125, v91, v95
	v_add_f32_dpp v83, v83, v83 row_shr:1 row_mask:0xf bank_mask:0xf bound_ctrl:1
	s_nop 1
	v_add_f32_dpp v83, v83, v83 row_shr:2 row_mask:0xf bank_mask:0xf bound_ctrl:1
	s_nop 0
	v_mul_f32_e32 v91, 0x3f317218, v202
	v_mul_f32_e32 v202, v119, v87
	v_max_f32_e32 v87, 0xc1f00000, v121
	v_mul_f32_e32 v87, 0xbfb8aa3b, v87
	v_mov_b32_e32 v204, v91
	v_exp_f32_e32 v91, v87
	v_add_f32_dpp v83, v83, v83 row_shr:4 row_mask:0xf bank_mask:0xf bound_ctrl:1
	v_add_f32_e32 v121, 1.0, v117
	v_rcp_f32_e32 v121, v121
	v_add_f32_dpp v205, v83, v83 row_shr:8 row_mask:0xf bank_mask:0xf bound_ctrl:1
	v_add_f32_e32 v83, 1.0, v91
	v_rcp_f32_e32 v95, v83
	v_fma_f32 v208, v121, v201, v191
	v_mul_f32_e32 v91, v91, v124
	v_add_f32_dpp v83, v204, v204 row_shr:1 row_mask:0xf bank_mask:0xf bound_ctrl:1
	v_fma_f32 v87, v95, v124, v173
	s_nop 0
	v_add_f32_dpp v83, v83, v83 row_shr:2 row_mask:0xf bank_mask:0xf bound_ctrl:1
	s_nop 0
	v_log_f32_e32 v100, v87
	v_add_f32_dpp v83, v83, v83 row_shr:4 row_mask:0xf bank_mask:0xf bound_ctrl:1
	v_mov_b32_dpp v87, v205 row_newbcast:15 row_mask:0xf bank_mask:0xf bound_ctrl:1
	s_nop 0
	v_add_f32_dpp v206, v83, v83 row_shr:8 row_mask:0xf bank_mask:0xf bound_ctrl:1
	s_nop 0
	v_mul_f32_e32 v100, 0x3f317218, v100
	v_mov_b32_dpp v83, v206 row_newbcast:15 row_mask:0xf bank_mask:0xf bound_ctrl:1
	v_log_f32_e32 v209, v208
	v_mul_f32_e32 v208, v95, v91
	s_nop 1
	v_mul_f32_e32 v91, 0x3f317218, v209
	v_mov_b32_e32 v210, v91
	v_max_f32_e32 v95, 0xc1f00000, v113
	v_mul_f32_e32 v91, v117, v201
	v_mul_f32_e32 v95, 0xbfb8aa3b, v95
	v_mul_f32_e32 v209, v121, v91
	v_add_f32_dpp v91, v100, v100 row_shr:1 row_mask:0xf bank_mask:0xf bound_ctrl:1
	v_exp_f32_e32 v100, v95
	v_add_f32_e32 v121, 1.0, v109
	v_add_f32_dpp v91, v91, v91 row_shr:2 row_mask:0xf bank_mask:0xf bound_ctrl:1
	v_rcp_f32_e32 v121, v121
	s_nop 0
	v_add_f32_dpp v91, v91, v91 row_shr:4 row_mask:0xf bank_mask:0xf bound_ctrl:1
	v_fma_f32 v213, v121, v201, v191
	s_nop 0
	v_add_f32_dpp v211, v91, v91 row_shr:8 row_mask:0xf bank_mask:0xf bound_ctrl:1
	v_add_f32_e32 v91, 1.0, v100
	v_rcp_f32_e32 v113, v91
	v_mul_f32_e32 v100, v100, v124
	v_add_f32_dpp v91, v210, v210 row_shr:1 row_mask:0xf bank_mask:0xf bound_ctrl:1
	v_fma_f32 v95, v113, v124, v173
	s_nop 0
	v_add_f32_dpp v91, v91, v91 row_shr:2 row_mask:0xf bank_mask:0xf bound_ctrl:1
	s_nop 0
	v_log_f32_e32 v117, v95
	v_add_f32_dpp v91, v91, v91 row_shr:4 row_mask:0xf bank_mask:0xf bound_ctrl:1
	v_mov_b32_dpp v95, v211 row_newbcast:15 row_mask:0xf bank_mask:0xf bound_ctrl:1
	s_nop 0
	v_add_f32_dpp v212, v91, v91 row_shr:8 row_mask:0xf bank_mask:0xf bound_ctrl:1
	s_nop 0
	v_mul_f32_e32 v117, 0x3f317218, v117
	v_mov_b32_dpp v91, v212 row_newbcast:15 row_mask:0xf bank_mask:0xf bound_ctrl:1
	v_log_f32_e32 v214, v213
	v_mul_f32_e32 v213, v113, v100
	s_nop 1
	v_mul_f32_e32 v100, 0x3f317218, v214
	v_mov_b32_e32 v215, v100
	v_mul_f32_e32 v100, v109, v201
	v_mul_f32_e32 v214, v121, v100
	v_add_f32_e32 v121, 1.0, v101
	v_add_f32_dpp v100, v117, v117 row_shr:1 row_mask:0xf bank_mask:0xf bound_ctrl:1
	v_rcp_f32_e32 v121, v121
	v_add_f32_dpp v109, v215, v215 row_shr:1 row_mask:0xf bank_mask:0xf bound_ctrl:1
	v_add_f32_dpp v100, v100, v100 row_shr:2 row_mask:0xf bank_mask:0xf bound_ctrl:1
	v_fma_f32 v218, v121, v201, v191
	s_nop 0
	v_add_f32_dpp v100, v100, v100 row_shr:4 row_mask:0xf bank_mask:0xf bound_ctrl:1
; __device__ __forceinline__ float scan16(float x) { x += dpp_shr<1>(x); x += dpp_shr<2>(x); x += dpp_shr<4>(x); x += dpp_shr<8>(x); return x; }
; __device__ __forceinline__ float clamp80(float x) { return fminf(fmaxf(x, -80.f), 80.f); }
;     __device__ __forceinline__ void operator()(const f32x4 (&acc)[2][2][4][2], const pg8::Unit& u, int wr, int wc, int fr, int fq) const {
;     ...
;                             { const float z = acc[ai][0][m][1][j]; const float e = __expf(fminf(-z, 30.f)); const float s = __builtin_amdgcn_rcpf(1.f + e); lfF[m] = __logf(lbF[j] + (1.f - lbF[j]) * s); kkF[m] = (1.f - lbF[j]) * e * s; }
;                             { const float z = acc[ai][1][m][0][j]; const float e = __expf(fminf(-z, 30.f)); const float s = __builtin_amdgcn_rcpf(1.f + e); lfB[m] = __logf(lbB[j] + (1.f - lbB[j]) * s); kkB[m] = (1.f - lbB[j]) * e * s; }
;                             pF[m] = scan16(lfF[m]); pB[m] = scan16(lfB[m]);
;                             tF[m] = __int_as_float(__builtin_amdgcn_update_dpp(0, __float_as_int(pF[m]), 0x15F, 0xf, 0xf, true));
;                             tB[m] = __int_as_float(__builtin_amdgcn_update_dpp(0, __float_as_int(pB[m]), 0x15F, 0xf, 0xf, true));
;                         }
;                         const float rF = tF[0] + tF[1], blF = rF + tF[2] + tF[3];
;                         const float rB = tB[2] + tB[3], blB = rB + tB[0] + tB[1];
;                         float cF = 0.f, cB = 0.f;
; #pragma unroll
;                         for (int m = 0; m < 4; ++m) {
;                             const float bF = pF[m] + cF; cF += tF[m];
;                             const float bB = blB - (pB[m] + cB) + lfB[m]; cB += tB[m];
;                             const float xF = clamp80(bF - rF), xB = clamp80(bB - rB);
;                             const float q = acc[ai][0][m][0][j];
;                             vQF[m][jj] = q * __expf(xF); vKF[m][jj] = kkF[m] * __expf(-xF);
;                             vQB[m][jj] = q * __expf(xB); vKB[m][jj] = kkB[m] * __expf(-xB);
;                         }
	v_add_f32_dpp v109, v109, v109 row_shr:2 row_mask:0xf bank_mask:0xf bound_ctrl:1
	s_nop 0
	v_add_f32_dpp v216, v100, v100 row_shr:8 row_mask:0xf bank_mask:0xf bound_ctrl:1
	v_add_f32_e32 v100, 1.0, v105
	v_rcp_f32_e32 v100, v100
	v_mul_f32_e32 v105, v105, v124
	v_add_f32_dpp v109, v109, v109 row_shr:4 row_mask:0xf bank_mask:0xf bound_ctrl:1
	v_fma_f32 v113, v100, v124, v173
	s_nop 0
	v_add_f32_dpp v217, v109, v109 row_shr:8 row_mask:0xf bank_mask:0xf bound_ctrl:1
	v_mov_b32_dpp v109, v216 row_newbcast:15 row_mask:0xf bank_mask:0xf bound_ctrl:1
	v_log_f32_e32 v113, v113
	v_mov_b32_dpp v119, v217 row_newbcast:15 row_mask:0xf bank_mask:0xf bound_ctrl:1
	s_nop 1
	v_mul_f32_e32 v113, 0x3f317218, v113
	s_nop 0
	v_log_f32_e32 v218, v218
	v_mul_f32_e32 v219, v100, v105
	s_nop 1
	v_mul_f32_e32 v100, 0x3f317218, v218
	v_mov_b32_e32 v218, v100
	v_mul_f32_e32 v100, v101, v201
	v_mul_f32_e32 v220, v121, v100
	s_nop 0
	v_add_f32_dpp v100, v113, v113 row_shr:1 row_mask:0xf bank_mask:0xf bound_ctrl:1
	s_nop 1
	v_add_f32_dpp v100, v100, v100 row_shr:2 row_mask:0xf bank_mask:0xf bound_ctrl:1
	s_nop 1
	v_add_f32_dpp v100, v100, v100 row_shr:4 row_mask:0xf bank_mask:0xf bound_ctrl:1
	s_nop 1
	v_add_f32_dpp v221, v100, v100 row_shr:8 row_mask:0xf bank_mask:0xf bound_ctrl:1
	v_add_f32_dpp v100, v218, v218 row_shr:1 row_mask:0xf bank_mask:0xf bound_ctrl:1
	s_nop 1
	v_add_f32_dpp v100, v100, v100 row_shr:2 row_mask:0xf bank_mask:0xf bound_ctrl:1
	s_nop 1
	v_add_f32_dpp v100, v100, v100 row_shr:4 row_mask:0xf bank_mask:0xf bound_ctrl:1
	s_nop 1
	v_add_f32_dpp v222, v100, v100 row_shr:8 row_mask:0xf bank_mask:0xf bound_ctrl:1
	v_pk_add_f32 v[100:101], v[86:87], v[94:95]
	v_add_f32_e32 v86, 0, v86
	v_sub_f32_e32 v105, v207, v100
	v_med3_f32 v105, v105, s96, v190
	v_mul_f32_e32 v113, 0x3fb8aa3b, v105
	v_exp_f32_e32 v121, v113
	v_mul_f32_e32 v105, 0xbfb8aa3b, v105
	v_exp_f32_e32 v105, v105
	v_mov_b32_dpp v117, v222 row_newbcast:15 row_mask:0xf bank_mask:0xf bound_ctrl:1
	v_mul_f32_e32 v207, v96, v121
	v_add_f32_e32 v121, v86, v143
	v_sub_f32_e32 v121, v121, v100
	v_med3_f32 v121, v121, s96, v190
	v_mul_f32_e32 v143, 0x3fb8aa3b, v121
	v_mul_f32_e32 v121, 0xbfb8aa3b, v121
	v_add_f32_e32 v86, v86, v94
	v_exp_f32_e32 v121, v121
	v_add_f32_e32 v104, v86, v104
	v_add_f32_e32 v86, v86, v108
	v_sub_f32_e32 v104, v104, v100
	v_add_f32_e32 v86, v86, v157
	v_med3_f32 v104, v104, s96, v190
	v_sub_f32_e32 v86, v86, v100
	v_mul_f32_e32 v133, v133, v105
	v_mul_f32_e32 v105, 0x3fb8aa3b, v104
	v_mul_f32_e32 v104, 0xbfb8aa3b, v104
	v_med3_f32 v86, v86, s96, v190
	v_mul_f32_e32 v223, v120, v121
	v_exp_f32_e32 v105, v105
	v_exp_f32_e32 v104, v104
	v_mul_f32_e32 v120, 0x3fb8aa3b, v86
	v_exp_f32_e32 v120, v120
	v_mul_f32_e32 v224, v88, v105
	v_mul_f32_e32 v225, v147, v104
	v_pk_add_f32 v[104:105], v[118:119], v[116:117]
	v_mul_f32_e32 v226, v84, v120
	v_add_f32_e32 v117, 0, v82
	v_pk_add_f32 v[120:121], v[104:105], v[82:83]
	v_add_f32_e32 v118, v117, v139
	v_pk_add_f32 v[120:121], v[120:121], v[90:91]
	v_add_f32_e32 v117, v117, v90
	v_sub_f32_e32 v82, v120, v203
	v_sub_f32_e32 v118, v120, v118
	v_add_f32_e32 v82, v131, v82
	v_add_f32_e32 v118, v137, v118
	v_sub_f32_e32 v82, v82, v104
	v_sub_f32_e32 v118, v118, v104
	v_med3_f32 v82, v82, s96, v190
	v_med3_f32 v118, v118, s96, v190
	v_mul_f32_e32 v90, 0x3fb8aa3b, v82
	v_mul_f32_e32 v131, 0x3fb8aa3b, v118
	v_mul_f32_e32 v118, 0xbfb8aa3b, v118
	v_exp_f32_e32 v90, v90
	v_exp_f32_e32 v118, v118
	v_add_f32_e32 v116, v117, v116
	v_mul_f32_e32 v82, 0xbfb8aa3b, v82
	v_add_f32_e32 v116, v116, v129
	v_exp_f32_e32 v82, v82
	v_sub_f32_e32 v116, v120, v116
	v_add_f32_e32 v139, v117, v149
	v_add_f32_e32 v116, v153, v116
	v_mul_f32_e32 v90, v96, v90
	v_mul_f32_e32 v96, v135, v118
	v_sub_f32_e32 v118, v120, v139
	v_sub_f32_e32 v116, v116, v104
	v_add_f32_e32 v118, v145, v118
	v_med3_f32 v116, v116, s96, v190
	v_mul_f32_e32 v82, v127, v82
	v_sub_f32_e32 v117, v118, v104
	v_mul_f32_e32 v127, 0x3fb8aa3b, v116
	v_med3_f32 v117, v117, s96, v190
	v_exp_f32_e32 v127, v127
	v_mul_f32_e32 v118, 0x3fb8aa3b, v117
	v_exp_f32_e32 v118, v118
	v_exp_f32_e32 v143, v143
	v_mul_f32_e32 v84, v84, v127
	v_add_f32_e32 v127, 0, v206
	v_exp_f32_e32 v131, v131
	v_sub_f32_e32 v127, v121, v127
	v_mul_f32_e32 v88, v88, v118
	v_add_f32_e32 v118, 0, v205
	v_add_f32_e32 v127, v204, v127
	v_sub_f32_e32 v118, v118, v101
	v_sub_f32_e32 v127, v127, v105
	v_med3_f32 v118, v118, s96, v190
	v_med3_f32 v127, v127, s96, v190
	v_mul_f32_e32 v94, v92, v143
	v_mul_f32_e32 v92, v92, v131
	v_mul_f32_e32 v129, 0x3fb8aa3b, v118
	v_mul_f32_e32 v118, 0xbfb8aa3b, v118
	v_mul_f32_e32 v131, 0x3fb8aa3b, v127
	v_mul_f32_e32 v127, 0xbfb8aa3b, v127
	v_exp_f32_e32 v118, v118
	v_exp_f32_e32 v127, v127
	v_add_f32_e32 v87, 0, v87
	v_add_f32_e32 v83, 0, v83
	v_mul_f32_e32 v118, v125, v118
	v_mul_f32_e32 v125, v202, v127
	v_add_f32_e32 v127, v87, v211
	v_add_f32_e32 v87, v87, v95
	v_add_f32_e32 v95, v83, v212
	v_exp_f32_e32 v129, v129
	v_exp_f32_e32 v131, v131
	v_sub_f32_e32 v95, v121, v95
	v_add_f32_e32 v95, v210, v95
	v_add_f32_e32 v83, v83, v91
	v_sub_f32_e32 v91, v127, v101
	v_sub_f32_e32 v95, v95, v105
	v_med3_f32 v91, v91, s96, v190
	v_med3_f32 v95, v95, s96, v190
	v_mul_f32_e32 v129, v97, v129
	v_mul_f32_e32 v97, v97, v131
	v_mul_f32_e32 v127, 0x3fb8aa3b, v91
	v_mul_f32_e32 v131, 0x3fb8aa3b, v95
	v_exp_f32_e32 v127, v127
	v_exp_f32_e32 v131, v131
	v_add_f32_e32 v135, v83, v217
	v_sub_f32_e32 v135, v121, v135
	v_mul_f32_e32 v127, v93, v127
	v_mul_f32_e32 v93, v93, v131
	v_add_f32_e32 v131, v87, v216
	v_add_f32_e32 v135, v215, v135
	v_add_f32_e32 v83, v83, v119
	v_sub_f32_e32 v119, v131, v101
; __device__ __forceinline__ float clamp80(float x) { return fminf(fmaxf(x, -80.f), 80.f); }
;     __device__ __forceinline__ void operator()(const f32x4 (&acc)[2][2][4][2], const pg8::Unit& u, int wr, int wc, int fr, int fq) const {
;     ...
;                         for (int m = 0; m < 4; ++m) {
;                             const float bF = pF[m] + cF; cF += tF[m];
;                             const float bB = blB - (pB[m] + cB) + lfB[m]; cB += tB[m];
;                             const float xF = clamp80(bF - rF), xB = clamp80(bB - rB);
;                             const float q = acc[ai][0][m][0][j];
;                             vQF[m][jj] = q * __expf(xF); vKF[m][jj] = kkF[m] * __expf(-xF);
;                             vQB[m][jj] = q * __expf(xB); vKB[m][jj] = kkB[m] * __expf(-xB);
;                         }
;                         rtv[0][j] = rF; rtv[1][j] = rB; rtv[2][j] = blF - rF; rtv[3][j] = blB - rB;
;                     }
; #pragma unroll
;                     for (int m = 0; m < 4; ++m) { oQF[m][jp] = cvt_pk_bf16(vQF[m][0], vQF[m][1]); oQB[m][jp] = cvt_pk_bf16(vQB[m][0], vQB[m][1]); oKF[m][jp] = cvt_pk_bf16(vKF[m][0], vKF[m][1]); oKB[m][jp] = cvt_pk_bf16(vKB[m][0], vKB[m][1]); }
;                 }
;                 if (fr == 0) {
; #pragma unroll
;                     for (int t = 0; t < 4; ++t) *(f32x4*)(RT + (size_t)t * NCHUNK * 512 + (size_t)cid * 512 + ch0) = rtv[t];
;                 }
; #pragma unroll
;                 for (int mp = 0; mp < 2; ++mp) {
;                     const int a = 2 * mp, bb = 2 * mp + 1, odd = fq & 1;
;                     const size_t off = (size_t)(rowc + 16 * (odd ? bb : a) + fr) * 512 + (ch0 - 4 * odd);
;                     const f32x4 va = acc[ai][1][a][1], vb = acc[ai][1][bb][1];
;                     const unsigned oVa0 = cvt_pk_bf16(va[0], va[1]), oVa1 = cvt_pk_bf16(va[2], va[3]), oVb0 = cvt_pk_bf16(vb[0], vb[1]), oVb1 = cvt_pk_bf16(vb[2], vb[3]);
;                     asm volatile("s_nop 1" ::: "memory");
;     ...
;                     WIDE_ST(QF, oQF[a][0], oQF[a][1], oQF[bb][0], oQF[bb][1]); WIDE_ST(QB, oQB[a][0], oQB[a][1], oQB[bb][0], oQB[bb][1]);
;                     WIDE_ST(KF, oKF[a][0], oKF[a][1], oKF[bb][0], oKF[bb][1]); WIDE_ST(KB, oKB[a][0], oKB[a][1], oKB[bb][0], oKB[bb][1]);
;                     WIDE_ST(V, oVa0, oVa1, oVb0, oVb1);
	v_sub_f32_e32 v131, v135, v105
	v_med3_f32 v119, v119, s96, v190
	v_med3_f32 v131, v131, s96, v190
	v_mul_f32_e32 v135, 0x3fb8aa3b, v119
	v_mul_f32_e32 v137, 0x3fb8aa3b, v131
	v_mul_f32_e32 v131, 0xbfb8aa3b, v131
	v_add_f32_e32 v87, v87, v109
	v_exp_f32_e32 v135, v135
	v_exp_f32_e32 v137, v137
	v_exp_f32_e32 v131, v131
	v_add_f32_e32 v83, v83, v222
	v_add_f32_e32 v87, v87, v221
	v_sub_f32_e32 v83, v121, v83
	v_add_f32_e32 v83, v218, v83
	v_sub_f32_e32 v87, v87, v101
	v_med3_f32 v87, v87, s96, v190
	v_sub_f32_e32 v83, v83, v105
	v_mul_f32_e32 v117, 0xbfb8aa3b, v117
	v_mul_f32_e32 v135, v89, v135
	v_mul_f32_e32 v89, v89, v137
	v_mul_f32_e32 v137, v214, v131
	v_med3_f32 v83, v83, s96, v190
	v_mul_f32_e32 v131, 0x3fb8aa3b, v87
	v_mul_f32_e32 v86, 0xbfb8aa3b, v86
	v_exp_f32_e32 v117, v117
	v_mul_f32_e32 v116, 0xbfb8aa3b, v116
	v_mul_f32_e32 v91, 0xbfb8aa3b, v91
	v_mul_f32_e32 v95, 0xbfb8aa3b, v95
	v_mul_f32_e32 v119, 0xbfb8aa3b, v119
	v_exp_f32_e32 v131, v131
	v_mul_f32_e32 v87, 0xbfb8aa3b, v87
	v_mul_f32_e32 v139, 0x3fb8aa3b, v83
	v_mul_f32_e32 v83, 0xbfb8aa3b, v83
	v_exp_f32_e32 v86, v86
	v_exp_f32_e32 v116, v116
	v_exp_f32_e32 v91, v91
	v_exp_f32_e32 v95, v95
	v_exp_f32_e32 v119, v119
	v_exp_f32_e32 v87, v87
	v_exp_f32_e32 v139, v139
	v_exp_f32_e32 v83, v83
	v_mov_b32_dpp v113, v221 row_newbcast:15 row_mask:0xf bank_mask:0xf bound_ctrl:1
	v_mul_f32_e32 v117, v141, v117
	v_mul_f32_e32 v141, v85, v131
	v_mul_f32_e32 v86, v155, v86
	v_mul_f32_e32 v116, v151, v116
	v_mul_f32_e32 v91, v208, v91
	v_mul_f32_e32 v95, v209, v95
	v_mul_f32_e32 v119, v213, v119
	v_mul_f32_e32 v87, v219, v87
	v_mul_f32_e32 v85, v85, v139
	v_mul_f32_e32 v83, v220, v83
	v_cvt_pk_bf16_f32 v155, v207, v129
	v_cvt_pk_bf16_f32 v151, v90, v97
	v_cvt_pk_bf16_f32 v147, v133, v118
	v_cvt_pk_bf16_f32 v143, v82, v125
	v_cvt_pk_bf16_f32 v157, v94, v127
	v_cvt_pk_bf16_f32 v153, v92, v93
	v_cvt_pk_bf16_f32 v149, v223, v91
	v_cvt_pk_bf16_f32 v145, v96, v95
	v_cvt_pk_bf16_f32 v131, v224, v135
	v_cvt_pk_bf16_f32 v139, v88, v89
	v_cvt_pk_bf16_f32 v135, v225, v119
	v_cvt_pk_bf16_f32 v127, v117, v137
	v_cvt_pk_bf16_f32 v133, v226, v141
	v_cvt_pk_bf16_f32 v141, v84, v85
	v_cvt_pk_bf16_f32 v137, v86, v87
	v_cvt_pk_bf16_f32 v129, v116, v83
	s_and_saveexec_b64 s[10:11], s[6:7]
	s_cbranch_execz .LBB0_195
	s_ashr_i32 s12, s45, 6
	s_ashr_i32 s13, s12, 31
	s_lshl_b64 s[12:13], s[12:13], 11
	v_lshl_add_u64 v[86:87], v[174:175], 0, s[12:13]
	v_add_co_u32_e32 v82, vcc, 0x110000, v86
	v_pk_add_f32 v[84:85], v[98:99], v[106:107]
	s_nop 0
	v_addc_co_u32_e32 v83, vcc, 0, v87, vcc
	global_store_dwordx4 v[82:83], v[102:105], off
	v_pk_add_f32 v[82:83], v[100:101], v[108:109]
	v_pk_add_f32 v[88:89], v[84:85], v[110:111]
	v_pk_add_f32 v[82:83], v[82:83], v[112:113]
	global_store_dwordx4 v[86:87], v[98:101], off
	v_sub_f32_e32 v84, v82, v100
	v_sub_f32_e32 v82, v88, v98
	v_add_co_u32_e32 v88, vcc, 0x220000, v86
	v_sub_f32_e32 v85, v83, v101
	v_sub_f32_e32 v83, v89, v99
	v_addc_co_u32_e32 v89, vcc, 0, v87, vcc
	v_add_co_u32_e32 v86, vcc, 0x330000, v86
	global_store_dwordx4 v[88:89], v[82:85], off
	s_nop 0
	v_addc_co_u32_e32 v87, vcc, 0, v87, vcc
	v_pk_add_f32 v[82:83], v[114:115], v[102:103] neg_lo:[0,1] neg_hi:[0,1]
	v_pk_add_f32 v[84:85], v[120:121], v[104:105] neg_lo:[0,1] neg_hi:[0,1]
	global_store_dwordx4 v[86:87], v[82:85], off
.LBB0_195:
	s_or_b64 exec, exec, s[10:11]
	s_nop 0
	v_or_b32_e32 v82, v172, v181
	v_sub_u32_e32 v94, v176, v180
	v_ashrrev_i32_e32 v83, 31, v82
	v_ashrrev_i32_e32 v95, 31, v94
	v_lshlrev_b64 v[82:83], 9, v[82:83]
	v_lshl_add_u64 v[82:83], v[82:83], 0, v[94:95]
	v_cvt_pk_bf16_f32 v78, v78, v79
	v_cvt_pk_bf16_f32 v79, v80, v81
	v_cvt_pk_bf16_f32 v80, v74, v75
	v_lshlrev_b64 v[74:75], 1, v[82:83]
	v_cvt_pk_bf16_f32 v81, v76, v77
	v_permlane16_swap_b32_e32 v154, v156
	v_permlane16_swap_b32_e32 v155, v157
	v_lshl_add_u64 v[76:77], s[24:25], 0, v[74:75]
	s_nop 1
	global_store_dwordx4 v[76:77], v[154:157], off
	v_permlane16_swap_b32_e32 v150, v152
	v_permlane16_swap_b32_e32 v151, v153
	v_lshl_add_u64 v[76:77], s[30:31], 0, v[74:75]
	global_store_dwordx4 v[76:77], v[150:153], off
	v_permlane16_swap_b32_e32 v146, v148
	v_permlane16_swap_b32_e32 v147, v149
	v_lshl_add_u64 v[76:77], s[26:27], 0, v[74:75]
	global_store_dwordx4 v[76:77], v[146:149], off
	v_lshl_add_u64 v[76:77], s[34:35], 0, v[74:75]
	v_permlane16_swap_b32_e32 v78, v80
	v_permlane16_swap_b32_e32 v79, v81
	v_lshl_add_u64 v[74:75], s[28:29], 0, v[74:75]
	global_store_dwordx4 v[74:75], v[78:81], off
	v_or_b32_e32 v74, v172, v179
	v_ashrrev_i32_e32 v75, 31, v74
	v_lshlrev_b64 v[74:75], 9, v[74:75]
	v_permlane16_swap_b32_e32 v142, v144
	v_permlane16_swap_b32_e32 v143, v145
	v_lshl_add_u64 v[74:75], v[74:75], 0, v[94:95]
	v_max_f32_e32 v62, 0xc1f00000, v62
	global_store_dwordx4 v[76:77], v[142:145], off
	v_cvt_pk_bf16_f32 v70, v70, v71
	v_cvt_pk_bf16_f32 v71, v72, v73
	v_cvt_pk_bf16_f32 v72, v66, v67
	v_lshlrev_b64 v[66:67], 1, v[74:75]
	v_mul_f32_e32 v62, 0xbfb8aa3b, v62
	v_cvt_pk_bf16_f32 v73, v68, v69
	v_permlane16_swap_b32_e32 v130, v132
	v_permlane16_swap_b32_e32 v131, v133
	v_lshl_add_u64 v[68:69], s[24:25], 0, v[66:67]
	v_exp_f32_e32 v62, v62
	s_nop 1
	global_store_dwordx4 v[68:69], v[130:133], off
	v_permlane16_swap_b32_e32 v138, v140
	v_permlane16_swap_b32_e32 v139, v141
	v_lshl_add_u64 v[68:69], s[30:31], 0, v[66:67]
	global_store_dwordx4 v[68:69], v[138:141], off
	v_permlane16_swap_b32_e32 v134, v136
	v_permlane16_swap_b32_e32 v135, v137
	v_lshl_add_u64 v[68:69], s[26:27], 0, v[66:67]
	global_store_dwordx4 v[68:69], v[134:137], off
	v_permlane16_swap_b32_e32 v126, v128
	v_permlane16_swap_b32_e32 v127, v129
; __device__ __forceinline__ float scan16(float x) { x += dpp_shr<1>(x); x += dpp_shr<2>(x); x += dpp_shr<4>(x); x += dpp_shr<8>(x); return x; }
;     __device__ __forceinline__ void operator()(const f32x4 (&acc)[2][2][4][2], const pg8::Unit& u, int wr, int wc, int fr, int fq) const {
;     ...
;                             { const float z = acc[ai][0][m][1][j]; const float e = __expf(fminf(-z, 30.f)); const float s = __builtin_amdgcn_rcpf(1.f + e); lfF[m] = __logf(lbF[j] + (1.f - lbF[j]) * s); kkF[m] = (1.f - lbF[j]) * e * s; }
;                             { const float z = acc[ai][1][m][0][j]; const float e = __expf(fminf(-z, 30.f)); const float s = __builtin_amdgcn_rcpf(1.f + e); lfB[m] = __logf(lbB[j] + (1.f - lbB[j]) * s); kkB[m] = (1.f - lbB[j]) * e * s; }
;                             pF[m] = scan16(lfF[m]); pB[m] = scan16(lfB[m]);
;                             tF[m] = __int_as_float(__builtin_amdgcn_update_dpp(0, __float_as_int(pF[m]), 0x15F, 0xf, 0xf, true));
;                             tB[m] = __int_as_float(__builtin_amdgcn_update_dpp(0, __float_as_int(pB[m]), 0x15F, 0xf, 0xf, true));
	v_lshl_add_u64 v[68:69], s[34:35], 0, v[66:67]
	global_store_dwordx4 v[68:69], v[126:129], off
	v_add_f32_e32 v68, 1.0, v62
	v_rcp_f32_e32 v68, v68
	v_max_f32_e32 v58, 0xc1f00000, v58
	v_mul_f32_e32 v58, 0xbfb8aa3b, v58
	v_fma_f32 v69, v68, v197, v196
	v_exp_f32_e32 v58, v58
	v_permlane16_swap_b32_e32 v70, v72
	v_log_f32_e32 v69, v69
	v_permlane16_swap_b32_e32 v71, v73
	v_lshl_add_u64 v[66:67], s[28:29], 0, v[66:67]
	global_store_dwordx4 v[66:67], v[70:73], off
	v_add_f32_e32 v67, 1.0, v58
	v_rcp_f32_e32 v67, v67
	s_nop 0
	v_fma_f32 v70, v67, v198, v195
	v_mul_f32_e32 v62, v62, v197
	v_mul_f32_e32 v66, 0x3f317218, v69
	v_mul_f32_e32 v74, v68, v62
	v_log_f32_e32 v70, v70
	v_max_f32_e32 v54, 0xc1f00000, v54
	v_mul_f32_e32 v54, 0xbfb8aa3b, v54
	v_mul_f32_e32 v58, v58, v198
	v_mul_f32_e32 v62, 0x3f317218, v70
	v_mov_b32_e32 v73, v62
	v_exp_f32_e32 v62, v54
	v_mul_f32_e32 v72, v67, v58
	v_add_f32_dpp v58, v66, v66 row_shr:1 row_mask:0xf bank_mask:0xf bound_ctrl:1
	v_max_f32_e32 v50, 0xc1f00000, v50
	s_nop 0
	v_add_f32_dpp v54, v58, v58 row_shr:2 row_mask:0xf bank_mask:0xf bound_ctrl:1
	v_mul_f32_e32 v50, 0xbfb8aa3b, v50
	v_exp_f32_e32 v50, v50
	v_add_f32_dpp v54, v54, v54 row_shr:4 row_mask:0xf bank_mask:0xf bound_ctrl:1
	v_max_f32_e32 v46, 0xc1f00000, v46
	s_nop 0
	v_add_f32_dpp v67, v54, v54 row_shr:8 row_mask:0xf bank_mask:0xf bound_ctrl:1
	v_add_f32_e32 v54, 1.0, v62
	v_rcp_f32_e32 v66, v54
	v_add_f32_e32 v71, 1.0, v50
	v_rcp_f32_e32 v71, v71
	v_mul_f32_e32 v62, v62, v197
	v_fma_f32 v58, v66, v197, v196
	v_fma_f32 v75, v71, v198, v195
	v_mul_f32_e32 v77, v66, v62
	v_log_f32_e32 v68, v58
	v_mul_f32_e32 v46, 0xbfb8aa3b, v46
	v_exp_f32_e32 v46, v46
	v_mul_f32_e32 v50, v50, v198
	v_max_f32_e32 v42, 0xc1f00000, v42
	v_mul_f32_e32 v68, 0x3f317218, v68
	v_mul_f32_e32 v42, 0xbfb8aa3b, v42
	v_log_f32_e32 v75, v75
	v_exp_f32_e32 v42, v42
	s_nop 0
	v_add_f32_e32 v79, 1.0, v42
	v_rcp_f32_e32 v79, v79
	v_mul_f32_e32 v62, 0x3f317218, v75
	v_mov_b32_e32 v76, v62
	v_add_f32_e32 v62, 1.0, v46
	v_mul_f32_e32 v75, v71, v50
	v_add_f32_dpp v50, v68, v68 row_shr:1 row_mask:0xf bank_mask:0xf bound_ctrl:1
	v_rcp_f32_e32 v68, v62
	v_fma_f32 v80, v79, v198, v195
	v_max_f32_e32 v38, 0xc1f00000, v38
	v_mul_f32_e32 v46, v46, v197
	v_fma_f32 v66, v68, v197, v196
	v_mul_f32_e32 v38, 0xbfb8aa3b, v38
	v_mul_f32_e32 v42, v42, v198
	v_log_f32_e32 v70, v66
	v_exp_f32_e32 v38, v38
	v_mul_f32_e32 v79, v79, v42
	v_max_f32_e32 v34, 0xc1f00000, v34
	v_mul_f32_e32 v34, 0xbfb8aa3b, v34
	v_mul_f32_e32 v70, 0x3f317218, v70
	v_exp_f32_e32 v34, v34
	v_log_f32_e32 v80, v80
	v_mul_f32_e32 v81, v68, v46
	v_add_f32_dpp v42, v70, v70 row_shr:1 row_mask:0xf bank_mask:0xf bound_ctrl:1
	s_nop 1
	v_add_f32_dpp v42, v42, v42 row_shr:2 row_mask:0xf bank_mask:0xf bound_ctrl:1
	s_nop 1
	v_add_f32_dpp v42, v42, v42 row_shr:4 row_mask:0xf bank_mask:0xf bound_ctrl:1
	v_add_f32_e32 v84, 1.0, v34
	v_mul_f32_e32 v46, 0x3f317218, v80
	v_add_f32_dpp v82, v42, v42 row_shr:8 row_mask:0xf bank_mask:0xf bound_ctrl:1
	v_add_f32_e32 v42, 1.0, v38
	v_mov_b32_e32 v80, v46
	v_rcp_f32_e32 v46, v42
	v_rcp_f32_e32 v84, v84
	v_mul_f32_e32 v38, v38, v197
	v_mul_f32_e32 v34, v34, v198
	v_fmac_f32_e32 v196, v46, v197
	v_fmac_f32_e32 v195, v84, v198
	v_mul_f32_e32 v38, v46, v38
	v_log_f32_e32 v68, v196
	v_mul_f32_e32 v84, v84, v34
	v_max_f32_e32 v59, 0xc1f00000, v59
	v_mul_f32_e32 v59, 0xbfb8aa3b, v59
	v_add_f32_dpp v54, v73, v73 row_shr:1 row_mask:0xf bank_mask:0xf bound_ctrl:1
	v_mul_f32_e32 v68, 0x3f317218, v68
	v_exp_f32_e32 v59, v59
	v_log_f32_e32 v85, v195
	v_add_f32_dpp v34, v68, v68 row_shr:1 row_mask:0xf bank_mask:0xf bound_ctrl:1
	v_add_f32_dpp v54, v54, v54 row_shr:2 row_mask:0xf bank_mask:0xf bound_ctrl:1
	s_nop 0
	v_add_f32_dpp v34, v34, v34 row_shr:2 row_mask:0xf bank_mask:0xf bound_ctrl:1
	v_add_f32_dpp v54, v54, v54 row_shr:4 row_mask:0xf bank_mask:0xf bound_ctrl:1
	v_mul_f32_e32 v46, 0x3f317218, v85
	v_mov_b32_e32 v85, v46
	v_max_f32_e32 v46, 0xc1f00000, v63
	v_mul_f32_e32 v46, 0xbfb8aa3b, v46
	v_exp_f32_e32 v63, v46
	v_add_f32_dpp v34, v34, v34 row_shr:4 row_mask:0xf bank_mask:0xf bound_ctrl:1
	v_add_f32_dpp v69, v54, v54 row_shr:8 row_mask:0xf bank_mask:0xf bound_ctrl:1
	v_add_f32_e32 v89, 0, v69
	v_add_f32_e32 v46, 1.0, v63
	v_rcp_f32_e32 v71, v46
	v_add_f32_dpp v86, v34, v34 row_shr:8 row_mask:0xf bank_mask:0xf bound_ctrl:1
	v_add_f32_dpp v34, v85, v85 row_shr:1 row_mask:0xf bank_mask:0xf bound_ctrl:1
	v_mov_b32_dpp v54, v69 row_newbcast:15 row_mask:0xf bank_mask:0xf bound_ctrl:1
	v_add_f32_e32 v69, 1.0, v59
	v_add_f32_dpp v34, v34, v34 row_shr:2 row_mask:0xf bank_mask:0xf bound_ctrl:1
	v_rcp_f32_e32 v69, v69
	v_mov_b32_dpp v58, v67 row_newbcast:15 row_mask:0xf bank_mask:0xf bound_ctrl:1
	v_add_f32_dpp v34, v34, v34 row_shr:4 row_mask:0xf bank_mask:0xf bound_ctrl:1
	v_add_f32_e32 v88, 0, v67
	v_fma_f32 v90, v69, v200, v193
	v_add_f32_dpp v87, v34, v34 row_shr:8 row_mask:0xf bank_mask:0xf bound_ctrl:1
	v_fma_f32 v34, v71, v199, v194
	v_mul_f32_e32 v63, v63, v199
	v_log_f32_e32 v34, v34
	v_max_f32_e32 v55, 0xc1f00000, v55
	v_mul_f32_e32 v55, 0xbfb8aa3b, v55
	v_mul_f32_e32 v59, v59, v200
	v_mul_f32_e32 v92, v69, v59
	v_mul_f32_e32 v34, 0x3f317218, v34
	v_max_f32_e32 v51, 0xc1f00000, v51
	v_log_f32_e32 v90, v90
	v_mul_f32_e32 v91, v71, v63
	v_add_f32_dpp v34, v34, v34 row_shr:1 row_mask:0xf bank_mask:0xf bound_ctrl:1
	s_nop 1
	v_add_f32_dpp v34, v34, v34 row_shr:2 row_mask:0xf bank_mask:0xf bound_ctrl:1
	v_mul_f32_e32 v51, 0xbfb8aa3b, v51
	v_mul_f32_e32 v63, 0x3f317218, v90
	v_mov_b32_e32 v90, v63
	v_exp_f32_e32 v63, v55
	v_add_f32_dpp v34, v34, v34 row_shr:4 row_mask:0xf bank_mask:0xf bound_ctrl:1
; __device__ __forceinline__ float scan16(float x) { x += dpp_shr<1>(x); x += dpp_shr<2>(x); x += dpp_shr<4>(x); x += dpp_shr<8>(x); return x; }
;     __device__ __forceinline__ void operator()(const f32x4 (&acc)[2][2][4][2], const pg8::Unit& u, int wr, int wc, int fr, int fq) const {
;     ...
;                             { const float z = acc[ai][0][m][1][j]; const float e = __expf(fminf(-z, 30.f)); const float s = __builtin_amdgcn_rcpf(1.f + e); lfF[m] = __logf(lbF[j] + (1.f - lbF[j]) * s); kkF[m] = (1.f - lbF[j]) * e * s; }
;                             { const float z = acc[ai][1][m][0][j]; const float e = __expf(fminf(-z, 30.f)); const float s = __builtin_amdgcn_rcpf(1.f + e); lfB[m] = __logf(lbB[j] + (1.f - lbB[j]) * s); kkB[m] = (1.f - lbB[j]) * e * s; }
;                             pF[m] = scan16(lfF[m]); pB[m] = scan16(lfB[m]);
;                             tF[m] = __int_as_float(__builtin_amdgcn_update_dpp(0, __float_as_int(pF[m]), 0x15F, 0xf, 0xf, true));
;                             tB[m] = __int_as_float(__builtin_amdgcn_update_dpp(0, __float_as_int(pB[m]), 0x15F, 0xf, 0xf, true));
	v_exp_f32_e32 v51, v51
	s_nop 0
	v_add_f32_dpp v93, v34, v34 row_shr:8 row_mask:0xf bank_mask:0xf bound_ctrl:1
	v_add_f32_e32 v34, 1.0, v63
	v_rcp_f32_e32 v34, v34
	v_add_f32_e32 v71, 1.0, v51
	v_rcp_f32_e32 v71, v71
	v_mul_f32_e32 v63, v63, v199
	v_fma_f32 v59, v34, v199, v194
	v_fma_f32 v97, v71, v200, v193
	v_max_f32_e32 v47, 0xc1f00000, v47
	v_log_f32_e32 v67, v59
	v_mul_f32_e32 v47, 0xbfb8aa3b, v47
	v_exp_f32_e32 v47, v47
	v_max_f32_e32 v43, 0xc1f00000, v43
	v_mul_f32_e32 v43, 0xbfb8aa3b, v43
	v_mul_f32_e32 v67, 0x3f317218, v67
	v_exp_f32_e32 v43, v43
	v_log_f32_e32 v97, v97
	v_mul_f32_e32 v98, v34, v63
	v_max_f32_e32 v39, 0xc1f00000, v39
	v_mul_f32_e32 v39, 0xbfb8aa3b, v39
	v_mul_f32_e32 v34, 0x3f317218, v97
	v_mov_b32_e32 v97, v34
	v_mul_f32_e32 v34, v51, v200
	v_mul_f32_e32 v99, v71, v34
	v_add_f32_dpp v51, v97, v97 row_shr:1 row_mask:0xf bank_mask:0xf bound_ctrl:1
	v_add_f32_dpp v34, v67, v67 row_shr:1 row_mask:0xf bank_mask:0xf bound_ctrl:1
	v_add_f32_e32 v71, 1.0, v43
	v_add_f32_dpp v51, v51, v51 row_shr:2 row_mask:0xf bank_mask:0xf bound_ctrl:1
	v_add_f32_dpp v34, v34, v34 row_shr:2 row_mask:0xf bank_mask:0xf bound_ctrl:1
	v_rcp_f32_e32 v71, v71
	v_add_f32_dpp v51, v51, v51 row_shr:4 row_mask:0xf bank_mask:0xf bound_ctrl:1
	v_add_f32_dpp v34, v34, v34 row_shr:4 row_mask:0xf bank_mask:0xf bound_ctrl:1
	v_exp_f32_e32 v39, v39
	v_add_f32_dpp v101, v51, v51 row_shr:8 row_mask:0xf bank_mask:0xf bound_ctrl:1
	v_add_f32_dpp v100, v34, v34 row_shr:8 row_mask:0xf bank_mask:0xf bound_ctrl:1
	v_add_f32_e32 v34, 1.0, v47
	v_rcp_f32_e32 v34, v34
	v_fma_f32 v102, v71, v200, v193
	v_mul_f32_e32 v47, v47, v199
	v_fma_f32 v63, v34, v199, v194
	v_max_f32_e32 v35, 0xc1f00000, v35
	v_mul_f32_e32 v35, 0xbfb8aa3b, v35
	v_log_f32_e32 v69, v63
	v_exp_f32_e32 v35, v35
	v_add_f32_dpp v50, v50, v50 row_shr:2 row_mask:0xf bank_mask:0xf bound_ctrl:1
	v_mov_b32_dpp v59, v93 row_newbcast:15 row_mask:0xf bank_mask:0xf bound_ctrl:1
	s_nop 0
	v_add_f32_dpp v50, v50, v50 row_shr:4 row_mask:0xf bank_mask:0xf bound_ctrl:1
	v_mov_b32_dpp v67, v100 row_newbcast:15 row_mask:0xf bank_mask:0xf bound_ctrl:1
	v_mul_f32_e32 v51, 0x3f317218, v69
	v_add_f32_dpp v50, v50, v50 row_shr:8 row_mask:0xf bank_mask:0xf bound_ctrl:1
	v_log_f32_e32 v102, v102
	v_mul_f32_e32 v103, v34, v47
	v_mov_b32_dpp v66, v50 row_newbcast:15 row_mask:0xf bank_mask:0xf bound_ctrl:1
	v_add_f32_dpp v42, v80, v80 row_shr:1 row_mask:0xf bank_mask:0xf bound_ctrl:1
	v_add_f32_dpp v62, v76, v76 row_shr:1 row_mask:0xf bank_mask:0xf bound_ctrl:1
	v_mul_f32_e32 v34, 0x3f317218, v102
	v_mov_b32_e32 v102, v34
	v_mul_f32_e32 v34, v43, v200
	v_mul_f32_e32 v104, v71, v34
	v_add_f32_e32 v71, 1.0, v35
	v_add_f32_dpp v34, v51, v51 row_shr:1 row_mask:0xf bank_mask:0xf bound_ctrl:1
	v_rcp_f32_e32 v71, v71
	v_add_f32_dpp v42, v42, v42 row_shr:2 row_mask:0xf bank_mask:0xf bound_ctrl:1
	v_add_f32_dpp v34, v34, v34 row_shr:2 row_mask:0xf bank_mask:0xf bound_ctrl:1
	v_add_f32_dpp v43, v102, v102 row_shr:1 row_mask:0xf bank_mask:0xf bound_ctrl:1
	v_fmac_f32_e32 v193, v71, v200
	v_add_f32_dpp v34, v34, v34 row_shr:4 row_mask:0xf bank_mask:0xf bound_ctrl:1
	v_add_f32_dpp v42, v42, v42 row_shr:4 row_mask:0xf bank_mask:0xf bound_ctrl:1
	v_add_f32_dpp v55, v90, v90 row_shr:1 row_mask:0xf bank_mask:0xf bound_ctrl:1
	v_add_f32_dpp v105, v34, v34 row_shr:8 row_mask:0xf bank_mask:0xf bound_ctrl:1
	v_add_f32_e32 v34, 1.0, v39
	v_rcp_f32_e32 v34, v34
	v_mul_f32_e32 v39, v39, v199
	v_add_f32_dpp v83, v42, v42 row_shr:8 row_mask:0xf bank_mask:0xf bound_ctrl:1
	v_mov_b32_dpp v42, v82 row_newbcast:15 row_mask:0xf bank_mask:0xf bound_ctrl:1
	v_fmac_f32_e32 v194, v34, v199
	v_mul_f32_e32 v108, v34, v39
	v_add_f32_dpp v43, v43, v43 row_shr:2 row_mask:0xf bank_mask:0xf bound_ctrl:1
	v_log_f32_e32 v47, v194
	v_add_f32_dpp v62, v62, v62 row_shr:2 row_mask:0xf bank_mask:0xf bound_ctrl:1
	v_add_f32_dpp v55, v55, v55 row_shr:2 row_mask:0xf bank_mask:0xf bound_ctrl:1
	v_add_f32_dpp v43, v43, v43 row_shr:4 row_mask:0xf bank_mask:0xf bound_ctrl:1
	v_add_f32_dpp v62, v62, v62 row_shr:4 row_mask:0xf bank_mask:0xf bound_ctrl:1
	v_add_f32_dpp v55, v55, v55 row_shr:4 row_mask:0xf bank_mask:0xf bound_ctrl:1
	v_mul_f32_e32 v47, 0x3f317218, v47
	v_add_f32_dpp v106, v43, v43 row_shr:8 row_mask:0xf bank_mask:0xf bound_ctrl:1
	v_log_f32_e32 v107, v193
	v_add_f32_dpp v78, v62, v62 row_shr:8 row_mask:0xf bank_mask:0xf bound_ctrl:1
	v_mov_b32_dpp v70, v83 row_newbcast:15 row_mask:0xf bank_mask:0xf bound_ctrl:1
	v_mov_b32_dpp v68, v87 row_newbcast:15 row_mask:0xf bank_mask:0xf bound_ctrl:1
	v_add_f32_dpp v96, v55, v55 row_shr:8 row_mask:0xf bank_mask:0xf bound_ctrl:1
	v_mul_f32_e32 v34, 0x3f317218, v107
	v_mov_b32_e32 v107, v34
	v_mul_f32_e32 v34, v35, v200
	v_mul_f32_e32 v109, v71, v34
	v_mov_b32_dpp v69, v106 row_newbcast:15 row_mask:0xf bank_mask:0xf bound_ctrl:1
	v_add_f32_dpp v34, v47, v47 row_shr:1 row_mask:0xf bank_mask:0xf bound_ctrl:1
	v_mov_b32_dpp v62, v78 row_newbcast:15 row_mask:0xf bank_mask:0xf bound_ctrl:1
	v_mov_b32_dpp v55, v96 row_newbcast:15 row_mask:0xf bank_mask:0xf bound_ctrl:1
	v_add_f32_dpp v34, v34, v34 row_shr:2 row_mask:0xf bank_mask:0xf bound_ctrl:1
	v_mov_b32_dpp v63, v101 row_newbcast:15 row_mask:0xf bank_mask:0xf bound_ctrl:1
	v_mov_b32_dpp v43, v105 row_newbcast:15 row_mask:0xf bank_mask:0xf bound_ctrl:1
	v_add_f32_dpp v34, v34, v34 row_shr:4 row_mask:0xf bank_mask:0xf bound_ctrl:1
	v_mov_b32_dpp v46, v86 row_newbcast:15 row_mask:0xf bank_mask:0xf bound_ctrl:1
	s_nop 0
	v_add_f32_dpp v110, v34, v34 row_shr:8 row_mask:0xf bank_mask:0xf bound_ctrl:1
	v_add_f32_dpp v34, v107, v107 row_shr:1 row_mask:0xf bank_mask:0xf bound_ctrl:1
; __device__ __forceinline__ float clamp80(float x) { return fminf(fmaxf(x, -80.f), 80.f); }
;     __device__ __forceinline__ void operator()(const f32x4 (&acc)[2][2][4][2], const pg8::Unit& u, int wr, int wc, int fr, int fq) const {
;     ...
;                         const float rF = tF[0] + tF[1], blF = rF + tF[2] + tF[3];
;                         const float rB = tB[2] + tB[3], blB = rB + tB[0] + tB[1];
;                         float cF = 0.f, cB = 0.f;
; #pragma unroll
;                         for (int m = 0; m < 4; ++m) {
;                             const float bF = pF[m] + cF; cF += tF[m];
;                             const float bB = blB - (pB[m] + cB) + lfB[m]; cB += tB[m];
;                             const float xF = clamp80(bF - rF), xB = clamp80(bB - rB);
;                             const float q = acc[ai][0][m][0][j];
;                             vQF[m][jj] = q * __expf(xF); vKF[m][jj] = kkF[m] * __expf(-xF);
;                             vQB[m][jj] = q * __expf(xB); vKB[m][jj] = kkB[m] * __expf(-xB);
;                         }
	v_max_f32_e32 v52, 0xc1f00000, v52
	v_mul_f32_e32 v52, 0xbfb8aa3b, v52
	v_add_f32_dpp v34, v34, v34 row_shr:2 row_mask:0xf bank_mask:0xf bound_ctrl:1
	v_exp_f32_e32 v52, v52
	s_nop 0
	v_add_f32_dpp v34, v34, v34 row_shr:4 row_mask:0xf bank_mask:0xf bound_ctrl:1
	v_max_f32_e32 v44, 0xc1f00000, v44
	v_mul_f32_e32 v44, 0xbfb8aa3b, v44
	v_add_f32_dpp v111, v34, v34 row_shr:8 row_mask:0xf bank_mask:0xf bound_ctrl:1
	v_pk_add_f32 v[34:35], v[58:59], v[66:67]
	v_add_f32_e32 v58, 0, v58
	v_sub_f32_e32 v39, v88, v34
	v_med3_f32 v39, v39, s96, v190
	v_mul_f32_e32 v47, 0x3fb8aa3b, v39
	v_exp_f32_e32 v51, v47
	v_add_f32_e32 v50, v58, v50
	v_sub_f32_e32 v50, v50, v34
	v_mul_f32_e32 v39, 0xbfb8aa3b, v39
	v_med3_f32 v50, v50, s96, v190
	v_mul_f32_e32 v88, v30, v51
	v_exp_f32_e32 v39, v39
	v_mul_f32_e32 v51, 0x3fb8aa3b, v50
	v_mul_f32_e32 v50, 0xbfb8aa3b, v50
	v_exp_f32_e32 v50, v50
	v_mul_f32_e32 v74, v74, v39
	v_add_f32_e32 v39, v58, v66
	v_exp_f32_e32 v51, v51
	v_mul_f32_e32 v66, v77, v50
	v_add_f32_e32 v50, v39, v82
	v_add_f32_e32 v39, v39, v42
	v_add_f32_e32 v39, v39, v86
	v_sub_f32_e32 v50, v50, v34
	v_sub_f32_e32 v39, v39, v34
	v_med3_f32 v50, v50, s96, v190
	v_med3_f32 v39, v39, s96, v190
	v_mul_f32_e32 v58, v26, v51
	v_mul_f32_e32 v51, 0x3fb8aa3b, v50
	v_mul_f32_e32 v50, 0xbfb8aa3b, v50
	v_mul_f32_e32 v77, 0x3fb8aa3b, v39
	v_mul_f32_e32 v39, 0xbfb8aa3b, v39
	v_exp_f32_e32 v50, v50
	v_exp_f32_e32 v39, v39
	v_exp_f32_e32 v51, v51
	v_mov_b32_dpp v71, v111 row_newbcast:15 row_mask:0xf bank_mask:0xf bound_ctrl:1
	v_mul_f32_e32 v81, v81, v50
	v_mul_f32_e32 v113, v38, v39
	v_pk_add_f32 v[38:39], v[68:69], v[70:71]
	v_add_f32_e32 v50, 0, v54
	v_mul_f32_e32 v112, v22, v51
	v_add_f32_e32 v68, v50, v78
	v_add_f32_e32 v71, v50, v62
	v_pk_add_f32 v[50:51], v[38:39], v[54:55]
	v_add_f32_e32 v70, v71, v70
	v_pk_add_f32 v[50:51], v[50:51], v[62:63]
	v_add_f32_e32 v70, v70, v87
	v_sub_f32_e32 v54, v50, v89
	v_sub_f32_e32 v68, v50, v68
	v_add_f32_e32 v54, v73, v54
	v_add_f32_e32 v68, v76, v68
	v_sub_f32_e32 v54, v54, v38
	v_sub_f32_e32 v68, v68, v38
	v_med3_f32 v54, v54, s96, v190
	v_med3_f32 v68, v68, s96, v190
	v_mul_f32_e32 v62, 0x3fb8aa3b, v54
	v_mul_f32_e32 v73, 0x3fb8aa3b, v68
	v_mul_f32_e32 v68, 0xbfb8aa3b, v68
	v_exp_f32_e32 v62, v62
	v_exp_f32_e32 v68, v68
	v_mul_f32_e32 v54, 0xbfb8aa3b, v54
	v_exp_f32_e32 v54, v54
	v_sub_f32_e32 v70, v50, v70
	v_add_f32_e32 v78, v71, v83
	v_add_f32_e32 v70, v85, v70
	v_mul_f32_e32 v30, v30, v62
	v_mul_f32_e32 v62, v75, v68
	v_sub_f32_e32 v68, v50, v78
	v_sub_f32_e32 v70, v70, v38
	v_add_f32_e32 v68, v80, v68
	v_med3_f32 v70, v70, s96, v190
	v_mul_f32_e32 v54, v72, v54
	v_sub_f32_e32 v68, v68, v38
	v_mul_f32_e32 v72, 0x3fb8aa3b, v70
	v_exp_f32_e32 v77, v77
	v_med3_f32 v68, v68, s96, v190
	v_exp_f32_e32 v72, v72
	v_mul_f32_e32 v71, 0x3fb8aa3b, v68
	v_mul_f32_e32 v70, 0xbfb8aa3b, v70
	v_exp_f32_e32 v71, v71
	v_exp_f32_e32 v70, v70
	v_mul_f32_e32 v77, v18, v77
	v_mul_f32_e32 v18, v18, v72
	v_add_f32_e32 v72, 0, v96
	v_exp_f32_e32 v73, v73
	v_sub_f32_e32 v72, v51, v72
	v_mul_f32_e32 v22, v22, v71
	v_mul_f32_e32 v71, v84, v70
	v_add_f32_e32 v70, 0, v93
	v_add_f32_e32 v72, v90, v72
	v_sub_f32_e32 v70, v70, v35
	v_sub_f32_e32 v72, v72, v39
	v_med3_f32 v70, v70, s96, v190
	v_med3_f32 v72, v72, s96, v190
	v_mul_f32_e32 v26, v26, v73
	v_mul_f32_e32 v73, 0x3fb8aa3b, v70
	v_mul_f32_e32 v75, 0x3fb8aa3b, v72
	v_exp_f32_e32 v73, v73
	v_exp_f32_e32 v75, v75
	v_add_f32_e32 v59, 0, v59
	v_add_f32_e32 v55, 0, v55
	v_mul_f32_e32 v73, v31, v73
	v_mul_f32_e32 v31, v31, v75
	v_add_f32_e32 v75, v59, v100
	v_add_f32_e32 v59, v59, v67
	v_add_f32_e32 v67, v55, v101
	v_sub_f32_e32 v67, v51, v67
	v_add_f32_e32 v67, v97, v67
	v_add_f32_e32 v55, v55, v63
	v_sub_f32_e32 v63, v75, v35
	v_sub_f32_e32 v67, v67, v39
	v_med3_f32 v63, v63, s96, v190
	v_med3_f32 v67, v67, s96, v190
	v_mul_f32_e32 v75, 0x3fb8aa3b, v63
	v_mul_f32_e32 v76, 0x3fb8aa3b, v67
	v_exp_f32_e32 v75, v75
	v_exp_f32_e32 v76, v76
	v_add_f32_e32 v78, v55, v106
	v_sub_f32_e32 v78, v51, v78
	v_mul_f32_e32 v75, v27, v75
	v_mul_f32_e32 v27, v27, v76
	v_add_f32_e32 v76, v59, v105
	v_add_f32_e32 v55, v55, v69
	v_sub_f32_e32 v69, v76, v35
	v_add_f32_e32 v78, v102, v78
	v_med3_f32 v69, v69, s96, v190
	v_sub_f32_e32 v76, v78, v39
	v_mul_f32_e32 v78, 0x3fb8aa3b, v69
	v_add_f32_e32 v59, v59, v43
	v_exp_f32_e32 v78, v78
	v_add_f32_e32 v59, v59, v110
	v_sub_f32_e32 v59, v59, v35
	v_med3_f32 v59, v59, s96, v190
	v_mul_f32_e32 v68, 0xbfb8aa3b, v68
	v_mul_f32_e32 v70, 0xbfb8aa3b, v70
	v_mul_f32_e32 v72, 0xbfb8aa3b, v72
	v_mul_f32_e32 v83, v23, v78
	v_mul_f32_e32 v78, 0x3fb8aa3b, v59
	v_exp_f32_e32 v68, v68
	v_exp_f32_e32 v70, v70
	v_exp_f32_e32 v72, v72
	v_exp_f32_e32 v78, v78
	v_med3_f32 v76, v76, s96, v190
	v_mul_f32_e32 v68, v79, v68
	v_mul_f32_e32 v70, v91, v70
	v_mul_f32_e32 v72, v92, v72
	v_mul_f32_e32 v79, 0x3fb8aa3b, v76
	v_add_f32_e32 v55, v55, v111
	v_mul_f32_e32 v85, v19, v78
	v_cvt_pk_bf16_f32 v90, v88, v73
	v_cvt_pk_bf16_f32 v86, v30, v31
	v_cvt_pk_bf16_f32 v82, v74, v70
	v_cvt_pk_bf16_f32 v78, v54, v72
	v_cvt_pk_bf16_f32 v92, v58, v75
	v_cvt_pk_bf16_f32 v88, v26, v27
	v_exp_f32_e32 v79, v79
	v_sub_f32_e32 v55, v51, v55
	v_max_f32_e32 v26, 0xc1f00000, v64
	v_mul_f32_e32 v63, 0xbfb8aa3b, v63
	v_mul_f32_e32 v67, 0xbfb8aa3b, v67
	v_add_f32_e32 v55, v107, v55
	v_mul_f32_e32 v26, 0xbfb8aa3b, v26
	v_exp_f32_e32 v63, v63
	v_exp_f32_e32 v67, v67
	v_sub_f32_e32 v55, v55, v39
	v_exp_f32_e32 v26, v26
	v_med3_f32 v55, v55, s96, v190
	v_mul_f32_e32 v76, 0xbfb8aa3b, v76
	v_mul_f32_e32 v23, v23, v79
	v_mul_f32_e32 v79, 0x3fb8aa3b, v55
	v_mul_f32_e32 v69, 0xbfb8aa3b, v69
	v_exp_f32_e32 v76, v76
; __device__ __forceinline__ unsigned cvt_pk_bf16(float lo, float hi) { unsigned r; asm volatile("v_cvt_pk_bf16_f32 %0, %1, %2" : "=v"(r) : "v"(lo), "v"(hi)); return r; }
;     __device__ __forceinline__ void operator()(const f32x4 (&acc)[2][2][4][2], const pg8::Unit& u, int wr, int wc, int fr, int fq) const {
;     ...
;                             { const float z = acc[ai][0][m][1][j]; const float e = __expf(fminf(-z, 30.f)); const float s = __builtin_amdgcn_rcpf(1.f + e); lfF[m] = __logf(lbF[j] + (1.f - lbF[j]) * s); kkF[m] = (1.f - lbF[j]) * e * s; }
;                             { const float z = acc[ai][1][m][0][j]; const float e = __expf(fminf(-z, 30.f)); const float s = __builtin_amdgcn_rcpf(1.f + e); lfB[m] = __logf(lbB[j] + (1.f - lbB[j]) * s); kkB[m] = (1.f - lbB[j]) * e * s; }
;                             pF[m] = scan16(lfF[m]); pB[m] = scan16(lfB[m]);
;                             tF[m] = __int_as_float(__builtin_amdgcn_update_dpp(0, __float_as_int(pF[m]), 0x15F, 0xf, 0xf, true));
;                             tB[m] = __int_as_float(__builtin_amdgcn_update_dpp(0, __float_as_int(pB[m]), 0x15F, 0xf, 0xf, true));
;                         }
;                         const float rF = tF[0] + tF[1], blF = rF + tF[2] + tF[3];
;                         const float rB = tB[2] + tB[3], blB = rB + tB[0] + tB[1];
;                         float cF = 0.f, cB = 0.f;
; #pragma unroll
;                         for (int m = 0; m < 4; ++m) {
;                             const float bF = pF[m] + cF; cF += tF[m];
;                             const float bB = blB - (pB[m] + cB) + lfB[m]; cB += tB[m];
;                             const float xF = clamp80(bF - rF), xB = clamp80(bB - rB);
;                             const float q = acc[ai][0][m][0][j];
;                             vQF[m][jj] = q * __expf(xF); vKF[m][jj] = kkF[m] * __expf(-xF);
;                             vQB[m][jj] = q * __expf(xB); vKB[m][jj] = kkB[m] * __expf(-xB);
;                         }
;                         rtv[0][j] = rF; rtv[1][j] = rB; rtv[2][j] = blF - rF; rtv[3][j] = blB - rB;
;                     }
; #pragma unroll
;                     for (int m = 0; m < 4; ++m) { oQF[m][jp] = cvt_pk_bf16(vQF[m][0], vQF[m][1]); oQB[m][jp] = cvt_pk_bf16(vQB[m][0], vQB[m][1]); oKF[m][jp] = cvt_pk_bf16(vKF[m][0], vKF[m][1]); oKB[m][jp] = cvt_pk_bf16(vKB[m][0], vKB[m][1]); }
	v_exp_f32_e32 v79, v79
	v_mul_f32_e32 v63, v98, v63
	v_mul_f32_e32 v67, v99, v67
	v_exp_f32_e32 v69, v69
	v_cvt_pk_bf16_f32 v84, v66, v63
	v_cvt_pk_bf16_f32 v80, v62, v67
	v_cvt_pk_bf16_f32 v74, v112, v83
	v_cvt_pk_bf16_f32 v70, v22, v23
	v_add_f32_e32 v22, 1.0, v26
	v_rcp_f32_e32 v22, v22
	v_mul_f32_e32 v76, v104, v76
	v_mul_f32_e32 v19, v19, v79
	v_mul_f32_e32 v69, v103, v69
	v_cvt_pk_bf16_f32 v66, v81, v69
	v_cvt_pk_bf16_f32 v62, v68, v76
	v_cvt_pk_bf16_f32 v76, v77, v85
	v_cvt_pk_bf16_f32 v72, v18, v19
	v_fma_f32 v23, v22, v122, v177
	v_max_f32_e32 v19, 0xc1f00000, v60
	v_mul_f32_e32 v19, 0xbfb8aa3b, v19
	v_exp_f32_e32 v19, v19
	v_log_f32_e32 v23, v23
	v_add_f32_e32 v27, 1.0, v19
	v_rcp_f32_e32 v27, v27
	v_mul_f32_e32 v19, v19, v123
	v_fma_f32 v30, v27, v123, v192
	v_mul_f32_e32 v58, v27, v19
	v_mul_f32_e32 v18, 0x3f317218, v23
	v_mul_f32_e32 v59, 0xbfb8aa3b, v59
	v_log_f32_e32 v30, v30
	v_mul_f32_e32 v23, v26, v122
	v_max_f32_e32 v19, 0xc1f00000, v56
	v_exp_f32_e32 v59, v59
	v_mul_f32_e32 v60, v22, v23
	v_mul_f32_e32 v19, 0xbfb8aa3b, v19
	v_exp_f32_e32 v19, v19
	v_add_f32_dpp v18, v18, v18 row_shr:1 row_mask:0xf bank_mask:0xf bound_ctrl:1
	s_nop 1
	v_add_f32_dpp v18, v18, v18 row_shr:2 row_mask:0xf bank_mask:0xf bound_ctrl:1
	v_mul_f32_e32 v59, v108, v59
	v_mul_f32_e32 v22, 0x3f317218, v30
	v_add_f32_dpp v18, v18, v18 row_shr:4 row_mask:0xf bank_mask:0xf bound_ctrl:1
	v_cvt_pk_bf16_f32 v68, v113, v59
	v_mov_b32_e32 v59, v22
	v_mul_f32_e32 v55, 0xbfb8aa3b, v55
	v_add_f32_dpp v23, v18, v18 row_shr:8 row_mask:0xf bank_mask:0xf bound_ctrl:1
	v_add_f32_e32 v18, 1.0, v19
	v_rcp_f32_e32 v26, v18
	v_exp_f32_e32 v55, v55
	v_add_f32_e32 v54, 1.0, v52
	v_rcp_f32_e32 v54, v54
	v_fma_f32 v22, v26, v122, v177
	v_mul_f32_e32 v55, v109, v55
	v_cvt_pk_bf16_f32 v64, v71, v55
	v_fma_f32 v55, v54, v123, v192
	v_log_f32_e32 v27, v22
	v_mul_f32_e32 v19, v19, v122
	v_exp_f32_e32 v44, v44
	v_max_f32_e32 v36, 0xc1f00000, v36
	v_mul_f32_e32 v36, 0xbfb8aa3b, v36
	v_mul_f32_e32 v27, 0x3f317218, v27
	v_exp_f32_e32 v36, v36
	v_log_f32_e32 v55, v55
	v_mul_f32_e32 v56, v26, v19
	v_add_f32_dpp v18, v59, v59 row_shr:1 row_mask:0xf bank_mask:0xf bound_ctrl:1
	s_nop 1
	v_add_f32_dpp v18, v18, v18 row_shr:2 row_mask:0xf bank_mask:0xf bound_ctrl:1
	v_mov_b32_dpp v22, v23 row_newbcast:15 row_mask:0xf bank_mask:0xf bound_ctrl:1
	v_mul_f32_e32 v19, 0x3f317218, v55
	v_mov_b32_e32 v67, v19
	v_max_f32_e32 v26, 0xc1f00000, v48
	v_mul_f32_e32 v26, 0xbfb8aa3b, v26
	v_mul_f32_e32 v19, v52, v123
	v_exp_f32_e32 v26, v26
	v_mul_f32_e32 v63, v54, v19
	v_add_f32_dpp v19, v27, v27 row_shr:1 row_mask:0xf bank_mask:0xf bound_ctrl:1
	v_add_f32_dpp v27, v67, v67 row_shr:1 row_mask:0xf bank_mask:0xf bound_ctrl:1
	v_add_f32_e32 v54, 1.0, v44
	v_add_f32_dpp v19, v19, v19 row_shr:2 row_mask:0xf bank_mask:0xf bound_ctrl:1
	v_add_f32_dpp v27, v27, v27 row_shr:2 row_mask:0xf bank_mask:0xf bound_ctrl:1
	v_rcp_f32_e32 v54, v54
	v_add_f32_dpp v19, v19, v19 row_shr:4 row_mask:0xf bank_mask:0xf bound_ctrl:1
	v_add_f32_dpp v27, v27, v27 row_shr:4 row_mask:0xf bank_mask:0xf bound_ctrl:1
	v_add_f32_dpp v18, v18, v18 row_shr:4 row_mask:0xf bank_mask:0xf bound_ctrl:1
	v_add_f32_dpp v69, v19, v19 row_shr:8 row_mask:0xf bank_mask:0xf bound_ctrl:1
	v_add_f32_e32 v19, 1.0, v26
	v_rcp_f32_e32 v19, v19
	v_add_f32_dpp v71, v27, v27 row_shr:8 row_mask:0xf bank_mask:0xf bound_ctrl:1
	v_fma_f32 v55, v54, v123, v192
	v_mul_f32_e32 v26, v26, v122
	v_fma_f32 v30, v19, v122, v177
	v_add_f32_dpp v31, v18, v18 row_shr:8 row_mask:0xf bank_mask:0xf bound_ctrl:1
	v_add_f32_e32 v89, 0, v31
	v_log_f32_e32 v52, v30
	v_mov_b32_dpp v18, v31 row_newbcast:15 row_mask:0xf bank_mask:0xf bound_ctrl:1
	v_max_f32_e32 v31, 0xc1f00000, v61
	v_mul_f32_e32 v31, 0xbfb8aa3b, v31
	v_exp_f32_e32 v31, v31
	v_mul_f32_e32 v27, 0x3f317218, v52
	v_add_f32_e32 v61, 1.0, v31
	v_log_f32_e32 v55, v55
	v_mul_f32_e32 v73, v19, v26
	v_rcp_f32_e32 v61, v61
	s_nop 0
	v_fma_f32 v91, v61, v201, v191
	v_mul_f32_e32 v19, 0x3f317218, v55
	v_mov_b32_e32 v75, v19
	v_max_f32_e32 v26, 0xc1f00000, v40
	v_mul_f32_e32 v19, v44, v123
	v_mul_f32_e32 v26, 0xbfb8aa3b, v26
	v_mul_f32_e32 v77, v54, v19
	v_add_f32_dpp v19, v27, v27 row_shr:1 row_mask:0xf bank_mask:0xf bound_ctrl:1
	v_exp_f32_e32 v27, v26
	v_add_f32_e32 v55, 1.0, v36
	v_add_f32_dpp v19, v19, v19 row_shr:2 row_mask:0xf bank_mask:0xf bound_ctrl:1
	v_rcp_f32_e32 v55, v55
	v_max_f32_e32 v53, 0xc1f00000, v53
	v_add_f32_dpp v19, v19, v19 row_shr:4 row_mask:0xf bank_mask:0xf bound_ctrl:1
	v_mul_f32_e32 v53, 0xbfb8aa3b, v53
	v_fmac_f32_e32 v192, v55, v123
	v_add_f32_dpp v40, v19, v19 row_shr:8 row_mask:0xf bank_mask:0xf bound_ctrl:1
	v_add_f32_e32 v19, 1.0, v27
	v_rcp_f32_e32 v19, v19
	v_mul_f32_e32 v27, v27, v122
	v_exp_f32_e32 v53, v53
	v_fmac_f32_e32 v177, v19, v122
	v_mul_f32_e32 v83, v19, v27
	v_add_f32_e32 v98, 1.0, v53
	v_log_f32_e32 v44, v177
	v_rcp_f32_e32 v98, v98
	v_max_f32_e32 v45, 0xc1f00000, v45
	v_mul_f32_e32 v45, 0xbfb8aa3b, v45
	v_fma_f32 v99, v98, v201, v191
	v_exp_f32_e32 v45, v45
	v_mul_f32_e32 v44, 0x3f317218, v44
	v_add_f32_e32 v103, 1.0, v45
	v_log_f32_e32 v81, v192
	v_rcp_f32_e32 v103, v103
	s_nop 0
	v_fma_f32 v104, v103, v201, v191
	v_max_f32_e32 v37, 0xc1f00000, v37
	v_mul_f32_e32 v19, 0x3f317218, v81
	v_mov_b32_e32 v81, v19
	v_max_f32_e32 v27, 0xc1f00000, v65
	v_mul_f32_e32 v27, 0xbfb8aa3b, v27
	v_exp_f32_e32 v27, v27
	v_mul_f32_e32 v19, v36, v123
	v_mul_f32_e32 v85, v55, v19
	v_add_f32_e32 v55, 0, v23
	v_add_f32_dpp v19, v44, v44 row_shr:1 row_mask:0xf bank_mask:0xf bound_ctrl:1
	v_add_f32_e32 v36, 1.0, v27
	v_rcp_f32_e32 v36, v36
	v_add_f32_dpp v19, v19, v19 row_shr:2 row_mask:0xf bank_mask:0xf bound_ctrl:1
; __device__ __forceinline__ float scan16(float x) { x += dpp_shr<1>(x); x += dpp_shr<2>(x); x += dpp_shr<4>(x); x += dpp_shr<8>(x); return x; }
;     __device__ __forceinline__ void operator()(const f32x4 (&acc)[2][2][4][2], const pg8::Unit& u, int wr, int wc, int fr, int fq) const {
;     ...
;                             { const float z = acc[ai][0][m][1][j]; const float e = __expf(fminf(-z, 30.f)); const float s = __builtin_amdgcn_rcpf(1.f + e); lfF[m] = __logf(lbF[j] + (1.f - lbF[j]) * s); kkF[m] = (1.f - lbF[j]) * e * s; }
;                             { const float z = acc[ai][1][m][0][j]; const float e = __expf(fminf(-z, 30.f)); const float s = __builtin_amdgcn_rcpf(1.f + e); lfB[m] = __logf(lbB[j] + (1.f - lbB[j]) * s); kkB[m] = (1.f - lbB[j]) * e * s; }
;                             pF[m] = scan16(lfF[m]); pB[m] = scan16(lfB[m]);
;                             tF[m] = __int_as_float(__builtin_amdgcn_update_dpp(0, __float_as_int(pF[m]), 0x15F, 0xf, 0xf, true));
;                             tB[m] = __int_as_float(__builtin_amdgcn_update_dpp(0, __float_as_int(pB[m]), 0x15F, 0xf, 0xf, true));
	v_mul_f32_e32 v37, 0xbfb8aa3b, v37
	v_exp_f32_e32 v37, v37
	v_add_f32_dpp v19, v19, v19 row_shr:4 row_mask:0xf bank_mask:0xf bound_ctrl:1
	v_mov_b32_dpp v47, v110 row_newbcast:15 row_mask:0xf bank_mask:0xf bound_ctrl:1
	v_mov_b32_dpp v48, v69 row_newbcast:15 row_mask:0xf bank_mask:0xf bound_ctrl:1
	v_add_f32_dpp v65, v19, v19 row_shr:8 row_mask:0xf bank_mask:0xf bound_ctrl:1
	v_add_f32_dpp v19, v81, v81 row_shr:1 row_mask:0xf bank_mask:0xf bound_ctrl:1
	v_add_f32_e32 v108, 1.0, v37
	v_rcp_f32_e32 v108, v108
	v_add_f32_dpp v19, v19, v19 row_shr:2 row_mask:0xf bank_mask:0xf bound_ctrl:1
	v_add_f32_dpp v26, v75, v75 row_shr:1 row_mask:0xf bank_mask:0xf bound_ctrl:1
	v_mov_b32_dpp v44, v65 row_newbcast:15 row_mask:0xf bank_mask:0xf bound_ctrl:1
	v_add_f32_dpp v19, v19, v19 row_shr:4 row_mask:0xf bank_mask:0xf bound_ctrl:1
	v_fmac_f32_e32 v191, v108, v201
	v_add_f32_dpp v26, v26, v26 row_shr:2 row_mask:0xf bank_mask:0xf bound_ctrl:1
	v_add_f32_dpp v87, v19, v19 row_shr:8 row_mask:0xf bank_mask:0xf bound_ctrl:1
	v_fma_f32 v19, v36, v124, v173
	v_add_f32_dpp v26, v26, v26 row_shr:4 row_mask:0xf bank_mask:0xf bound_ctrl:1
	v_mov_b32_dpp v30, v71 row_newbcast:15 row_mask:0xf bank_mask:0xf bound_ctrl:1
	v_log_f32_e32 v19, v19
	v_add_f32_dpp v79, v26, v26 row_shr:8 row_mask:0xf bank_mask:0xf bound_ctrl:1
	v_mov_b32_dpp v26, v40 row_newbcast:15 row_mask:0xf bank_mask:0xf bound_ctrl:1
	v_mov_b32_dpp v52, v87 row_newbcast:15 row_mask:0xf bank_mask:0xf bound_ctrl:1
	v_mov_b32_dpp v54, v79 row_newbcast:15 row_mask:0xf bank_mask:0xf bound_ctrl:1
	s_addk_i32 s45, 0x80
	v_mul_f32_e32 v19, 0x3f317218, v19
	v_mul_f32_e32 v23, v27, v124
	v_log_f32_e32 v91, v91
	v_mul_f32_e32 v93, v36, v23
	v_add_f32_dpp v19, v19, v19 row_shr:1 row_mask:0xf bank_mask:0xf bound_ctrl:1
	s_nop 1
	v_add_f32_dpp v19, v19, v19 row_shr:2 row_mask:0xf bank_mask:0xf bound_ctrl:1
	s_nop 0
	v_mul_f32_e32 v23, 0x3f317218, v91
	v_mov_b32_e32 v91, v23
	v_mul_f32_e32 v23, v31, v201
	v_mul_f32_e32 v61, v61, v23
	v_max_f32_e32 v23, 0xc1f00000, v57
	v_mul_f32_e32 v23, 0xbfb8aa3b, v23
	v_exp_f32_e32 v27, v23
	v_add_f32_dpp v19, v19, v19 row_shr:4 row_mask:0xf bank_mask:0xf bound_ctrl:1
	s_nop 1
	v_add_f32_dpp v96, v19, v19 row_shr:8 row_mask:0xf bank_mask:0xf bound_ctrl:1
	v_add_f32_e32 v19, 1.0, v27
	v_rcp_f32_e32 v31, v19
	v_mul_f32_e32 v27, v27, v124
	v_add_f32_dpp v19, v91, v91 row_shr:1 row_mask:0xf bank_mask:0xf bound_ctrl:1
	v_fma_f32 v23, v31, v124, v173
	s_nop 0
	v_add_f32_dpp v19, v19, v19 row_shr:2 row_mask:0xf bank_mask:0xf bound_ctrl:1
	s_nop 0
	v_log_f32_e32 v36, v23
	v_add_f32_dpp v19, v19, v19 row_shr:4 row_mask:0xf bank_mask:0xf bound_ctrl:1
	v_mov_b32_dpp v23, v96 row_newbcast:15 row_mask:0xf bank_mask:0xf bound_ctrl:1
	s_nop 0
	v_add_f32_dpp v97, v19, v19 row_shr:8 row_mask:0xf bank_mask:0xf bound_ctrl:1
	s_nop 0
	v_mul_f32_e32 v36, 0x3f317218, v36
	v_mov_b32_dpp v19, v97 row_newbcast:15 row_mask:0xf bank_mask:0xf bound_ctrl:1
	v_log_f32_e32 v99, v99
	v_mul_f32_e32 v100, v31, v27
	s_nop 1
	v_mul_f32_e32 v27, 0x3f317218, v99
	v_mov_b32_e32 v99, v27
	v_max_f32_e32 v31, 0xc1f00000, v49
	v_mul_f32_e32 v27, v53, v201
	v_mul_f32_e32 v31, 0xbfb8aa3b, v31
	v_mul_f32_e32 v98, v98, v27
	v_add_f32_dpp v27, v36, v36 row_shr:1 row_mask:0xf bank_mask:0xf bound_ctrl:1
	v_exp_f32_e32 v36, v31
	v_add_f32_dpp v31, v99, v99 row_shr:1 row_mask:0xf bank_mask:0xf bound_ctrl:1
	v_add_f32_dpp v27, v27, v27 row_shr:2 row_mask:0xf bank_mask:0xf bound_ctrl:1
	s_nop 0
	v_add_f32_dpp v31, v31, v31 row_shr:2 row_mask:0xf bank_mask:0xf bound_ctrl:1
	v_add_f32_dpp v27, v27, v27 row_shr:4 row_mask:0xf bank_mask:0xf bound_ctrl:1
	s_nop 0
	v_add_f32_dpp v31, v31, v31 row_shr:4 row_mask:0xf bank_mask:0xf bound_ctrl:1
	v_add_f32_dpp v101, v27, v27 row_shr:8 row_mask:0xf bank_mask:0xf bound_ctrl:1
	v_add_f32_e32 v27, 1.0, v36
	v_rcp_f32_e32 v27, v27
	v_mul_f32_e32 v36, v36, v124
	v_add_f32_dpp v102, v31, v31 row_shr:8 row_mask:0xf bank_mask:0xf bound_ctrl:1
	v_fma_f32 v49, v27, v124, v173
	s_nop 0
	v_mov_b32_dpp v31, v102 row_newbcast:15 row_mask:0xf bank_mask:0xf bound_ctrl:1
	s_nop 0
	v_log_f32_e32 v53, v49
	s_nop 0
	v_mov_b32_dpp v49, v101 row_newbcast:15 row_mask:0xf bank_mask:0xf bound_ctrl:1
	s_nop 1
	v_mul_f32_e32 v53, 0x3f317218, v53
	s_nop 0
	v_log_f32_e32 v104, v104
	v_mul_f32_e32 v105, v27, v36
	s_nop 1
	v_mul_f32_e32 v27, 0x3f317218, v104
	v_mov_b32_e32 v104, v27
	v_max_f32_e32 v36, 0xc1f00000, v41
	v_mul_f32_e32 v36, 0xbfb8aa3b, v36
	v_mul_f32_e32 v27, v45, v201
	v_exp_f32_e32 v36, v36
	v_mul_f32_e32 v103, v103, v27
	v_add_f32_dpp v27, v53, v53 row_shr:1 row_mask:0xf bank_mask:0xf bound_ctrl:1
	s_nop 1
	v_add_f32_dpp v27, v27, v27 row_shr:2 row_mask:0xf bank_mask:0xf bound_ctrl:1
	s_nop 1
	v_add_f32_dpp v27, v27, v27 row_shr:4 row_mask:0xf bank_mask:0xf bound_ctrl:1
	s_nop 1
	v_add_f32_dpp v106, v27, v27 row_shr:8 row_mask:0xf bank_mask:0xf bound_ctrl:1
	v_add_f32_e32 v27, 1.0, v36
	v_rcp_f32_e32 v41, v27
	v_mul_f32_e32 v36, v36, v124
	v_add_f32_dpp v27, v104, v104 row_shr:1 row_mask:0xf bank_mask:0xf bound_ctrl:1
	v_fmac_f32_e32 v173, v41, v124
	v_mul_f32_e32 v110, v41, v36
	v_add_f32_dpp v27, v27, v27 row_shr:2 row_mask:0xf bank_mask:0xf bound_ctrl:1
	v_log_f32_e32 v45, v173
	s_nop 0
	v_add_f32_dpp v27, v27, v27 row_shr:4 row_mask:0xf bank_mask:0xf bound_ctrl:1
	s_nop 1
	v_add_f32_dpp v107, v27, v27 row_shr:8 row_mask:0xf bank_mask:0xf bound_ctrl:1
	v_mov_b32_dpp v27, v106 row_newbcast:15 row_mask:0xf bank_mask:0xf bound_ctrl:1
	v_mul_f32_e32 v45, 0x3f317218, v45
	v_mov_b32_dpp v53, v107 row_newbcast:15 row_mask:0xf bank_mask:0xf bound_ctrl:1
	v_log_f32_e32 v109, v191
	s_nop 1
; __device__ __forceinline__ unsigned cvt_pk_bf16(float lo, float hi) { unsigned r; asm volatile("v_cvt_pk_bf16_f32 %0, %1, %2" : "=v"(r) : "v"(lo), "v"(hi)); return r; }
;     __device__ __forceinline__ void operator()(const f32x4 (&acc)[2][2][4][2], const pg8::Unit& u, int wr, int wc, int fr, int fq) const {
;     ...
;                             { const float z = acc[ai][0][m][1][j]; const float e = __expf(fminf(-z, 30.f)); const float s = __builtin_amdgcn_rcpf(1.f + e); lfF[m] = __logf(lbF[j] + (1.f - lbF[j]) * s); kkF[m] = (1.f - lbF[j]) * e * s; }
;                             { const float z = acc[ai][1][m][0][j]; const float e = __expf(fminf(-z, 30.f)); const float s = __builtin_amdgcn_rcpf(1.f + e); lfB[m] = __logf(lbB[j] + (1.f - lbB[j]) * s); kkB[m] = (1.f - lbB[j]) * e * s; }
;                             pF[m] = scan16(lfF[m]); pB[m] = scan16(lfB[m]);
;                             tF[m] = __int_as_float(__builtin_amdgcn_update_dpp(0, __float_as_int(pF[m]), 0x15F, 0xf, 0xf, true));
;                             tB[m] = __int_as_float(__builtin_amdgcn_update_dpp(0, __float_as_int(pB[m]), 0x15F, 0xf, 0xf, true));
;                         }
;                         const float rF = tF[0] + tF[1], blF = rF + tF[2] + tF[3];
;                         const float rB = tB[2] + tB[3], blB = rB + tB[0] + tB[1];
;                         float cF = 0.f, cB = 0.f;
; #pragma unroll
;                         for (int m = 0; m < 4; ++m) {
;                             const float bF = pF[m] + cF; cF += tF[m];
;                             const float bB = blB - (pB[m] + cB) + lfB[m]; cB += tB[m];
;                             const float xF = clamp80(bF - rF), xB = clamp80(bB - rB);
;                             const float q = acc[ai][0][m][0][j];
;                             vQF[m][jj] = q * __expf(xF); vKF[m][jj] = kkF[m] * __expf(-xF);
;                             vQB[m][jj] = q * __expf(xB); vKB[m][jj] = kkB[m] * __expf(-xB);
;                         }
;                         rtv[0][j] = rF; rtv[1][j] = rB; rtv[2][j] = blF - rF; rtv[3][j] = blB - rB;
;                     }
; #pragma unroll
;                     for (int m = 0; m < 4; ++m) { oQF[m][jp] = cvt_pk_bf16(vQF[m][0], vQF[m][1]); oQB[m][jp] = cvt_pk_bf16(vQB[m][0], vQB[m][1]); oKF[m][jp] = cvt_pk_bf16(vKF[m][0], vKF[m][1]); oKB[m][jp] = cvt_pk_bf16(vKB[m][0], vKB[m][1]); }
	v_mul_f32_e32 v36, 0x3f317218, v109
	v_mov_b32_e32 v109, v36
	v_mul_f32_e32 v36, v37, v201
	v_mul_f32_e32 v108, v108, v36
	s_nop 0
	v_add_f32_dpp v36, v45, v45 row_shr:1 row_mask:0xf bank_mask:0xf bound_ctrl:1
	s_nop 1
	v_add_f32_dpp v36, v36, v36 row_shr:2 row_mask:0xf bank_mask:0xf bound_ctrl:1
	s_nop 1
	v_add_f32_dpp v36, v36, v36 row_shr:4 row_mask:0xf bank_mask:0xf bound_ctrl:1
	s_nop 1
	v_add_f32_dpp v111, v36, v36 row_shr:8 row_mask:0xf bank_mask:0xf bound_ctrl:1
	v_add_f32_dpp v36, v109, v109 row_shr:1 row_mask:0xf bank_mask:0xf bound_ctrl:1
	s_nop 1
	v_add_f32_dpp v36, v36, v36 row_shr:2 row_mask:0xf bank_mask:0xf bound_ctrl:1
	s_nop 1
	v_add_f32_dpp v36, v36, v36 row_shr:4 row_mask:0xf bank_mask:0xf bound_ctrl:1
	s_nop 1
	v_add_f32_dpp v112, v36, v36 row_shr:8 row_mask:0xf bank_mask:0xf bound_ctrl:1
	v_pk_add_f32 v[36:37], v[22:23], v[48:49]
	v_add_f32_e32 v22, 0, v22
	v_sub_f32_e32 v41, v55, v36
	v_med3_f32 v41, v41, s96, v190
	v_mul_f32_e32 v45, 0x3fb8aa3b, v41
	v_exp_f32_e32 v57, v45
	v_mul_f32_e32 v41, 0xbfb8aa3b, v41
	v_exp_f32_e32 v41, v41
	v_mov_b32_dpp v55, v112 row_newbcast:15 row_mask:0xf bank_mask:0xf bound_ctrl:1
	v_mul_f32_e32 v113, v32, v57
	v_add_f32_e32 v57, v22, v69
	v_sub_f32_e32 v57, v57, v36
	v_med3_f32 v57, v57, s96, v190
	v_mul_f32_e32 v69, 0x3fb8aa3b, v57
	v_mul_f32_e32 v57, 0xbfb8aa3b, v57
	v_add_f32_e32 v22, v22, v48
	v_exp_f32_e32 v69, v69
	v_exp_f32_e32 v57, v57
	v_add_f32_e32 v40, v22, v40
	v_add_f32_e32 v22, v22, v26
	v_sub_f32_e32 v40, v40, v36
	v_add_f32_e32 v22, v22, v65
	v_med3_f32 v40, v40, s96, v190
	v_sub_f32_e32 v22, v22, v36
	v_mul_f32_e32 v60, v60, v41
	v_mul_f32_e32 v41, 0x3fb8aa3b, v40
	v_mul_f32_e32 v40, 0xbfb8aa3b, v40
	v_med3_f32 v22, v22, s96, v190
	v_mul_f32_e32 v48, v28, v69
	v_mul_f32_e32 v69, v56, v57
	v_exp_f32_e32 v41, v41
	v_exp_f32_e32 v40, v40
	v_mul_f32_e32 v56, 0x3fb8aa3b, v22
	v_exp_f32_e32 v56, v56
	v_mul_f32_e32 v65, v24, v41
	v_mul_f32_e32 v73, v73, v40
	v_pk_add_f32 v[40:41], v[52:53], v[54:55]
	v_mul_f32_e32 v114, v20, v56
	v_pk_add_f32 v[56:57], v[40:41], v[18:19]
	v_add_f32_e32 v52, 0, v18
	v_pk_add_f32 v[56:57], v[56:57], v[30:31]
	v_add_f32_e32 v55, v52, v71
	v_sub_f32_e32 v18, v56, v89
	v_add_f32_e32 v18, v59, v18
	v_add_f32_e32 v52, v52, v30
	v_sub_f32_e32 v18, v18, v40
	v_add_f32_e32 v71, v52, v79
	v_med3_f32 v18, v18, s96, v190
	v_sub_f32_e32 v55, v56, v55
	v_add_f32_e32 v52, v52, v54
	v_mul_f32_e32 v30, 0x3fb8aa3b, v18
	v_mul_f32_e32 v18, 0xbfb8aa3b, v18
	v_add_f32_e32 v55, v67, v55
	v_add_f32_e32 v52, v52, v87
	v_exp_f32_e32 v18, v18
	v_sub_f32_e32 v55, v55, v40
	v_sub_f32_e32 v52, v56, v52
	v_med3_f32 v55, v55, s96, v190
	v_add_f32_e32 v52, v81, v52
	v_mul_f32_e32 v59, 0x3fb8aa3b, v55
	v_mul_f32_e32 v55, 0xbfb8aa3b, v55
	v_sub_f32_e32 v52, v52, v40
	v_exp_f32_e32 v30, v30
	v_exp_f32_e32 v55, v55
	v_med3_f32 v52, v52, s96, v190
	v_mul_f32_e32 v18, v58, v18
	v_mul_f32_e32 v58, 0x3fb8aa3b, v52
	v_exp_f32_e32 v58, v58
	v_mul_f32_e32 v30, v32, v30
	v_mul_f32_e32 v32, v63, v55
	v_sub_f32_e32 v55, v56, v71
	v_add_f32_e32 v55, v75, v55
	v_sub_f32_e32 v54, v55, v40
	v_mul_f32_e32 v20, v20, v58
	v_add_f32_e32 v58, 0, v97
	v_med3_f32 v54, v54, s96, v190
	v_sub_f32_e32 v58, v57, v58
	v_mul_f32_e32 v55, 0x3fb8aa3b, v54
	v_add_f32_e32 v58, v91, v58
	v_exp_f32_e32 v55, v55
	v_sub_f32_e32 v58, v58, v41
	v_med3_f32 v58, v58, s96, v190
	v_mul_f32_e32 v63, 0x3fb8aa3b, v58
	v_mul_f32_e32 v58, 0xbfb8aa3b, v58
	v_exp_f32_e32 v59, v59
	v_exp_f32_e32 v58, v58
	v_mul_f32_e32 v24, v24, v55
	v_add_f32_e32 v55, 0, v96
	v_sub_f32_e32 v55, v55, v37
	v_add_f32_e32 v23, 0, v23
	v_add_f32_e32 v19, 0, v19
	v_med3_f32 v55, v55, s96, v190
	v_mul_f32_e32 v28, v28, v59
	v_mul_f32_e32 v59, 0x3fb8aa3b, v55
	v_mul_f32_e32 v58, v61, v58
	v_add_f32_e32 v61, v23, v101
	v_add_f32_e32 v23, v23, v49
	v_add_f32_e32 v49, v19, v102
	v_exp_f32_e32 v59, v59
	v_exp_f32_e32 v63, v63
	v_sub_f32_e32 v49, v57, v49
	v_add_f32_e32 v49, v99, v49
	v_add_f32_e32 v19, v19, v31
	v_sub_f32_e32 v31, v61, v37
	v_sub_f32_e32 v49, v49, v41
	v_med3_f32 v31, v31, s96, v190
	v_med3_f32 v49, v49, s96, v190
	v_mul_f32_e32 v59, v33, v59
	v_mul_f32_e32 v33, v33, v63
	v_mul_f32_e32 v61, 0x3fb8aa3b, v31
	v_mul_f32_e32 v63, 0x3fb8aa3b, v49
	v_exp_f32_e32 v61, v61
	v_exp_f32_e32 v63, v63
	v_add_f32_e32 v67, v19, v107
	v_sub_f32_e32 v67, v57, v67
	v_mul_f32_e32 v61, v29, v61
	v_mul_f32_e32 v29, v29, v63
	v_add_f32_e32 v63, v23, v106
	v_add_f32_e32 v67, v104, v67
	v_add_f32_e32 v19, v19, v53
	v_sub_f32_e32 v53, v63, v37
	v_sub_f32_e32 v63, v67, v41
	v_med3_f32 v53, v53, s96, v190
	v_med3_f32 v63, v63, s96, v190
	v_mul_f32_e32 v67, 0x3fb8aa3b, v53
	v_mul_f32_e32 v71, 0x3fb8aa3b, v63
	v_add_f32_e32 v23, v23, v27
	v_exp_f32_e32 v67, v67
	v_exp_f32_e32 v71, v71
	v_add_f32_e32 v19, v19, v112
	v_add_f32_e32 v23, v23, v111
	v_sub_f32_e32 v19, v57, v19
	v_add_f32_e32 v19, v109, v19
	v_sub_f32_e32 v23, v23, v37
	v_med3_f32 v23, v23, s96, v190
	v_sub_f32_e32 v19, v19, v41
	v_mul_f32_e32 v54, 0xbfb8aa3b, v54
	v_mul_f32_e32 v63, 0xbfb8aa3b, v63
	v_mul_f32_e32 v67, v25, v67
	v_mul_f32_e32 v25, v25, v71
	v_med3_f32 v19, v19, s96, v190
	v_mul_f32_e32 v71, 0x3fb8aa3b, v23
	v_mul_f32_e32 v22, 0xbfb8aa3b, v22
	v_exp_f32_e32 v54, v54
	v_mul_f32_e32 v52, 0xbfb8aa3b, v52
	v_mul_f32_e32 v55, 0xbfb8aa3b, v55
	v_mul_f32_e32 v31, 0xbfb8aa3b, v31
	v_mul_f32_e32 v49, 0xbfb8aa3b, v49
	v_mul_f32_e32 v53, 0xbfb8aa3b, v53
	v_exp_f32_e32 v63, v63
	v_exp_f32_e32 v71, v71
	v_mul_f32_e32 v23, 0xbfb8aa3b, v23
	v_mul_f32_e32 v75, 0x3fb8aa3b, v19
	v_mul_f32_e32 v19, 0xbfb8aa3b, v19
	v_exp_f32_e32 v22, v22
	v_exp_f32_e32 v52, v52
	v_exp_f32_e32 v55, v55
	v_exp_f32_e32 v31, v31
	v_exp_f32_e32 v49, v49
	v_exp_f32_e32 v53, v53
	v_exp_f32_e32 v23, v23
	v_exp_f32_e32 v75, v75
	v_exp_f32_e32 v19, v19
	v_mov_b32_dpp v45, v111 row_newbcast:15 row_mask:0xf bank_mask:0xf bound_ctrl:1
	v_mul_f32_e32 v54, v77, v54
	v_mul_f32_e32 v63, v103, v63
	v_mul_f32_e32 v77, v21, v71
	v_mul_f32_e32 v22, v83, v22
	v_mul_f32_e32 v52, v85, v52
	v_mul_f32_e32 v55, v93, v55
	v_mul_f32_e32 v31, v100, v31
	v_mul_f32_e32 v49, v98, v49
	v_mul_f32_e32 v53, v105, v53
	v_mul_f32_e32 v23, v110, v23
	v_mul_f32_e32 v21, v21, v75
	v_mul_f32_e32 v19, v108, v19
	v_cvt_pk_bf16_f32 v91, v113, v59
	v_cvt_pk_bf16_f32 v87, v30, v33
	v_cvt_pk_bf16_f32 v83, v60, v55
	v_cvt_pk_bf16_f32 v79, v18, v58
	v_cvt_pk_bf16_f32 v93, v48, v61
	v_cvt_pk_bf16_f32 v89, v28, v29
	v_cvt_pk_bf16_f32 v85, v69, v31
	v_cvt_pk_bf16_f32 v81, v32, v49
	v_cvt_pk_bf16_f32 v75, v65, v67
	v_cvt_pk_bf16_f32 v71, v24, v25
	v_cvt_pk_bf16_f32 v67, v73, v53
	v_cvt_pk_bf16_f32 v63, v54, v63
	v_cvt_pk_bf16_f32 v77, v114, v77
	v_cvt_pk_bf16_f32 v73, v20, v21
	v_cvt_pk_bf16_f32 v69, v22, v23
	v_cvt_pk_bf16_f32 v65, v52, v19
	s_and_saveexec_b64 s[10:11], s[6:7]
	s_cbranch_execz .LBB0_197
; __device__ __forceinline__ unsigned cvt_pk_bf16(float lo, float hi) { unsigned r; asm volatile("v_cvt_pk_bf16_f32 %0, %1, %2" : "=v"(r) : "v"(lo), "v"(hi)); return r; }
;     __device__ __forceinline__ void operator()(const f32x4 (&acc)[2][2][4][2], const pg8::Unit& u, int wr, int wc, int fr, int fq) const {
;     ...
;                         rtv[0][j] = rF; rtv[1][j] = rB; rtv[2][j] = blF - rF; rtv[3][j] = blB - rB;
;                     }
; #pragma unroll
;                     for (int m = 0; m < 4; ++m) { oQF[m][jp] = cvt_pk_bf16(vQF[m][0], vQF[m][1]); oQB[m][jp] = cvt_pk_bf16(vQB[m][0], vQB[m][1]); oKF[m][jp] = cvt_pk_bf16(vKF[m][0], vKF[m][1]); oKB[m][jp] = cvt_pk_bf16(vKB[m][0], vKB[m][1]); }
;                 }
;                 if (fr == 0) {
; #pragma unroll
;                     for (int t = 0; t < 4; ++t) *(f32x4*)(RT + (size_t)t * NCHUNK * 512 + (size_t)cid * 512 + ch0) = rtv[t];
;                 }
	s_ashr_i32 s12, s45, 6
	s_ashr_i32 s13, s12, 31
	s_lshl_b64 s[12:13], s[12:13], 11
	v_lshl_add_u64 v[22:23], v[174:175], 0, s[12:13]
	v_add_co_u32_e32 v18, vcc, 0x110000, v22
	v_pk_add_f32 v[20:21], v[34:35], v[42:43]
	s_nop 0
	v_addc_co_u32_e32 v19, vcc, 0, v23, vcc
	global_store_dwordx4 v[18:19], v[38:41], off
	v_pk_add_f32 v[18:19], v[36:37], v[26:27]
	v_pk_add_f32 v[24:25], v[20:21], v[46:47]
	v_pk_add_f32 v[18:19], v[18:19], v[44:45]
	global_store_dwordx4 v[22:23], v[34:37], off
	v_sub_f32_e32 v20, v18, v36
	v_sub_f32_e32 v18, v24, v34
	v_add_co_u32_e32 v24, vcc, 0x220000, v22
	v_sub_f32_e32 v21, v19, v37
	v_sub_f32_e32 v19, v25, v35
	v_addc_co_u32_e32 v25, vcc, 0, v23, vcc
	v_add_co_u32_e32 v22, vcc, 0x330000, v22
	global_store_dwordx4 v[24:25], v[18:21], off
	s_nop 0
	v_addc_co_u32_e32 v23, vcc, 0, v23, vcc
	v_pk_add_f32 v[18:19], v[50:51], v[38:39] neg_lo:[0,1] neg_hi:[0,1]
	v_pk_add_f32 v[20:21], v[56:57], v[40:41] neg_lo:[0,1] neg_hi:[0,1]
	global_store_dwordx4 v[22:23], v[18:21], off

; __device__ __forceinline__ unsigned cvt_pk_bf16(float lo, float hi) { unsigned r; asm volatile("v_cvt_pk_bf16_f32 %0, %1, %2" : "=v"(r) : "v"(lo), "v"(hi)); return r; }
; __device__ void conv_phase(LAS unsigned char* lds, const Params& p) {
;     ...
;         float cbv[8], lg[8], lbv[8], hg[8];
;         { const f32x4 a0 = *(const f32x4*)(p.conv_b + ch0), a1 = *(const f32x4*)(p.conv_b + ch0 + 4), b0 = *(const f32x4*)(p.conv_ln_g + ch0), b1 = *(const f32x4*)(p.conv_ln_g + ch0 + 4);
;           const f32x4 d0 = *(const f32x4*)(p.conv_ln_b + ch0), d1 = *(const f32x4*)(p.conv_ln_b + ch0 + 4), e0 = *(const f32x4*)(p.hgrn_norm_g + ch0), e1 = *(const f32x4*)(p.hgrn_norm_g + ch0 + 4);
; #pragma unroll
;           for (int c = 0; c < 4; ++c) { cbv[c] = a0[c]; cbv[4 + c] = a1[c]; lg[c] = b0[c]; lg[4 + c] = b1[c]; lbv[c] = d0[c]; lbv[4 + c] = d1[c]; hg[c] = e0[c]; hg[4 + c] = e1[c]; } }
; #pragma unroll
;         for (int lr = 0; lr < 2; ++lr)
; #pragma unroll
;             for (int lc = 0; lc < 2; ++lc) {
;                 const size_t token = (size_t)b * 4096 + (r0 + lr) * 64 + (c0 + lc);
;                 float v[8]; float s1 = 0.f, s2 = 0.f;
; #pragma unroll
;                 for (int c = 0; c < 8; ++c) { v[c] = (half ? acc[lc * 2 + lr][c] : acc[lr * 2 + lc][c]) + cbv[c]; s1 += v[c]; s2 += v[c] * v[c]; }
; #pragma unroll
;                 for (int m = 32; m >= 1; m >>= 1) { s1 += __shfl_xor(s1, m); s2 += __shfl_xor(s2, m); }
;                 const float mean = s1 * (1.f / 512.f), var = fmaxf(s2 * (1.f / 512.f) - mean * mean, 0.f), rstd = rsqrtf(var + EPS);
;                 const u32x4 gbr = *(const u32x4*)(GBp + token * 512 + ch0);
;                 const float gbv[8] = {bf_lo(gbr[0]), bf_hi(gbr[0]), bf_lo(gbr[1]), bf_hi(gbr[1]), bf_lo(gbr[2]), bf_hi(gbr[2]), bf_lo(gbr[3]), bf_hi(gbr[3])};
;                 float y[8];
; #pragma unroll
;                 for (int c = 0; c < 8; ++c) { const float t = (v[c] - mean) * rstd * lg[c] + lbv[c]; y[c] = siluf_(t) * gbv[c]; }
;                 u32x4 ob = {cvt_pk_bf16(y[0], y[1]), cvt_pk_bf16(y[2], y[3]), cvt_pk_bf16(y[4], y[5]), cvt_pk_bf16(y[6], y[7])};
;                 *(u32x4*)(A2 + token * 1024 + 512 + ch0) = ob;
;                 const u32x4 fo = *(const u32x4*)(O + token * 512 + ch0), bo = *(const u32x4*)(O + ((size_t)NLAT + token) * 512 + ch0);
.LBB0_371:
	global_load_dwordx4 v[22:25], v[76:77], off
	global_load_dwordx4 v[14:17], v[76:77], off offset:16
	v_ashrrev_i32_e32 v115, 31, v114
	v_lshlrev_b64 v[36:37], 12, v[114:115]
	v_lshl_or_b32 v48, v124, 6, v36
	v_or_b32_e32 v36, v48, v123
	v_lshlrev_b64 v[40:41], 10, v[36:37]
	v_lshl_add_u64 v[38:39], v[70:71], 0, v[40:41]
	global_load_dwordx4 v[50:53], v[38:39], off
	global_load_dwordx4 v[18:21], v[78:79], off offset:16
	global_load_dwordx4 v[30:33], v[78:79], off
	global_load_dwordx4 v[10:13], v[80:81], off offset:16
	global_load_dwordx4 v[26:29], v[80:81], off
	global_load_dwordx4 v[2:5], v[82:83], off offset:16
	global_load_dwordx4 v[6:9], v[82:83], off
	v_add_co_u32_e32 v252, vcc, 0x10000, v40
	s_nop 1
	v_addc_co_u32_e32 v253, vcc, 0, v41, vcc
	v_lshl_add_u64 v[254:255], s[68:69], 0, v[66:67]
	v_add_co_u32_e32 v254, vcc, s35, v254
	s_nop 1
	v_addc_co_u32_e32 v255, vcc, 0, v255, vcc
	v_lshl_add_u64 v[192:193], v[254:255], 0, v[40:41]
	v_lshl_add_u64 v[196:197], v[72:73], 0, v[40:41]
	v_lshl_add_u64 v[200:201], v[74:75], 0, v[40:41]
	v_lshl_add_u64 v[204:205], v[70:71], 0, v[40:41]
	v_lshl_add_u64 v[208:209], v[254:255], 0, v[40:41]
	v_lshl_add_u64 v[212:213], v[72:73], 0, v[40:41]
	v_lshl_add_u64 v[216:217], v[74:75], 0, v[40:41]
	v_lshl_add_u64 v[220:221], v[70:71], 0, v[252:253]
	v_lshl_add_u64 v[224:225], v[254:255], 0, v[252:253]
	v_lshl_add_u64 v[228:229], v[72:73], 0, v[252:253]
	v_lshl_add_u64 v[232:233], v[74:75], 0, v[252:253]
	v_lshl_add_u64 v[236:237], v[70:71], 0, v[252:253]
	v_lshl_add_u64 v[240:241], v[254:255], 0, v[252:253]
	v_lshl_add_u64 v[244:245], v[72:73], 0, v[252:253]
	v_lshl_add_u64 v[248:249], v[74:75], 0, v[252:253]
	global_load_dwordx4 v[192:195], v[192:193], off
	global_load_dwordx4 v[196:199], v[196:197], off
	global_load_dwordx4 v[200:203], v[200:201], off
	global_load_dwordx4 v[204:207], v[204:205], off offset:1024
	global_load_dwordx4 v[208:211], v[208:209], off offset:1024
	global_load_dwordx4 v[212:215], v[212:213], off offset:1024
	global_load_dwordx4 v[216:219], v[216:217], off offset:1024
	global_load_dwordx4 v[220:223], v[220:221], off
	global_load_dwordx4 v[224:227], v[224:225], off
	global_load_dwordx4 v[228:231], v[228:229], off
	global_load_dwordx4 v[232:235], v[232:233], off
	global_load_dwordx4 v[236:239], v[236:237], off offset:1024
	global_load_dwordx4 v[240:243], v[240:241], off offset:1024
	global_load_dwordx4 v[244:247], v[244:245], off offset:1024
	global_load_dwordx4 v[248:251], v[248:249], off offset:1024
	v_and_b32_e32 v38, 64, v69
	v_xor_b32_e32 v39, 32, v69
	v_add_u32_e32 v116, 64, v38
	v_cmp_lt_i32_e32 vcc, v39, v116
	v_xor_b32_e32 v65, 4, v69
	v_mov_b32_e32 v42, v88
	v_cndmask_b32_e32 v38, v69, v39, vcc
	v_lshlrev_b32_e32 v46, 2, v38
	v_xor_b32_e32 v47, 16, v69
	v_cmp_lt_i32_e32 vcc, v47, v116
	v_xor_b32_e32 v49, 8, v69
	s_waitcnt vmcnt(23)
	v_pk_add_f32 v[54:55], v[92:93], v[22:23]
	s_waitcnt vmcnt(22)
	v_pk_mov_b32 v[38:39], v[16:17], v[16:17] op_sel:[1,0]
	v_mul_f32_e32 v44, v55, v55
	v_add_f32_e32 v39, 0, v54
	v_pk_add_f32 v[56:57], v[90:91], v[24:25]
	v_add_f32_e32 v39, v55, v39
	v_pk_fma_f32 v[44:45], v[54:55], v[54:55], v[44:45] op_sel_hi:[1,1,0]
	v_mul_f32_e32 v62, v57, v57
	v_add_f32_e32 v39, v56, v39
	v_pk_fma_f32 v[44:45], v[56:57], v[56:57], v[44:45]
	v_pk_add_f32 v[58:59], v[86:87], v[14:15]
	v_add_f32_e32 v39, v57, v39
	v_pk_add_f32 v[44:45], v[62:63], v[44:45] op_sel_hi:[0,1]
	v_pk_add_f32 v[60:61], v[88:89], v[16:17] op_sel:[0,1] op_sel_hi:[1,0]
	v_mul_f32_e32 v64, v59, v59
	v_mov_b32_e32 v43, v59
	v_add_f32_e32 v39, v58, v39
	v_pk_fma_f32 v[44:45], v[58:59], v[58:59], v[44:45]
	v_pk_mul_f32 v[114:115], v[60:61], v[60:61]
	v_pk_add_f32 v[44:45], v[64:65], v[44:45] op_sel_hi:[0,1]
	v_pk_add_f32 v[42:43], v[42:43], v[38:39]
	v_pk_mov_b32 v[114:115], v[114:115], v[88:89] op_sel:[1,0]
	v_mov_b32_e32 v45, v17
	v_pk_mul_f32 v[62:63], v[60:61], v[42:43]
	v_pk_add_f32 v[42:43], v[60:61], v[42:43]
	v_pk_add_f32 v[44:45], v[114:115], v[44:45]
	v_mov_b32_e32 v63, v43
	v_pk_add_f32 v[42:43], v[62:63], v[44:45]
	ds_bpermute_b32 v45, v46, v43
	ds_bpermute_b32 v44, v46, v42
	v_cndmask_b32_e32 v47, v69, v47, vcc
	v_lshlrev_b32_e32 v47, 2, v47
	v_cmp_lt_i32_e32 vcc, v49, v116
	v_xor_b32_e32 v39, 2, v69
	s_waitcnt lgkmcnt(0)
	v_pk_add_f32 v[44:45], v[42:43], v[44:45]
	ds_bpermute_b32 v63, v47, v45
	ds_bpermute_b32 v62, v47, v44
	v_cndmask_b32_e32 v42, v69, v49, vcc
	v_lshlrev_b32_e32 v42, 2, v42
	v_cmp_lt_i32_e32 vcc, v65, v116
	v_xor_b32_e32 v114, 1, v69
	s_waitcnt lgkmcnt(0)
	v_pk_add_f32 v[44:45], v[44:45], v[62:63]
	ds_bpermute_b32 v63, v42, v45
	ds_bpermute_b32 v62, v42, v44
	v_cndmask_b32_e32 v43, v69, v65, vcc
	v_lshlrev_b32_e32 v43, 2, v43
	v_cmp_lt_i32_e32 vcc, v39, v116
	s_waitcnt vmcnt(21)
	v_and_b32_e32 v49, 0xffff0000, v50
	s_waitcnt lgkmcnt(0)
	v_pk_add_f32 v[62:63], v[44:45], v[62:63]
	ds_bpermute_b32 v65, v43, v63
	ds_bpermute_b32 v64, v43, v62
	v_cndmask_b32_e32 v39, v69, v39, vcc
	v_lshlrev_b32_e32 v44, 2, v39
	v_cmp_lt_i32_e32 vcc, v114, v116
	v_lshlrev_b32_e32 v39, 16, v50
	s_waitcnt lgkmcnt(0)
	v_pk_add_f32 v[62:63], v[62:63], v[64:65]
	ds_bpermute_b32 v65, v44, v63
	ds_bpermute_b32 v64, v44, v62
	v_cndmask_b32_e32 v45, v69, v114, vcc
	v_lshlrev_b32_e32 v45, 2, v45
	v_lshlrev_b32_e32 v114, 16, v51
	v_and_b32_e32 v115, 0xffff0000, v51
	s_waitcnt lgkmcnt(0)
	v_pk_add_f32 v[50:51], v[62:63], v[64:65]
	ds_bpermute_b32 v63, v45, v51
	ds_bpermute_b32 v62, v45, v50
	v_lshlrev_b32_e32 v64, 16, v52
	v_and_b32_e32 v52, 0xffff0000, v52
	v_lshlrev_b32_e32 v65, 16, v53
	v_and_b32_e32 v53, 0xffff0000, v53
	s_waitcnt lgkmcnt(0)
; __device__ __forceinline__ unsigned cvt_pk_bf16(float lo, float hi) { unsigned r; asm volatile("v_cvt_pk_bf16_f32 %0, %1, %2" : "=v"(r) : "v"(lo), "v"(hi)); return r; }
; __device__ __forceinline__ float bf_lo(unsigned u) { return __uint_as_float(u << 16); }
; __device__ __forceinline__ float bf_hi(unsigned u) { return __uint_as_float(u & 0xffff0000u); }
; __device__ __forceinline__ float siluf_(float v) { return v * __builtin_amdgcn_rcpf(1.f + __expf(-v)); }
; __device__ void conv_phase(LAS unsigned char* lds, const Params& p) {
;     ...
;                 const float mean = s1 * (1.f / 512.f), var = fmaxf(s2 * (1.f / 512.f) - mean * mean, 0.f), rstd = rsqrtf(var + EPS);
;                 const u32x4 gbr = *(const u32x4*)(GBp + token * 512 + ch0);
;                 const float gbv[8] = {bf_lo(gbr[0]), bf_hi(gbr[0]), bf_lo(gbr[1]), bf_hi(gbr[1]), bf_lo(gbr[2]), bf_hi(gbr[2]), bf_lo(gbr[3]), bf_hi(gbr[3])};
;                 float y[8];
; #pragma unroll
;                 for (int c = 0; c < 8; ++c) { const float t = (v[c] - mean) * rstd * lg[c] + lbv[c]; y[c] = siluf_(t) * gbv[c]; }
;                 u32x4 ob = {cvt_pk_bf16(y[0], y[1]), cvt_pk_bf16(y[2], y[3]), cvt_pk_bf16(y[4], y[5]), cvt_pk_bf16(y[6], y[7])};
;                 *(u32x4*)(A2 + token * 1024 + 512 + ch0) = ob;
;                 const u32x4 fo = *(const u32x4*)(O + token * 512 + ch0), bo = *(const u32x4*)(O + ((size_t)NLAT + token) * 512 + ch0);
;                 float ov[8]; float ss = 0.f;
; #pragma unroll
;                 for (int c = 0; c < 4; ++c) { ov[2 * c] = bf_lo(fo[c]) + bf_lo(bo[c]); ov[2 * c + 1] = bf_hi(fo[c]) + bf_hi(bo[c]); }
; #pragma unroll
;                 for (int c = 0; c < 8; ++c) ss += ov[c] * ov[c];
;                 ss += __shfl_xor(ss, 1); ss += __shfl_xor(ss, 2); ss += __shfl_xor(ss, 4); ss += __shfl_xor(ss, 8);
	v_pk_add_f32 v[50:51], v[50:51], v[62:63]
	s_nop 0
	v_pk_mul_f32 v[50:51], v[50:51], s[34:35] op_sel_hi:[1,0]
	s_nop 0
	v_fma_f32 v50, -v51, v51, v50
	v_max_f32_e32 v50, 0, v50
	v_add_f32_e32 v50, 0x358637bd, v50
	v_mul_f32_e32 v62, 0x4b800000, v50
	v_cmp_gt_f32_e32 vcc, s3, v50
	v_sub_f32_e32 v55, v55, v51
	v_sub_f32_e32 v54, v54, v51
	v_cndmask_b32_e32 v50, v50, v62, vcc
	v_rsq_f32_e32 v50, v50
	v_sub_f32_e32 v56, v56, v51
	v_sub_f32_e32 v57, v57, v51
	v_sub_f32_e32 v58, v58, v51
	v_mul_f32_e32 v62, 0x45800000, v50
	v_cndmask_b32_e32 v50, v50, v62, vcc
	v_mul_f32_e32 v55, v55, v50
	v_mul_f32_e32 v54, v54, v50
	v_mul_f32_e32 v56, v56, v50
	v_mul_f32_e32 v57, v57, v50
	s_waitcnt vmcnt(17)
	v_fma_f32 v55, v31, v55, v27
	v_mul_f32_e32 v58, v58, v50
	v_fma_f32 v54, v30, v54, v26
	v_fma_f32 v56, v32, v56, v28
	v_fma_f32 v57, v33, v57, v29
	v_mul_f32_e32 v63, 0xbfb8aa3b, v55
	v_fma_f32 v58, v18, v58, v10
	v_mul_f32_e32 v62, 0xbfb8aa3b, v54
	v_mul_f32_e32 v116, 0xbfb8aa3b, v56
	v_mul_f32_e32 v117, 0xbfb8aa3b, v57
	v_exp_f32_e32 v63, v63
	v_mul_f32_e32 v124, 0xbfb8aa3b, v58
	v_exp_f32_e32 v62, v62
	v_exp_f32_e32 v116, v116
	v_exp_f32_e32 v117, v117
	v_exp_f32_e32 v124, v124
	v_add_f32_e32 v63, 1.0, v63
	v_add_f32_e32 v62, 1.0, v62
	v_add_f32_e32 v116, 1.0, v116
	v_add_f32_e32 v117, 1.0, v117
	v_rcp_f32_e32 v63, v63
	v_sub_f32_e32 v59, v59, v51
	v_add_f32_e32 v124, 1.0, v124
	v_rcp_f32_e32 v62, v62
	v_rcp_f32_e32 v116, v116
	v_rcp_f32_e32 v117, v117
	v_mul_f32_e32 v59, v59, v50
	v_rcp_f32_e32 v124, v124
	v_fma_f32 v59, v19, v59, v11
	v_mul_f32_e32 v125, 0xbfb8aa3b, v59
	v_mul_f32_e32 v55, v55, v63
	v_mul_f32_e32 v54, v54, v62
	v_mul_f32_e32 v56, v56, v116
	v_mul_f32_e32 v57, v57, v117
	v_mul_f32_e32 v49, v55, v49
	v_exp_f32_e32 v55, v125
	v_mul_f32_e32 v39, v54, v39
	v_mul_f32_e32 v54, v56, v114
	v_mul_f32_e32 v56, v57, v115
	v_mul_f32_e32 v57, v58, v124
	v_sub_f32_e32 v58, v61, v51
	v_sub_f32_e32 v51, v60, v51
	v_mul_f32_e32 v58, v58, v50
	v_mul_f32_e32 v50, v51, v50
	v_fma_f32 v58, v20, v58, v12
	v_fma_f32 v50, v21, v50, v13
	v_add_f32_e32 v55, 1.0, v55
	v_mul_f32_e32 v61, 0xbfb8aa3b, v58
	v_mul_f32_e32 v51, 0xbfb8aa3b, v50
	v_rcp_f32_e32 v55, v55
	v_exp_f32_e32 v61, v61
	v_exp_f32_e32 v51, v51
	v_mul_f32_e32 v57, v57, v64
	v_mul_f32_e32 v55, v59, v55
	v_add_f32_e32 v59, 1.0, v61
	v_add_f32_e32 v51, 1.0, v51
	v_rcp_f32_e32 v59, v59
	v_rcp_f32_e32 v51, v51
	v_mul_f32_e32 v52, v55, v52
	v_mul_f32_e32 v55, v58, v59
	v_mul_f32_e32 v50, v50, v51
	v_mul_f32_e32 v55, v55, v65
	v_mul_f32_e32 v53, v50, v53
	v_cvt_pk_bf16_f32 v50, v39, v49
	v_cvt_pk_bf16_f32 v51, v54, v56
	v_cvt_pk_bf16_f32 v52, v57, v52
	v_cvt_pk_bf16_f32 v53, v55, v53
	v_lshlrev_b64 v[54:55], 11, v[36:37]
	v_lshl_add_u64 v[62:63], v[84:85], 0, v[54:55]
	global_store_dwordx4 v[62:63], v[50:53], off offset:1024
	v_lshl_add_u64 v[58:59], v[72:73], 0, v[40:41]
	s_nop 0
	v_lshl_add_u64 v[50:51], s[68:69], 0, v[40:41]
	v_lshl_add_u64 v[50:51], v[50:51], 0, v[66:67]
	v_add_co_u32_e32 v60, vcc, s35, v50
	v_lshl_add_u64 v[40:41], v[74:75], 0, v[40:41]
	s_nop 0
	v_addc_co_u32_e32 v61, vcc, 0, v51, vcc
	s_waitcnt vmcnt(14)
	v_mov_b32_e32 v50, v192
	v_mov_b32_e32 v51, v193
	v_mov_b32_e32 v52, v194
	v_mov_b32_e32 v53, v195
	v_mov_b32_e32 v54, v196
	v_mov_b32_e32 v55, v197
	v_mov_b32_e32 v56, v198
	v_mov_b32_e32 v57, v199
	v_lshlrev_b32_e32 v36, 16, v50
	s_waitcnt vmcnt(13)
	v_mov_b32_e32 v58, v200
	v_mov_b32_e32 v59, v201
	v_mov_b32_e32 v60, v202
	v_mov_b32_e32 v61, v203
	v_lshlrev_b32_e32 v39, 16, v54
	v_and_b32_e32 v49, 0xffff0000, v50
	v_and_b32_e32 v124, 0xffff0000, v54
	v_lshlrev_b32_e32 v41, 16, v51
	v_lshlrev_b32_e32 v65, 16, v55
	v_and_b32_e32 v40, 0xffff0000, v51
	v_and_b32_e32 v64, 0xffff0000, v55
	v_add_f32_e32 v36, v36, v39
	v_lshlrev_b32_e32 v51, 16, v52
	v_and_b32_e32 v50, 0xffff0000, v52
	v_lshlrev_b32_e32 v115, 16, v53
	v_and_b32_e32 v114, 0xffff0000, v53
	v_add_f32_e32 v39, v49, v124
	v_pk_add_f32 v[52:53], v[64:65], v[40:41]
	v_mul_f32_e32 v49, v36, v36
	v_lshlrev_b32_e32 v55, 16, v56
	v_and_b32_e32 v54, 0xffff0000, v56
	v_pk_mul_f32 v[40:41], v[52:53], v[52:53]
	v_fmac_f32_e32 v49, v39, v39
	v_pk_add_f32 v[50:51], v[54:55], v[50:51]
	v_add_f32_e32 v41, v41, v49
	v_lshlrev_b32_e32 v117, 16, v57
	v_and_b32_e32 v116, 0xffff0000, v57
	v_pk_mul_f32 v[56:57], v[50:51], v[50:51]
	v_add_f32_e32 v40, v40, v41
	v_pk_add_f32 v[54:55], v[116:117], v[114:115]
	v_add_f32_e32 v40, v57, v40
	v_pk_mul_f32 v[64:65], v[54:55], v[54:55]
	v_add_f32_e32 v40, v56, v40
	v_add_f32_e32 v40, v65, v40
	v_add_f32_e32 v40, v64, v40
	ds_bpermute_b32 v41, v45, v40
	v_or_b32_e32 v49, 1, v123
	s_waitcnt lgkmcnt(0)
	v_add_f32_e32 v40, v40, v41
	ds_bpermute_b32 v41, v44, v40
	s_waitcnt lgkmcnt(0)
	v_add_f32_e32 v56, v40, v41
	ds_bpermute_b32 v57, v43, v56
	v_pk_mov_b32 v[40:41], v[112:113], v[112:113] op_sel:[1,0]
	s_waitcnt lgkmcnt(0)
	v_add_f32_e32 v56, v56, v57
	ds_bpermute_b32 v57, v42, v56
	s_waitcnt lgkmcnt(0)
; __device__ __forceinline__ unsigned cvt_pk_bf16(float lo, float hi) { unsigned r; asm volatile("v_cvt_pk_bf16_f32 %0, %1, %2" : "=v"(r) : "v"(lo), "v"(hi)); return r; }
; __device__ __forceinline__ float bf_lo(unsigned u) { return __uint_as_float(u << 16); }
; __device__ __forceinline__ float bf_hi(unsigned u) { return __uint_as_float(u & 0xffff0000u); }
; __device__ void conv_phase(LAS unsigned char* lds, const Params& p) {
;     ...
;                 float v[8]; float s1 = 0.f, s2 = 0.f;
; #pragma unroll
;                 for (int c = 0; c < 8; ++c) { v[c] = (half ? acc[lc * 2 + lr][c] : acc[lr * 2 + lc][c]) + cbv[c]; s1 += v[c]; s2 += v[c] * v[c]; }
; #pragma unroll
;                 for (int m = 32; m >= 1; m >>= 1) { s1 += __shfl_xor(s1, m); s2 += __shfl_xor(s2, m); }
;                 const float mean = s1 * (1.f / 512.f), var = fmaxf(s2 * (1.f / 512.f) - mean * mean, 0.f), rstd = rsqrtf(var + EPS);
;     ...
;                 ss += __shfl_xor(ss, 1); ss += __shfl_xor(ss, 2); ss += __shfl_xor(ss, 4); ss += __shfl_xor(ss, 8);
;                 const float rn = rsqrtf(ss * (1.f / 128.f) + EPS);
;                 const u32x4 gar = *(const u32x4*)(GAp + token * 512 + ch0);
;                 const float gav[8] = {bf_lo(gar[0]), bf_hi(gar[0]), bf_lo(gar[1]), bf_hi(gar[1]), bf_lo(gar[2]), bf_hi(gar[2]), bf_lo(gar[3]), bf_hi(gar[3])};
;                 float z[8];
; #pragma unroll
;                 for (int c = 0; c < 8; ++c) z[c] = ov[c] * rn * hg[c] * gav[c];
;                 u32x4 oa = {cvt_pk_bf16(z[0], z[1]), cvt_pk_bf16(z[2], z[3]), cvt_pk_bf16(z[4], z[5]), cvt_pk_bf16(z[6], z[7])};
;                 *(u32x4*)(A2 + token * 1024 + ch0) = oa;
	v_add_f32_e32 v56, v56, v57
	v_fmamk_f32 v56, v56, 0x3c000000, v120
	v_mul_f32_e32 v57, 0x4b800000, v56
	v_cmp_gt_f32_e32 vcc, s3, v56
	v_lshlrev_b32_e32 v64, 16, v58
	v_cndmask_b32_e32 v56, v56, v57, vcc
	v_rsq_f32_e32 v56, v56
	v_and_b32_e32 v58, 0xffff0000, v58
	v_lshlrev_b32_e32 v65, 16, v59
	v_and_b32_e32 v59, 0xffff0000, v59
	v_mul_f32_e32 v113, 0x45800000, v56
	v_cndmask_b32_e32 v56, v56, v113, vcc
	v_mul_f32_e32 v36, v36, v56
	v_mul_f32_e32 v39, v39, v56
	v_mul_f32_e32 v53, v53, v56
	v_mul_f32_e32 v52, v52, v56
	v_mul_f32_e32 v51, v51, v56
	v_mul_f32_e32 v50, v50, v56
	v_lshlrev_b32_e32 v112, 16, v60
	v_and_b32_e32 v57, 0xffff0000, v60
	v_mul_f32_e32 v55, v55, v56
	v_mul_f32_e32 v54, v54, v56
	v_mul_f32_e32 v36, v6, v36
	v_mul_f32_e32 v39, v7, v39
	v_mul_f32_e32 v53, v8, v53
	v_mul_f32_e32 v52, v9, v52
	v_mul_f32_e32 v51, v2, v51
	v_mul_f32_e32 v50, v3, v50
	v_lshlrev_b32_e32 v60, 16, v61
	v_and_b32_e32 v61, 0xffff0000, v61
	v_mul_f32_e32 v55, v4, v55
	v_mul_f32_e32 v54, v5, v54
	v_mul_f32_e32 v36, v36, v64
	v_mul_f32_e32 v39, v39, v58
	v_mul_f32_e32 v53, v53, v65
	v_mul_f32_e32 v52, v52, v59
	v_mul_f32_e32 v56, v51, v112
	v_mul_f32_e32 v57, v50, v57
	v_cvt_pk_bf16_f32 v50, v36, v39
	v_cvt_pk_bf16_f32 v51, v53, v52
	v_mul_f32_e32 v55, v55, v60
	v_mul_f32_e32 v54, v54, v61
	v_cvt_pk_bf16_f32 v52, v56, v57
	v_cvt_pk_bf16_f32 v53, v55, v54
	global_store_dwordx4 v[62:63], v[50:53], off
	v_cndmask_b32_e64 v61, v107, v95, s[6:7]
	v_cndmask_b32_e64 v60, v106, v94, s[6:7]
	v_cndmask_b32_e64 v51, v111, v99, s[6:7]
	v_cndmask_b32_e64 v50, v110, v98, s[6:7]
	v_pk_add_f32 v[54:55], v[50:51], v[22:23]
	v_cndmask_b32_e64 v53, v109, v97, s[6:7]
	v_add_f32_e32 v36, 0, v54
	v_cndmask_b32_e64 v52, v108, v96, s[6:7]
	v_add_f32_e32 v39, v55, v36
	v_mul_f32_e32 v36, v55, v55
	v_pk_add_f32 v[56:57], v[52:53], v[24:25]
	v_pk_fma_f32 v[50:51], v[54:55], v[54:55], v[36:37] op_sel_hi:[1,1,0]
	v_add_f32_e32 v36, v56, v39
	v_pk_fma_f32 v[50:51], v[56:57], v[56:57], v[50:51]
	v_add_f32_e32 v39, v57, v36
	v_mul_f32_e32 v36, v57, v57
	v_pk_add_f32 v[58:59], v[36:37], v[50:51] op_sel_hi:[0,1]
	v_or_b32_e32 v36, v48, v49
	v_lshlrev_b64 v[62:63], 10, v[36:37]
	v_lshl_add_u64 v[50:51], v[70:71], 0, v[62:63]
	s_waitcnt vmcnt(13)
	v_mov_b32_e32 v50, v204
	v_mov_b32_e32 v51, v205
	v_mov_b32_e32 v52, v206
	v_mov_b32_e32 v53, v207
	v_pk_add_f32 v[60:61], v[60:61], v[14:15]
	v_or_b32_e32 v48, 64, v48
	v_pk_fma_f32 v[58:59], v[60:61], v[60:61], v[58:59]
	v_mul_f32_e32 v64, v61, v61
	v_pk_add_f32 v[58:59], v[64:65], v[58:59] op_sel_hi:[0,1]
	v_cndmask_b32_e64 v65, v41, v122, s[6:7]
	v_cndmask_b32_e64 v64, v40, v121, s[6:7]
	v_pk_add_f32 v[112:113], v[64:65], v[16:17] op_sel:[0,1] op_sel_hi:[1,0]
	v_add_f32_e32 v39, v60, v39
	v_pk_mul_f32 v[114:115], v[112:113], v[112:113]
	v_mov_b32_e32 v116, v64
	v_mov_b32_e32 v117, v61
	v_pk_add_f32 v[116:117], v[116:117], v[38:39]
	v_pk_mov_b32 v[64:65], v[114:115], v[64:65] op_sel:[1,0]
	v_mov_b32_e32 v59, v17
	v_pk_add_f32 v[58:59], v[64:65], v[58:59]
	v_pk_mul_f32 v[64:65], v[112:113], v[116:117]
	v_pk_add_f32 v[114:115], v[112:113], v[116:117]
	v_cndmask_b32_e64 v41, v122, v41, s[6:7]
	v_mov_b32_e32 v65, v115
	v_pk_add_f32 v[58:59], v[64:65], v[58:59]
	ds_bpermute_b32 v65, v46, v59
	ds_bpermute_b32 v64, v46, v58
	v_cndmask_b32_e64 v40, v121, v40, s[6:7]
	s_waitcnt lgkmcnt(0)
	v_pk_add_f32 v[58:59], v[58:59], v[64:65]
	ds_bpermute_b32 v65, v47, v59
	ds_bpermute_b32 v64, v47, v58
	s_waitcnt lgkmcnt(0)
	v_pk_add_f32 v[58:59], v[58:59], v[64:65]
	ds_bpermute_b32 v65, v42, v59
	ds_bpermute_b32 v64, v42, v58
	s_waitcnt lgkmcnt(0)
	v_pk_add_f32 v[58:59], v[58:59], v[64:65]
	ds_bpermute_b32 v65, v43, v59
	ds_bpermute_b32 v64, v43, v58
	s_waitcnt lgkmcnt(0)
	v_pk_add_f32 v[58:59], v[58:59], v[64:65]
	ds_bpermute_b32 v65, v44, v59
	ds_bpermute_b32 v64, v44, v58
	s_waitcnt lgkmcnt(0)
	v_pk_add_f32 v[58:59], v[58:59], v[64:65]
	ds_bpermute_b32 v65, v45, v59
	ds_bpermute_b32 v64, v45, v58
	s_waitcnt lgkmcnt(0)
	v_pk_add_f32 v[58:59], v[58:59], v[64:65]
	s_nop 0
	v_pk_mul_f32 v[58:59], v[58:59], s[34:35] op_sel_hi:[1,0]
	v_lshlrev_b32_e32 v64, 16, v50
	v_fma_f32 v39, -v59, v59, v58
	v_max_f32_e32 v39, 0, v39
	v_add_f32_e32 v39, 0x358637bd, v39
	v_mul_f32_e32 v58, 0x4b800000, v39
	v_cmp_gt_f32_e32 vcc, s3, v39
	v_sub_f32_e32 v54, v54, v59
	v_sub_f32_e32 v55, v55, v59
	v_cndmask_b32_e32 v39, v39, v58, vcc
	v_rsq_f32_e32 v39, v39
	v_sub_f32_e32 v56, v56, v59
	v_sub_f32_e32 v57, v57, v59
	v_sub_f32_e32 v60, v60, v59
	v_mul_f32_e32 v58, 0x45800000, v39
	v_cndmask_b32_e32 v39, v39, v58, vcc
	v_mul_f32_e32 v54, v54, v39
	v_fma_f32 v54, v30, v54, v26
	v_mul_f32_e32 v58, 0xbfb8aa3b, v54
	v_exp_f32_e32 v58, v58
	v_mul_f32_e32 v55, v55, v39
	v_fma_f32 v55, v31, v55, v27
	v_mul_f32_e32 v115, 0xbfb8aa3b, v55
	v_add_f32_e32 v58, 1.0, v58
	v_exp_f32_e32 v115, v115
	v_rcp_f32_e32 v58, v58
	v_mul_f32_e32 v56, v56, v39
	v_mul_f32_e32 v57, v57, v39
	v_add_f32_e32 v115, 1.0, v115
	v_mul_f32_e32 v54, v54, v58
	v_fma_f32 v56, v32, v56, v28
	v_fma_f32 v57, v33, v57, v29
	v_rcp_f32_e32 v115, v115
	v_mul_f32_e32 v54, v54, v64
	v_mul_f32_e32 v58, 0xbfb8aa3b, v56
	v_mul_f32_e32 v64, 0xbfb8aa3b, v57
	v_exp_f32_e32 v58, v58
	v_exp_f32_e32 v64, v64
	v_mul_f32_e32 v60, v60, v39
	v_and_b32_e32 v50, 0xffff0000, v50
	v_mul_f32_e32 v55, v55, v115
	v_fma_f32 v60, v18, v60, v10
	v_mul_f32_e32 v50, v55, v50
	v_add_f32_e32 v55, 1.0, v58
	v_add_f32_e32 v58, 1.0, v64
	v_mul_f32_e32 v64, 0xbfb8aa3b, v60
	v_rcp_f32_e32 v55, v55
	v_rcp_f32_e32 v58, v58
	v_exp_f32_e32 v64, v64
	v_lshlrev_b32_e32 v65, 16, v51
	v_mul_f32_e32 v55, v56, v55
	v_mul_f32_e32 v56, v57, v58
	v_add_f32_e32 v57, 1.0, v64
; __device__ __forceinline__ unsigned cvt_pk_bf16(float lo, float hi) { unsigned r; asm volatile("v_cvt_pk_bf16_f32 %0, %1, %2" : "=v"(r) : "v"(lo), "v"(hi)); return r; }
; __device__ __forceinline__ float bf_lo(unsigned u) { return __uint_as_float(u << 16); }
; __device__ __forceinline__ float bf_hi(unsigned u) { return __uint_as_float(u & 0xffff0000u); }
; __device__ __forceinline__ float siluf_(float v) { return v * __builtin_amdgcn_rcpf(1.f + __expf(-v)); }
; __device__ void conv_phase(LAS unsigned char* lds, const Params& p) {
;     ...
;                 float v[8]; float s1 = 0.f, s2 = 0.f;
; #pragma unroll
;                 for (int c = 0; c < 8; ++c) { v[c] = (half ? acc[lc * 2 + lr][c] : acc[lr * 2 + lc][c]) + cbv[c]; s1 += v[c]; s2 += v[c] * v[c]; }
; #pragma unroll
;                 for (int m = 32; m >= 1; m >>= 1) { s1 += __shfl_xor(s1, m); s2 += __shfl_xor(s2, m); }
;     ...
;                 for (int c = 0; c < 8; ++c) { const float t = (v[c] - mean) * rstd * lg[c] + lbv[c]; y[c] = siluf_(t) * gbv[c]; }
;                 u32x4 ob = {cvt_pk_bf16(y[0], y[1]), cvt_pk_bf16(y[2], y[3]), cvt_pk_bf16(y[4], y[5]), cvt_pk_bf16(y[6], y[7])};
;                 *(u32x4*)(A2 + token * 1024 + 512 + ch0) = ob;
;                 const u32x4 fo = *(const u32x4*)(O + token * 512 + ch0), bo = *(const u32x4*)(O + ((size_t)NLAT + token) * 512 + ch0);
;                 float ov[8]; float ss = 0.f;
; #pragma unroll
;                 for (int c = 0; c < 4; ++c) { ov[2 * c] = bf_lo(fo[c]) + bf_lo(bo[c]); ov[2 * c + 1] = bf_hi(fo[c]) + bf_hi(bo[c]); }
; #pragma unroll
;                 for (int c = 0; c < 8; ++c) ss += ov[c] * ov[c];
;                 ss += __shfl_xor(ss, 1); ss += __shfl_xor(ss, 2); ss += __shfl_xor(ss, 4); ss += __shfl_xor(ss, 8);
	v_sub_f32_e32 v58, v61, v59
	v_rcp_f32_e32 v57, v57
	v_mul_f32_e32 v58, v58, v39
	v_fma_f32 v58, v19, v58, v11
	v_mul_f32_e32 v61, 0xbfb8aa3b, v58
	v_and_b32_e32 v51, 0xffff0000, v51
	v_exp_f32_e32 v61, v61
	v_mul_f32_e32 v51, v56, v51
	v_mul_f32_e32 v56, v60, v57
	v_sub_f32_e32 v60, v113, v59
	v_sub_f32_e32 v59, v112, v59
	v_mul_f32_e32 v60, v60, v39
	v_mul_f32_e32 v39, v59, v39
	v_fma_f32 v60, v20, v60, v12
	v_fma_f32 v39, v21, v39, v13
	v_add_f32_e32 v57, 1.0, v61
	v_mul_f32_e32 v61, 0xbfb8aa3b, v60
	v_mul_f32_e32 v59, 0xbfb8aa3b, v39
	v_rcp_f32_e32 v57, v57
	v_exp_f32_e32 v61, v61
	v_exp_f32_e32 v59, v59
	v_mul_f32_e32 v55, v55, v65
	v_mul_f32_e32 v57, v58, v57
	v_add_f32_e32 v58, 1.0, v61
	v_add_f32_e32 v59, 1.0, v59
	v_rcp_f32_e32 v58, v58
	v_rcp_f32_e32 v59, v59
	v_lshlrev_b32_e32 v114, 16, v52
	v_and_b32_e32 v52, 0xffff0000, v52
	v_cvt_pk_bf16_f32 v50, v54, v50
	v_cvt_pk_bf16_f32 v51, v55, v51
	v_lshlrev_b64 v[54:55], 11, v[36:37]
	v_lshlrev_b32_e32 v116, 16, v53
	v_and_b32_e32 v53, 0xffff0000, v53
	v_mul_f32_e32 v52, v57, v52
	v_mul_f32_e32 v57, v60, v58
	v_mul_f32_e32 v39, v39, v59
	v_lshl_add_u64 v[64:65], v[84:85], 0, v[54:55]
	v_mul_f32_e32 v56, v56, v114
	v_mul_f32_e32 v57, v57, v116
	v_mul_f32_e32 v39, v39, v53
	v_cvt_pk_bf16_f32 v52, v56, v52
	v_cvt_pk_bf16_f32 v53, v57, v39
	global_store_dwordx4 v[64:65], v[50:53], off offset:1024
	v_lshl_add_u64 v[58:59], v[72:73], 0, v[62:63]
	s_nop 0
	v_lshl_add_u64 v[50:51], s[68:69], 0, v[62:63]
	v_lshl_add_u64 v[50:51], v[50:51], 0, v[66:67]
	v_add_co_u32_e32 v60, vcc, s35, v50
	s_nop 1
	v_addc_co_u32_e32 v61, vcc, 0, v51, vcc
	s_waitcnt vmcnt(12)
	v_mov_b32_e32 v50, v208
	v_mov_b32_e32 v51, v209
	v_mov_b32_e32 v52, v210
	v_mov_b32_e32 v53, v211
	v_mov_b32_e32 v54, v212
	v_mov_b32_e32 v55, v213
	v_mov_b32_e32 v56, v214
	v_mov_b32_e32 v57, v215
	v_lshl_add_u64 v[58:59], v[74:75], 0, v[62:63]
	s_waitcnt vmcnt(11)
	v_mov_b32_e32 v58, v216
	v_mov_b32_e32 v59, v217
	v_mov_b32_e32 v60, v218
	v_mov_b32_e32 v61, v219
	v_lshlrev_b32_e32 v36, 16, v50
	v_lshlrev_b32_e32 v39, 16, v54
	v_add_f32_e32 v36, v36, v39
	v_and_b32_e32 v39, 0xffff0000, v50
	v_and_b32_e32 v50, 0xffff0000, v54
	v_lshlrev_b32_e32 v63, 16, v51
	v_lshlrev_b32_e32 v113, 16, v55
	v_and_b32_e32 v62, 0xffff0000, v51
	v_and_b32_e32 v112, 0xffff0000, v55
	v_lshlrev_b32_e32 v115, 16, v53
	v_lshlrev_b32_e32 v117, 16, v57
	v_and_b32_e32 v114, 0xffff0000, v53
	v_and_b32_e32 v116, 0xffff0000, v57
	v_add_f32_e32 v39, v39, v50
	v_lshlrev_b32_e32 v51, 16, v52
	v_and_b32_e32 v50, 0xffff0000, v52
	v_pk_add_f32 v[52:53], v[112:113], v[62:63]
	v_pk_add_f32 v[62:63], v[116:117], v[114:115]
	v_mul_f32_e32 v114, v36, v36
	v_lshlrev_b32_e32 v55, 16, v56
	v_and_b32_e32 v54, 0xffff0000, v56
	v_pk_mul_f32 v[56:57], v[52:53], v[52:53]
	v_fmac_f32_e32 v114, v39, v39
	v_pk_add_f32 v[50:51], v[54:55], v[50:51]
	v_add_f32_e32 v57, v57, v114
	v_pk_mul_f32 v[54:55], v[50:51], v[50:51]
	v_add_f32_e32 v56, v56, v57
	v_add_f32_e32 v55, v55, v56
	v_pk_mul_f32 v[112:113], v[62:63], v[62:63]
	v_add_f32_e32 v54, v54, v55
	v_add_f32_e32 v54, v113, v54
	v_add_f32_e32 v54, v112, v54
	ds_bpermute_b32 v55, v45, v54
	v_and_b32_e32 v56, 0xffff0000, v58
	v_lshlrev_b32_e32 v57, 16, v59
	v_lshlrev_b32_e32 v112, 16, v61
	v_and_b32_e32 v61, 0xffff0000, v61
	s_waitcnt lgkmcnt(0)
	v_add_f32_e32 v54, v54, v55
	ds_bpermute_b32 v55, v44, v54
	s_waitcnt lgkmcnt(0)
	v_add_f32_e32 v54, v54, v55
	ds_bpermute_b32 v55, v43, v54
	s_waitcnt lgkmcnt(0)
	v_add_f32_e32 v54, v54, v55
	ds_bpermute_b32 v55, v42, v54
	s_waitcnt lgkmcnt(0)
	v_add_f32_e32 v54, v54, v55
	v_fmamk_f32 v54, v54, 0x3c000000, v120
	v_mul_f32_e32 v55, 0x4b800000, v54
	v_cmp_gt_f32_e32 vcc, s3, v54
	s_nop 1
	v_cndmask_b32_e32 v54, v54, v55, vcc
	v_rsq_f32_e32 v54, v54
	s_nop 0
	v_mul_f32_e32 v55, 0x45800000, v54
	v_cndmask_b32_e32 v54, v54, v55, vcc
	v_mul_f32_e32 v39, v39, v54
	v_mul_f32_e32 v50, v50, v54
	v_lshlrev_b32_e32 v55, 16, v58
	v_and_b32_e32 v58, 0xffff0000, v59
	v_lshlrev_b32_e32 v59, 16, v60
	v_and_b32_e32 v60, 0xffff0000, v60
	v_mul_f32_e32 v39, v7, v39
	v_mul_f32_e32 v50, v3, v50
	v_mul_f32_e32 v39, v39, v56
	v_mul_f32_e32 v53, v53, v54
	v_mul_f32_e32 v56, v50, v60
	v_mul_f32_e32 v50, v63, v54
	v_mul_f32_e32 v36, v36, v54
	v_mul_f32_e32 v53, v8, v53
	v_mul_f32_e32 v50, v4, v50
	v_mul_f32_e32 v36, v6, v36
	v_mul_f32_e32 v53, v53, v57
	v_mul_f32_e32 v57, v50, v112
	v_mul_f32_e32 v50, v62, v54
	v_mul_f32_e32 v36, v36, v55
	v_mul_f32_e32 v50, v5, v50
	v_mul_f32_e32 v52, v52, v54
	v_mul_f32_e32 v51, v51, v54
	v_mul_f32_e32 v54, v50, v61
	v_cvt_pk_bf16_f32 v50, v36, v39
	v_cndmask_b32_e64 v36, v98, v110, s[6:7]
	v_add_f32_e32 v110, v36, v22
	v_cndmask_b32_e64 v39, v99, v111, s[6:7]
	v_add_f32_e32 v36, 0, v110
	v_add_f32_e32 v111, v39, v23
	v_cndmask_b32_e64 v39, v96, v108, s[6:7]
	v_add_f32_e32 v36, v111, v36
	v_add_f32_e32 v108, v39, v24
	v_mul_f32_e32 v52, v9, v52
	v_mul_f32_e32 v51, v2, v51
	v_add_f32_e32 v39, v108, v36
	v_or_b32_e32 v36, v48, v123
	v_mul_f32_e32 v52, v52, v58
	v_mul_f32_e32 v55, v51, v59
	v_cvt_pk_bf16_f32 v51, v53, v52
	v_lshlrev_b64 v[58:59], 10, v[36:37]
	v_cvt_pk_bf16_f32 v52, v55, v56
	v_cvt_pk_bf16_f32 v53, v57, v54
	global_store_dwordx4 v[64:65], v[50:53], off
	v_mul_f32_e32 v54, v111, v111
	v_fmac_f32_e32 v54, v110, v110
	v_lshl_add_u64 v[50:51], v[70:71], 0, v[58:59]
	s_waitcnt vmcnt(11)
; __device__ __forceinline__ unsigned cvt_pk_bf16(float lo, float hi) { unsigned r; asm volatile("v_cvt_pk_bf16_f32 %0, %1, %2" : "=v"(r) : "v"(lo), "v"(hi)); return r; }
; __device__ __forceinline__ float bf_lo(unsigned u) { return __uint_as_float(u << 16); }
; __device__ __forceinline__ float bf_hi(unsigned u) { return __uint_as_float(u & 0xffff0000u); }
; __device__ __forceinline__ float siluf_(float v) { return v * __builtin_amdgcn_rcpf(1.f + __expf(-v)); }
; __device__ void conv_phase(LAS unsigned char* lds, const Params& p) {
;     ...
;                 float v[8]; float s1 = 0.f, s2 = 0.f;
; #pragma unroll
;                 for (int c = 0; c < 8; ++c) { v[c] = (half ? acc[lc * 2 + lr][c] : acc[lr * 2 + lc][c]) + cbv[c]; s1 += v[c]; s2 += v[c] * v[c]; }
; #pragma unroll
;                 for (int m = 32; m >= 1; m >>= 1) { s1 += __shfl_xor(s1, m); s2 += __shfl_xor(s2, m); }
;                 const float mean = s1 * (1.f / 512.f), var = fmaxf(s2 * (1.f / 512.f) - mean * mean, 0.f), rstd = rsqrtf(var + EPS);
;                 const u32x4 gbr = *(const u32x4*)(GBp + token * 512 + ch0);
;                 const float gbv[8] = {bf_lo(gbr[0]), bf_hi(gbr[0]), bf_lo(gbr[1]), bf_hi(gbr[1]), bf_lo(gbr[2]), bf_hi(gbr[2]), bf_lo(gbr[3]), bf_hi(gbr[3])};
;                 float y[8];
; #pragma unroll
;                 for (int c = 0; c < 8; ++c) { const float t = (v[c] - mean) * rstd * lg[c] + lbv[c]; y[c] = siluf_(t) * gbv[c]; }
;                 u32x4 ob = {cvt_pk_bf16(y[0], y[1]), cvt_pk_bf16(y[2], y[3]), cvt_pk_bf16(y[4], y[5]), cvt_pk_bf16(y[6], y[7])};
;                 *(u32x4*)(A2 + token * 1024 + 512 + ch0) = ob;
;                 const u32x4 fo = *(const u32x4*)(O + token * 512 + ch0), bo = *(const u32x4*)(O + ((size_t)NLAT + token) * 512 + ch0);
	v_mov_b32_e32 v50, v220
	v_mov_b32_e32 v51, v221
	v_mov_b32_e32 v52, v222
	v_mov_b32_e32 v53, v223
	v_cndmask_b32_e64 v55, v97, v109, s[6:7]
	v_fmac_f32_e32 v54, v108, v108
	v_add_f32_e32 v109, v55, v25
	v_cndmask_b32_e64 v55, v94, v106, s[6:7]
	v_add_f32_e32 v39, v109, v39
	v_fmac_f32_e32 v54, v109, v109
	v_add_f32_e32 v106, v55, v14
	v_cndmask_b32_e64 v55, v95, v107, s[6:7]
	v_pk_add_f32 v[60:61], v[40:41], v[16:17] op_sel:[0,1] op_sel_hi:[1,0]
	v_add_f32_e32 v39, v106, v39
	v_fmac_f32_e32 v54, v106, v106
	v_add_f32_e32 v57, v55, v15
	v_pk_mul_f32 v[62:63], v[60:61], v[60:61]
	v_mov_b32_e32 v56, v40
	v_fmac_f32_e32 v54, v57, v57
	v_pk_add_f32 v[64:65], v[56:57], v[38:39]
	v_pk_mov_b32 v[40:41], v[62:63], v[40:41] op_sel:[1,0]
	v_mov_b32_e32 v55, v17
	v_pk_add_f32 v[40:41], v[40:41], v[54:55]
	v_pk_mul_f32 v[54:55], v[60:61], v[64:65]
	v_pk_add_f32 v[62:63], v[60:61], v[64:65]
	v_pk_add_f32 v[22:23], v[104:105], v[22:23]
	v_mov_b32_e32 v55, v63
	v_pk_add_f32 v[40:41], v[54:55], v[40:41]
	ds_bpermute_b32 v55, v46, v41
	ds_bpermute_b32 v54, v46, v40
	v_pk_add_f32 v[24:25], v[102:103], v[24:25]
	v_pk_add_f32 v[14:15], v[100:101], v[14:15]
	s_waitcnt lgkmcnt(0)
	v_pk_add_f32 v[40:41], v[40:41], v[54:55]
	ds_bpermute_b32 v55, v47, v41
	ds_bpermute_b32 v54, v47, v40
	s_waitcnt lgkmcnt(0)
	v_pk_add_f32 v[40:41], v[40:41], v[54:55]
	ds_bpermute_b32 v55, v42, v41
	ds_bpermute_b32 v54, v42, v40
	s_waitcnt lgkmcnt(0)
	v_pk_add_f32 v[40:41], v[40:41], v[54:55]
	ds_bpermute_b32 v55, v43, v41
	ds_bpermute_b32 v54, v43, v40
	s_waitcnt lgkmcnt(0)
	v_pk_add_f32 v[40:41], v[40:41], v[54:55]
	ds_bpermute_b32 v55, v44, v41
	ds_bpermute_b32 v54, v44, v40
	s_waitcnt lgkmcnt(0)
	v_pk_add_f32 v[40:41], v[40:41], v[54:55]
	ds_bpermute_b32 v55, v45, v41
	ds_bpermute_b32 v54, v45, v40
	s_waitcnt lgkmcnt(0)
	v_pk_add_f32 v[40:41], v[40:41], v[54:55]
	s_nop 0
	v_pk_mul_f32 v[40:41], v[40:41], s[34:35] op_sel_hi:[1,0]
	v_lshlrev_b32_e32 v54, 16, v51
	v_fma_f32 v39, -v41, v41, v40
	v_max_f32_e32 v39, 0, v39
	v_add_f32_e32 v39, 0x358637bd, v39
	v_mul_f32_e32 v40, 0x4b800000, v39
	v_cmp_gt_f32_e32 vcc, s3, v39
	v_sub_f32_e32 v56, v110, v41
	v_sub_f32_e32 v63, v111, v41
	v_cndmask_b32_e32 v39, v39, v40, vcc
	v_rsq_f32_e32 v39, v39
	v_sub_f32_e32 v106, v106, v41
	v_sub_f32_e32 v57, v57, v41
	v_sub_f32_e32 v61, v61, v41
	v_mul_f32_e32 v40, 0x45800000, v39
	v_cndmask_b32_e32 v39, v39, v40, vcc
	v_mul_f32_e32 v56, v56, v39
	v_fma_f32 v56, v30, v56, v26
	v_mul_f32_e32 v63, v63, v39
	v_mul_f32_e32 v62, 0xbfb8aa3b, v56
	v_fma_f32 v63, v31, v63, v27
	v_exp_f32_e32 v62, v62
	v_mul_f32_e32 v64, 0xbfb8aa3b, v63
	v_exp_f32_e32 v64, v64
	v_lshlrev_b32_e32 v40, 16, v50
	v_add_f32_e32 v62, 1.0, v62
	v_rcp_f32_e32 v62, v62
	v_add_f32_e32 v64, 1.0, v64
	v_rcp_f32_e32 v64, v64
	v_mul_f32_e32 v106, v106, v39
	v_mul_f32_e32 v56, v56, v62
	v_mul_f32_e32 v40, v56, v40
	v_mul_f32_e32 v56, v63, v64
	v_sub_f32_e32 v62, v108, v41
	v_sub_f32_e32 v64, v109, v41
	v_mul_f32_e32 v62, v62, v39
	v_mul_f32_e32 v64, v64, v39
	v_fma_f32 v62, v32, v62, v28
	v_fma_f32 v64, v33, v64, v29
	v_mul_f32_e32 v63, 0xbfb8aa3b, v62
	v_mul_f32_e32 v107, 0xbfb8aa3b, v64
	v_exp_f32_e32 v63, v63
	v_exp_f32_e32 v107, v107
	v_and_b32_e32 v50, 0xffff0000, v50
	v_fma_f32 v106, v18, v106, v10
	v_mul_f32_e32 v50, v56, v50
	v_add_f32_e32 v56, 1.0, v63
	v_add_f32_e32 v63, 1.0, v107
	v_mul_f32_e32 v107, 0xbfb8aa3b, v106
	v_rcp_f32_e32 v56, v56
	v_exp_f32_e32 v107, v107
	v_rcp_f32_e32 v63, v63
	v_mul_f32_e32 v57, v57, v39
	v_mul_f32_e32 v56, v62, v56
	v_add_f32_e32 v62, 1.0, v107
	v_fma_f32 v57, v19, v57, v11
	v_mul_f32_e32 v54, v56, v54
	v_mul_f32_e32 v56, v64, v63
	v_rcp_f32_e32 v62, v62
	v_mul_f32_e32 v63, 0xbfb8aa3b, v57
	v_exp_f32_e32 v63, v63
	v_sub_f32_e32 v41, v60, v41
	v_mul_f32_e32 v61, v61, v39
	v_mul_f32_e32 v39, v41, v39
	v_and_b32_e32 v51, 0xffff0000, v51
	v_fma_f32 v39, v21, v39, v13
	v_lshlrev_b32_e32 v55, 16, v52
	v_mul_f32_e32 v51, v56, v51
	v_mul_f32_e32 v56, v106, v62
	v_fma_f32 v61, v20, v61, v12
	v_mul_f32_e32 v41, 0xbfb8aa3b, v39
	v_mul_f32_e32 v55, v56, v55
	v_add_f32_e32 v56, 1.0, v63
	v_mul_f32_e32 v62, 0xbfb8aa3b, v61
	v_exp_f32_e32 v41, v41
	v_rcp_f32_e32 v56, v56
	v_exp_f32_e32 v62, v62
	v_and_b32_e32 v52, 0xffff0000, v52
	v_add_f32_e32 v41, 1.0, v41
	v_mul_f32_e32 v56, v57, v56
	v_add_f32_e32 v57, 1.0, v62
	v_rcp_f32_e32 v41, v41
	v_rcp_f32_e32 v57, v57
	v_cvt_pk_bf16_f32 v50, v40, v50
	v_lshlrev_b32_e32 v65, 16, v53
	v_mul_f32_e32 v39, v39, v41
	v_lshlrev_b64 v[40:41], 11, v[36:37]
	v_and_b32_e32 v53, 0xffff0000, v53
	v_mul_f32_e32 v52, v56, v52
	v_mul_f32_e32 v56, v61, v57
	v_cvt_pk_bf16_f32 v51, v54, v51
	v_lshl_add_u64 v[40:41], v[84:85], 0, v[40:41]
	v_mul_f32_e32 v56, v56, v65
	v_mul_f32_e32 v39, v39, v53
	v_cvt_pk_bf16_f32 v52, v55, v52
	v_cvt_pk_bf16_f32 v53, v56, v39
	global_store_dwordx4 v[40:41], v[50:53], off offset:1024
	v_lshl_add_u64 v[60:61], v[72:73], 0, v[58:59]
	s_nop 0
	v_lshl_add_u64 v[50:51], s[68:69], 0, v[58:59]
	v_lshl_add_u64 v[50:51], v[50:51], 0, v[66:67]
	v_add_co_u32_e32 v62, vcc, s35, v50
	v_lshl_add_u64 v[58:59], v[74:75], 0, v[58:59]
	s_nop 0
	v_addc_co_u32_e32 v63, vcc, 0, v51, vcc
	s_waitcnt vmcnt(10)
	v_mov_b32_e32 v50, v224
	v_mov_b32_e32 v51, v225
	v_mov_b32_e32 v52, v226
	v_mov_b32_e32 v53, v227
	v_mov_b32_e32 v54, v228
	v_mov_b32_e32 v55, v229
	v_mov_b32_e32 v56, v230
	v_mov_b32_e32 v57, v231
	v_lshlrev_b32_e32 v36, 16, v50
	s_waitcnt vmcnt(9)
; __device__ __forceinline__ unsigned cvt_pk_bf16(float lo, float hi) { unsigned r; asm volatile("v_cvt_pk_bf16_f32 %0, %1, %2" : "=v"(r) : "v"(lo), "v"(hi)); return r; }
; __device__ __forceinline__ float bf_lo(unsigned u) { return __uint_as_float(u << 16); }
; __device__ __forceinline__ float bf_hi(unsigned u) { return __uint_as_float(u & 0xffff0000u); }
; __device__ void conv_phase(LAS unsigned char* lds, const Params& p) {
;     ...
;                 float v[8]; float s1 = 0.f, s2 = 0.f;
; #pragma unroll
;                 for (int c = 0; c < 8; ++c) { v[c] = (half ? acc[lc * 2 + lr][c] : acc[lr * 2 + lc][c]) + cbv[c]; s1 += v[c]; s2 += v[c] * v[c]; }
; #pragma unroll
;                 for (int m = 32; m >= 1; m >>= 1) { s1 += __shfl_xor(s1, m); s2 += __shfl_xor(s2, m); }
;     ...
;                 const u32x4 fo = *(const u32x4*)(O + token * 512 + ch0), bo = *(const u32x4*)(O + ((size_t)NLAT + token) * 512 + ch0);
;                 float ov[8]; float ss = 0.f;
; #pragma unroll
;                 for (int c = 0; c < 4; ++c) { ov[2 * c] = bf_lo(fo[c]) + bf_lo(bo[c]); ov[2 * c + 1] = bf_hi(fo[c]) + bf_hi(bo[c]); }
; #pragma unroll
;                 for (int c = 0; c < 8; ++c) ss += ov[c] * ov[c];
;                 ss += __shfl_xor(ss, 1); ss += __shfl_xor(ss, 2); ss += __shfl_xor(ss, 4); ss += __shfl_xor(ss, 8);
;                 const float rn = rsqrtf(ss * (1.f / 128.f) + EPS);
;                 const u32x4 gar = *(const u32x4*)(GAp + token * 512 + ch0);
;                 const float gav[8] = {bf_lo(gar[0]), bf_hi(gar[0]), bf_lo(gar[1]), bf_hi(gar[1]), bf_lo(gar[2]), bf_hi(gar[2]), bf_lo(gar[3]), bf_hi(gar[3])};
;                 float z[8];
; #pragma unroll
;                 for (int c = 0; c < 8; ++c) z[c] = ov[c] * rn * hg[c] * gav[c];
;                 u32x4 oa = {cvt_pk_bf16(z[0], z[1]), cvt_pk_bf16(z[2], z[3]), cvt_pk_bf16(z[4], z[5]), cvt_pk_bf16(z[6], z[7])};
;                 *(u32x4*)(A2 + token * 1024 + ch0) = oa;
	v_mov_b32_e32 v58, v232
	v_mov_b32_e32 v59, v233
	v_mov_b32_e32 v60, v234
	v_mov_b32_e32 v61, v235
	v_lshlrev_b32_e32 v39, 16, v54
	v_add_f32_e32 v36, v36, v39
	v_and_b32_e32 v39, 0xffff0000, v50
	v_and_b32_e32 v50, 0xffff0000, v54
	v_lshlrev_b32_e32 v63, 16, v51
	v_lshlrev_b32_e32 v65, 16, v55
	v_and_b32_e32 v62, 0xffff0000, v51
	v_and_b32_e32 v64, 0xffff0000, v55
	v_lshlrev_b32_e32 v107, 16, v53
	v_lshlrev_b32_e32 v109, 16, v57
	v_and_b32_e32 v106, 0xffff0000, v53
	v_and_b32_e32 v108, 0xffff0000, v57
	v_add_f32_e32 v39, v39, v50
	v_lshlrev_b32_e32 v51, 16, v52
	v_and_b32_e32 v50, 0xffff0000, v52
	v_pk_add_f32 v[52:53], v[64:65], v[62:63]
	v_pk_add_f32 v[62:63], v[108:109], v[106:107]
	v_mul_f32_e32 v106, v36, v36
	v_lshlrev_b32_e32 v55, 16, v56
	v_and_b32_e32 v54, 0xffff0000, v56
	v_pk_mul_f32 v[56:57], v[52:53], v[52:53]
	v_fmac_f32_e32 v106, v39, v39
	v_pk_add_f32 v[50:51], v[54:55], v[50:51]
	v_add_f32_e32 v57, v57, v106
	v_pk_mul_f32 v[54:55], v[50:51], v[50:51]
	v_add_f32_e32 v56, v56, v57
	v_add_f32_e32 v55, v55, v56
	v_pk_mul_f32 v[64:65], v[62:63], v[62:63]
	v_add_f32_e32 v54, v54, v55
	v_add_f32_e32 v54, v65, v54
	v_add_f32_e32 v54, v64, v54
	ds_bpermute_b32 v55, v45, v54
	s_waitcnt lgkmcnt(0)
	v_add_f32_e32 v54, v54, v55
	ds_bpermute_b32 v55, v44, v54
	s_waitcnt lgkmcnt(0)
	v_add_f32_e32 v54, v54, v55
	ds_bpermute_b32 v55, v43, v54
	s_waitcnt lgkmcnt(0)
	v_add_f32_e32 v54, v54, v55
	ds_bpermute_b32 v55, v42, v54
	s_waitcnt lgkmcnt(0)
	v_add_f32_e32 v54, v54, v55
	v_fmamk_f32 v54, v54, 0x3c000000, v120
	v_mul_f32_e32 v55, 0x4b800000, v54
	v_cmp_gt_f32_e32 vcc, s3, v54
	v_and_b32_e32 v56, 0xffff0000, v58
	v_cndmask_b32_e32 v54, v54, v55, vcc
	v_rsq_f32_e32 v54, v54
	v_lshlrev_b32_e32 v57, 16, v59
	v_lshlrev_b32_e32 v64, 16, v61
	v_and_b32_e32 v61, 0xffff0000, v61
	v_mul_f32_e32 v55, 0x45800000, v54
	v_cndmask_b32_e32 v54, v54, v55, vcc
	v_mul_f32_e32 v39, v39, v54
	v_mul_f32_e32 v50, v50, v54
	v_lshlrev_b32_e32 v55, 16, v58
	v_and_b32_e32 v58, 0xffff0000, v59
	v_lshlrev_b32_e32 v59, 16, v60
	v_and_b32_e32 v60, 0xffff0000, v60
	v_mul_f32_e32 v39, v7, v39
	v_mul_f32_e32 v50, v3, v50
	v_mul_f32_e32 v39, v39, v56
	v_mul_f32_e32 v53, v53, v54
	v_mul_f32_e32 v56, v50, v60
	v_mul_f32_e32 v50, v63, v54
	v_mul_f32_e32 v36, v36, v54
	v_mul_f32_e32 v53, v8, v53
	v_mul_f32_e32 v50, v4, v50
	v_mul_f32_e32 v36, v6, v36
	v_mul_f32_e32 v53, v53, v57
	v_mul_f32_e32 v52, v52, v54
	v_mul_f32_e32 v57, v50, v64
	v_mul_f32_e32 v50, v62, v54
	v_mul_f32_e32 v36, v36, v55
	v_mul_f32_e32 v52, v9, v52
	v_mul_f32_e32 v51, v51, v54
	v_mul_f32_e32 v50, v5, v50
	v_mul_f32_e32 v52, v52, v58
	v_mul_f32_e32 v51, v2, v51
	v_mul_f32_e32 v54, v50, v61
	v_cvt_pk_bf16_f32 v50, v36, v39
	v_add_f32_e32 v36, 0, v22
	v_mul_f32_e32 v55, v51, v59
	v_cvt_pk_bf16_f32 v51, v53, v52
	v_cvt_pk_bf16_f32 v52, v55, v56
	v_cvt_pk_bf16_f32 v53, v57, v54
	v_add_f32_e32 v39, v23, v36
	v_or_b32_e32 v36, v48, v49
	global_store_dwordx4 v[40:41], v[50:53], off
	v_mul_f32_e32 v40, v23, v23
	v_pk_fma_f32 v[40:41], v[22:23], v[22:23], v[40:41] op_sel_hi:[1,1,0]
	v_lshlrev_b64 v[52:53], 10, v[36:37]
	v_lshl_add_u64 v[48:49], v[70:71], 0, v[52:53]
	s_waitcnt vmcnt(9)
	v_mov_b32_e32 v48, v236
	v_mov_b32_e32 v49, v237
	v_mov_b32_e32 v50, v238
	v_mov_b32_e32 v51, v239
	v_pk_fma_f32 v[40:41], v[24:25], v[24:25], v[40:41]
	v_mul_f32_e32 v54, v25, v25
	v_pk_add_f32 v[40:41], v[54:55], v[40:41] op_sel_hi:[0,1]
	v_add_f32_e32 v39, v24, v39
	v_pk_fma_f32 v[40:41], v[14:15], v[14:15], v[40:41]
	v_mul_f32_e32 v54, v15, v15
	v_add_f32_e32 v39, v25, v39
	v_pk_add_f32 v[40:41], v[54:55], v[40:41] op_sel_hi:[0,1]
	v_pk_add_f32 v[54:55], v[34:35], v[16:17] op_sel:[0,1] op_sel_hi:[1,0]
	v_add_f32_e32 v39, v14, v39
	v_pk_mul_f32 v[56:57], v[54:55], v[54:55]
	v_mov_b32_e32 v58, v34
	v_mov_b32_e32 v59, v15
	v_pk_add_f32 v[38:39], v[58:59], v[38:39]
	v_pk_mov_b32 v[34:35], v[56:57], v[34:35] op_sel:[1,0]
	v_mov_b32_e32 v41, v17
	v_pk_add_f32 v[16:17], v[34:35], v[40:41]
	v_pk_mul_f32 v[34:35], v[54:55], v[38:39]
	v_pk_add_f32 v[38:39], v[54:55], v[38:39]
	v_lshlrev_b32_e32 v40, 16, v50
	v_mov_b32_e32 v35, v39
	v_pk_add_f32 v[16:17], v[34:35], v[16:17]
	ds_bpermute_b32 v35, v46, v17
	ds_bpermute_b32 v34, v46, v16
	v_and_b32_e32 v41, 0xffff0000, v50
	v_lshlrev_b32_e32 v38, 16, v49
	v_and_b32_e32 v39, 0xffff0000, v49
	s_waitcnt lgkmcnt(0)
	v_pk_add_f32 v[16:17], v[16:17], v[34:35]
	ds_bpermute_b32 v35, v47, v17
	ds_bpermute_b32 v34, v47, v16
	s_waitcnt lgkmcnt(0)
	v_pk_add_f32 v[16:17], v[16:17], v[34:35]
	ds_bpermute_b32 v35, v42, v17
	ds_bpermute_b32 v34, v42, v16
	s_waitcnt lgkmcnt(0)
	v_pk_add_f32 v[16:17], v[16:17], v[34:35]
	ds_bpermute_b32 v35, v43, v17
	ds_bpermute_b32 v34, v43, v16
	s_waitcnt lgkmcnt(0)
	v_pk_add_f32 v[16:17], v[16:17], v[34:35]
	ds_bpermute_b32 v35, v44, v17
	ds_bpermute_b32 v34, v44, v16
	s_waitcnt lgkmcnt(0)
	v_pk_add_f32 v[16:17], v[16:17], v[34:35]
	ds_bpermute_b32 v35, v45, v17
	ds_bpermute_b32 v34, v45, v16
	s_waitcnt lgkmcnt(0)
; __device__ __forceinline__ unsigned cvt_pk_bf16(float lo, float hi) { unsigned r; asm volatile("v_cvt_pk_bf16_f32 %0, %1, %2" : "=v"(r) : "v"(lo), "v"(hi)); return r; }
; __device__ void conv_phase(LAS unsigned char* lds, const Params& p) {
;     ...
;     for (int it = blockIdx.x * 8 + w; it < 8192; it += gridDim.x * 8) {
;     ...
;                 for (int m = 32; m >= 1; m >>= 1) { s1 += __shfl_xor(s1, m); s2 += __shfl_xor(s2, m); }
;                 const float mean = s1 * (1.f / 512.f), var = fmaxf(s2 * (1.f / 512.f) - mean * mean, 0.f), rstd = rsqrtf(var + EPS);
;                 const u32x4 gbr = *(const u32x4*)(GBp + token * 512 + ch0);
;                 const float gbv[8] = {bf_lo(gbr[0]), bf_hi(gbr[0]), bf_lo(gbr[1]), bf_hi(gbr[1]), bf_lo(gbr[2]), bf_hi(gbr[2]), bf_lo(gbr[3]), bf_hi(gbr[3])};
;                 float y[8];
; #pragma unroll
;                 for (int c = 0; c < 8; ++c) { const float t = (v[c] - mean) * rstd * lg[c] + lbv[c]; y[c] = siluf_(t) * gbv[c]; }
;                 u32x4 ob = {cvt_pk_bf16(y[0], y[1]), cvt_pk_bf16(y[2], y[3]), cvt_pk_bf16(y[4], y[5]), cvt_pk_bf16(y[6], y[7])};
;                 *(u32x4*)(A2 + token * 1024 + 512 + ch0) = ob;
;                 const u32x4 fo = *(const u32x4*)(O + token * 512 + ch0), bo = *(const u32x4*)(O + ((size_t)NLAT + token) * 512 + ch0);
;                 float ov[8]; float ss = 0.f;
; #pragma unroll
;                 for (int c = 0; c < 4; ++c) { ov[2 * c] = bf_lo(fo[c]) + bf_lo(bo[c]); ov[2 * c + 1] = bf_hi(fo[c]) + bf_hi(bo[c]); }
; #pragma unroll
;                 for (int c = 0; c < 8; ++c) ss += ov[c] * ov[c];
;                 ss += __shfl_xor(ss, 1); ss += __shfl_xor(ss, 2); ss += __shfl_xor(ss, 4); ss += __shfl_xor(ss, 8);
;                 const float rn = rsqrtf(ss * (1.f / 128.f) + EPS);
;                 const u32x4 gar = *(const u32x4*)(GAp + token * 512 + ch0);
;                 const float gav[8] = {bf_lo(gar[0]), bf_hi(gar[0]), bf_lo(gar[1]), bf_hi(gar[1]), bf_lo(gar[2]), bf_hi(gar[2]), bf_lo(gar[3]), bf_hi(gar[3])};
;                 float z[8];
; #pragma unroll
;                 for (int c = 0; c < 8; ++c) z[c] = ov[c] * rn * hg[c] * gav[c];
;                 u32x4 oa = {cvt_pk_bf16(z[0], z[1]), cvt_pk_bf16(z[2], z[3]), cvt_pk_bf16(z[4], z[5]), cvt_pk_bf16(z[6], z[7])};
;                 *(u32x4*)(A2 + token * 1024 + ch0) = oa;
;             }
	v_pk_add_f32 v[16:17], v[16:17], v[34:35]
	s_nop 0
	v_pk_mul_f32 v[16:17], v[16:17], s[34:35] op_sel_hi:[1,0]
	v_and_b32_e32 v35, 0xffff0000, v48
	v_fma_f32 v16, -v17, v17, v16
	v_max_f32_e32 v16, 0, v16
	v_add_f32_e32 v16, 0x358637bd, v16
	v_mul_f32_e32 v34, 0x4b800000, v16
	v_cmp_gt_f32_e32 vcc, s3, v16
	v_sub_f32_e32 v14, v14, v17
	v_sub_f32_e32 v22, v22, v17
	v_cndmask_b32_e32 v16, v16, v34, vcc
	v_rsq_f32_e32 v16, v16
	v_sub_f32_e32 v15, v15, v17
	v_sub_f32_e32 v23, v23, v17
	v_sub_f32_e32 v24, v24, v17
	v_mul_f32_e32 v34, 0x45800000, v16
	v_cndmask_b32_e32 v16, v16, v34, vcc
	v_mul_f32_e32 v14, v14, v16
	v_fma_f32 v10, v18, v14, v10
	v_mul_f32_e32 v14, 0xbfb8aa3b, v10
	v_exp_f32_e32 v14, v14
	v_mul_f32_e32 v22, v22, v16
	v_fma_f32 v22, v30, v22, v26
	v_mul_f32_e32 v15, v15, v16
	v_mul_f32_e32 v26, 0xbfb8aa3b, v22
	v_add_f32_e32 v14, 1.0, v14
	v_fma_f32 v11, v19, v15, v11
	v_exp_f32_e32 v26, v26
	v_rcp_f32_e32 v14, v14
	v_mul_f32_e32 v15, 0xbfb8aa3b, v11
	v_exp_f32_e32 v15, v15
	v_add_f32_e32 v26, 1.0, v26
	v_mul_f32_e32 v10, v10, v14
	v_rcp_f32_e32 v26, v26
	v_mul_f32_e32 v14, v10, v40
	v_add_f32_e32 v10, 1.0, v15
	v_sub_f32_e32 v15, v55, v17
	v_sub_f32_e32 v25, v25, v17
	v_mul_f32_e32 v15, v15, v16
	v_sub_f32_e32 v17, v54, v17
	v_mul_f32_e32 v23, v23, v16
	v_mul_f32_e32 v24, v24, v16
	v_mul_f32_e32 v25, v25, v16
	v_fma_f32 v12, v20, v15, v12
	v_mul_f32_e32 v16, v17, v16
	v_fma_f32 v23, v31, v23, v27
	v_fma_f32 v24, v32, v24, v28
	v_fmac_f32_e32 v29, v33, v25
	v_mul_f32_e32 v15, 0xbfb8aa3b, v12
	v_fmac_f32_e32 v13, v21, v16
	v_mul_f32_e32 v27, 0xbfb8aa3b, v23
	v_mul_f32_e32 v22, v22, v26
	v_mul_f32_e32 v26, 0xbfb8aa3b, v24
	v_mul_f32_e32 v25, 0xbfb8aa3b, v29
	v_rcp_f32_e32 v10, v10
	v_exp_f32_e32 v15, v15
	v_mul_f32_e32 v16, 0xbfb8aa3b, v13
	v_exp_f32_e32 v27, v27
	v_exp_f32_e32 v26, v26
	v_exp_f32_e32 v25, v25
	v_exp_f32_e32 v16, v16
	v_mul_f32_e32 v10, v11, v10
	v_add_f32_e32 v11, 1.0, v15
	v_add_f32_e32 v27, 1.0, v27
	v_add_f32_e32 v26, 1.0, v26
	v_add_f32_e32 v25, 1.0, v25
	v_rcp_f32_e32 v11, v11
	v_add_f32_e32 v15, 1.0, v16
	v_rcp_f32_e32 v27, v27
	v_rcp_f32_e32 v26, v26
	v_rcp_f32_e32 v25, v25
	v_rcp_f32_e32 v15, v15
	v_lshlrev_b32_e32 v30, 16, v51
	v_mul_f32_e32 v16, v10, v41
	v_mul_f32_e32 v10, v12, v11
	v_lshlrev_b32_e32 v34, 16, v48
	v_and_b32_e32 v31, 0xffff0000, v51
	v_mul_f32_e32 v23, v23, v27
	v_mul_f32_e32 v18, v24, v26
	v_mul_f32_e32 v24, v29, v25
	v_mul_f32_e32 v17, v10, v30
	v_mul_f32_e32 v10, v13, v15
	v_mul_f32_e32 v22, v22, v34
	v_mul_f32_e32 v23, v23, v35
	v_mul_f32_e32 v18, v18, v38
	v_mul_f32_e32 v19, v24, v39
	v_mul_f32_e32 v13, v10, v31
	v_cvt_pk_bf16_f32 v10, v22, v23
	v_cvt_pk_bf16_f32 v11, v18, v19
	v_cvt_pk_bf16_f32 v12, v14, v16
	v_lshlrev_b64 v[14:15], 11, v[36:37]
	v_lshl_add_u64 v[22:23], v[84:85], 0, v[14:15]
	v_cvt_pk_bf16_f32 v13, v17, v13
	global_store_dwordx4 v[22:23], v[10:13], off offset:1024
	v_lshl_add_u64 v[18:19], v[72:73], 0, v[52:53]
	s_nop 0
	v_lshl_add_u64 v[10:11], s[68:69], 0, v[52:53]
	v_lshl_add_u64 v[10:11], v[10:11], 0, v[66:67]
	v_add_co_u32_e32 v20, vcc, s35, v10
	s_nop 1
	v_addc_co_u32_e32 v21, vcc, 0, v11, vcc
	s_waitcnt vmcnt(8)
	v_mov_b32_e32 v10, v240
	v_mov_b32_e32 v11, v241
	v_mov_b32_e32 v12, v242
	v_mov_b32_e32 v13, v243
	v_mov_b32_e32 v14, v244
	v_mov_b32_e32 v15, v245
	v_mov_b32_e32 v16, v246
	v_mov_b32_e32 v17, v247
	v_lshl_add_u64 v[18:19], v[74:75], 0, v[52:53]
	s_waitcnt vmcnt(7)
	v_mov_b32_e32 v18, v248
	v_mov_b32_e32 v19, v249
	v_mov_b32_e32 v20, v250
	v_mov_b32_e32 v21, v251
	v_lshlrev_b32_e32 v24, 16, v10
	v_lshlrev_b32_e32 v25, 16, v14
	v_add_f32_e32 v32, v24, v25
	v_and_b32_e32 v10, 0xffff0000, v10
	v_and_b32_e32 v14, 0xffff0000, v14
	v_lshlrev_b32_e32 v25, 16, v11
	v_lshlrev_b32_e32 v27, 16, v15
	v_and_b32_e32 v24, 0xffff0000, v11
	v_and_b32_e32 v26, 0xffff0000, v15
	v_lshlrev_b32_e32 v29, 16, v13
	v_lshlrev_b32_e32 v31, 16, v17
	v_and_b32_e32 v28, 0xffff0000, v13
	v_and_b32_e32 v30, 0xffff0000, v17
	v_add_f32_e32 v33, v10, v14
	v_lshlrev_b32_e32 v11, 16, v12
	v_and_b32_e32 v10, 0xffff0000, v12
	v_pk_add_f32 v[12:13], v[26:27], v[24:25]
	v_pk_add_f32 v[24:25], v[30:31], v[28:29]
	v_mul_f32_e32 v28, v32, v32
	v_lshlrev_b32_e32 v15, 16, v16
	v_and_b32_e32 v14, 0xffff0000, v16
	v_pk_mul_f32 v[16:17], v[12:13], v[12:13]
	v_fmac_f32_e32 v28, v33, v33
	v_pk_add_f32 v[10:11], v[14:15], v[10:11]
	v_add_f32_e32 v17, v17, v28
	v_pk_mul_f32 v[14:15], v[10:11], v[10:11]
	v_add_f32_e32 v16, v16, v17
	v_add_f32_e32 v15, v15, v16
	v_pk_mul_f32 v[26:27], v[24:25], v[24:25]
	v_add_f32_e32 v14, v14, v15
	v_add_f32_e32 v14, v27, v14
	v_add_f32_e32 v14, v26, v14
	ds_bpermute_b32 v15, v45, v14
	v_and_b32_e32 v16, 0xffff0000, v18
	v_lshlrev_b32_e32 v17, 16, v19
	v_lshlrev_b32_e32 v26, 16, v21
	v_and_b32_e32 v21, 0xffff0000, v21
	s_waitcnt lgkmcnt(0)
	v_add_f32_e32 v14, v14, v15
	ds_bpermute_b32 v15, v44, v14
	s_waitcnt lgkmcnt(0)
	v_add_f32_e32 v14, v14, v15
	ds_bpermute_b32 v15, v43, v14
	s_waitcnt lgkmcnt(0)
	v_add_f32_e32 v14, v14, v15
	ds_bpermute_b32 v15, v42, v14
	s_waitcnt lgkmcnt(0)
	v_add_f32_e32 v14, v14, v15
	v_fmamk_f32 v14, v14, 0x3c000000, v120
	v_mul_f32_e32 v15, 0x4b800000, v14
	v_cmp_gt_f32_e32 vcc, s3, v14
	s_nop 1
	v_cndmask_b32_e32 v14, v14, v15, vcc
	v_rsq_f32_e32 v14, v14
	s_nop 0
	v_mul_f32_e32 v15, 0x45800000, v14
	v_cndmask_b32_e32 v14, v14, v15, vcc
	v_mul_f32_e32 v11, v11, v14
	v_lshlrev_b32_e32 v15, 16, v18
	v_and_b32_e32 v18, 0xffff0000, v19
	v_lshlrev_b32_e32 v19, 16, v20
	v_mul_f32_e32 v2, v2, v11
	v_mul_f32_e32 v11, v2, v19
	v_mul_f32_e32 v2, v10, v14
	v_and_b32_e32 v20, 0xffff0000, v20
	v_mul_f32_e32 v2, v3, v2
	v_mul_f32_e32 v10, v2, v20
	v_mul_f32_e32 v2, v25, v14
	v_mul_f32_e32 v27, v32, v14
	v_mul_f32_e32 v12, v12, v14
	v_mul_f32_e32 v2, v4, v2
	v_mul_f32_e32 v6, v6, v27
	v_mul_f32_e32 v9, v9, v12
	v_mul_f32_e32 v12, v2, v26
	v_mul_f32_e32 v2, v24, v14
	v_mul_f32_e32 v6, v6, v15
	v_mul_f32_e32 v15, v33, v14
	v_mul_f32_e32 v13, v13, v14
	v_mul_f32_e32 v2, v5, v2
	v_mul_f32_e32 v7, v7, v15
	v_mul_f32_e32 v8, v8, v13
	v_mul_f32_e32 v5, v2, v21
	v_mul_f32_e32 v7, v7, v16
	v_mul_f32_e32 v8, v8, v17
	v_mul_f32_e32 v9, v9, v18
	v_cvt_pk_bf16_f32 v2, v6, v7
	v_cvt_pk_bf16_f32 v3, v8, v9
	v_cvt_pk_bf16_f32 v4, v11, v10
	v_cvt_pk_bf16_f32 v5, v12, v5
	global_store_dwordx4 v[22:23], v[2:5], off
	s_load_dword s4, s[28:29], 0x0
	s_waitcnt lgkmcnt(0)
	v_lshl_add_u32 v1, s4, 3, v1
	v_cmp_lt_i32_e32 vcc, s40, v1
	s_or_b64 s[30:31], vcc, s[30:31]
	s_andn2_b64 exec, exec, s[30:31]
	s_cbranch_execz .LBB0_377

; #define LAS __attribute__((address_space(3)))
; __global__ void __launch_bounds__(NTHR, 2) hymba_fwd(Params p) {
;     extern __shared__ __attribute__((aligned(16))) unsigned char lds_raw[];
;     LAS unsigned char* lds = (LAS unsigned char*)lds_raw;
	.amdhsa_kernel _Z9hymba_fwd6Params
		.amdhsa_group_segment_fixed_size 25600
		.amdhsa_private_segment_fixed_size 0
		.amdhsa_kernarg_size 408
		.amdhsa_user_sgpr_count 2
		.amdhsa_user_sgpr_dispatch_ptr 0
		.amdhsa_user_sgpr_queue_ptr 0
		.amdhsa_user_sgpr_kernarg_segment_ptr 1
		.amdhsa_user_sgpr_dispatch_id 0
		.amdhsa_user_sgpr_kernarg_preload_length 0
		.amdhsa_user_sgpr_kernarg_preload_offset 0
		.amdhsa_user_sgpr_private_segment_size 0
		.amdhsa_uses_dynamic_stack 0
		.amdhsa_enable_private_segment 0
		.amdhsa_system_sgpr_workgroup_id_x 1
		.amdhsa_system_sgpr_workgroup_id_y 0
		.amdhsa_system_sgpr_workgroup_id_z 0
		.amdhsa_system_sgpr_workgroup_info 0
		.amdhsa_system_vgpr_workitem_id 0
		.amdhsa_next_free_vgpr 256
		.amdhsa_next_free_sgpr 100
		.amdhsa_accum_offset 256
		.amdhsa_reserve_vcc 1
		.amdhsa_float_round_mode_32 0
		.amdhsa_float_round_mode_16_64 0
		.amdhsa_float_denorm_mode_32 3
		.amdhsa_float_denorm_mode_16_64 3
		.amdhsa_dx10_clamp 1
		.amdhsa_ieee_mode 1
		.amdhsa_fp16_overflow 0
		.amdhsa_tg_split 0
		.amdhsa_exception_fp_ieee_invalid_op 0
		.amdhsa_exception_fp_denorm_src 0
		.amdhsa_exception_fp_ieee_div_zero 0
		.amdhsa_exception_fp_ieee_overflow 0
		.amdhsa_exception_fp_ieee_underflow 0
		.amdhsa_exception_fp_ieee_inexact 0
		.amdhsa_exception_int_div_zero 0
	.end_amdhsa_kernel

; #define LAS __attribute__((address_space(3)))
; __global__ void __launch_bounds__(NTHR, 2) hymba_fwd(Params p) {
;     extern __shared__ __attribute__((aligned(16))) unsigned char lds_raw[];
;     LAS unsigned char* lds = (LAS unsigned char*)lds_raw;
amdhsa.kernels:
  - .agpr_count:     0
    .args:
      - .offset:         0
        .size:           152
        .value_kind:     by_value
      - .offset:         152
        .size:           4
        .value_kind:     hidden_block_count_x
      - .offset:         156
        .size:           4
        .value_kind:     hidden_block_count_y
      - .offset:         160
        .size:           4
        .value_kind:     hidden_block_count_z
      - .offset:         164
        .size:           2
        .value_kind:     hidden_group_size_x
      - .offset:         166
        .size:           2
        .value_kind:     hidden_group_size_y
      - .offset:         168
        .size:           2
        .value_kind:     hidden_group_size_z
      - .offset:         170
        .size:           2
        .value_kind:     hidden_remainder_x
      - .offset:         172
        .size:           2
        .value_kind:     hidden_remainder_y
      - .offset:         174
        .size:           2
        .value_kind:     hidden_remainder_z
      - .offset:         192
        .size:           8
        .value_kind:     hidden_global_offset_x
      - .offset:         200
        .size:           8
        .value_kind:     hidden_global_offset_y
      - .offset:         208
        .size:           8
        .value_kind:     hidden_global_offset_z
      - .offset:         216
        .size:           2
        .value_kind:     hidden_grid_dims
      - .offset:         272
        .size:           4
        .value_kind:     hidden_dynamic_lds_size
    .group_segment_fixed_size: 25600
    .kernarg_segment_align: 8
    .kernarg_segment_size: 408
    .language:       OpenCL C
    .language_version:
      - 2
      - 0
    .max_flat_workgroup_size: 512
    .name:           _Z9hymba_fwd6Params
    .private_segment_fixed_size: 0
    .sgpr_count:     106
    .sgpr_spill_count: 4
    .symbol:         _Z9hymba_fwd6Params.kd
    .uniform_work_group_size: 1
    .uses_dynamic_stack: false
    .vgpr_count:     256
    .vgpr_spill_count: 0
    .wavefront_size: 64
